# first residual quarter fetched right after the barrier that retires the even K-tile slot, under the last K-tile's MFMAs (readfirstlane hazard fixed)
# speedup vs baseline: 1.0055x; 1.0029x over previous
; DI f32x4 mfma16(bf16x8 a, bf16x8 b, f32x4 c) { return __builtin_amdgcn_mfma_f32_16x16x32_bf16(a, b, c, 0, 0, 0); }
;     ...
;         for (int nt = 0; nt < NT; ++nt) {
;             const int br = BM + (nt / NTS) * (BN / NSEG) + wc * (NTS * 16) + (nt % NTS) * 16;
;             bfr[nt] = *(const bf16x8*)(base + (br + l15) * 64 + rsw);
;         }
; #pragma unroll
;         for (int mt = 0; mt < MT; ++mt) af[mt] = *(const bf16x8*)(base + (wr * WM + mt * 16 + l15) * 64 + rsw);
;         constexpr int TOT = MT * NT, PER = (TOT + NIT - 1) / NIT;
; #pragma unroll
;         for (int part = 0; part < NIT; ++part) {
; #pragma unroll
;             for (int q = 0; q < PER; ++q) {
;                 const int idx = part * PER + q;
;                 if (idx < TOT) {
;                     const int mt = idx / NT, nt = idx % NT;
;                     acc[mt][nt] = SWAP ? mfma16(bfr[nt], af[mt], acc[mt][nt]) : mfma16(af[mt], bfr[nt], acc[mt][nt]);
;                 }
;             }
;             __builtin_amdgcn_sched_barrier(0);
;             if (do_issue) issue_one(ikt, ib, part);
;             __builtin_amdgcn_sched_barrier(0);
;         }
; DI void unit_O(const Params& p, char* lds, int l, int tile, int glu_tiles, int tile_b) {
;     ...
;     auto issue_x = [&](int half) {
;         if (l == 0) {
; #pragma unroll 1
;             for (int i = 0; i < 16; ++i) {
;                 const int pc = (wid * 16 + i + xrot) & 127, row = pc >> 2, phys = (pc & 3) * 64 + lane, logical = phys ^ (row & 15);
;                 __builtin_amdgcn_global_load_lds((const unsigned*)(xres + (r0 + half * 32 + row) * 1024 + logical * 4), (unsigned*)(XR + pc * 1024 + lane * 16), 16, 0, 0);
;             }
;         } else {
; #pragma unroll 1
;             for (int i = 0; i < 8; ++i) {
;                 const int pc = (wid * 8 + i + (xrot >> 1)) & 63, kt = pc >> 1, sub = pc & 1;
;                 __builtin_amdgcn_global_load_lds((const unsigned*)(xbres + ((size_t)kt * 128 + half * 32) * 32 + sub * 512 + lane * 8), (unsigned*)(XR + pc * 1024 + lane * 16), 16, 0, 0);
;             }
;         }
;     };
;     issue_x(0);
;     {
;         const float* gsrc = (tid < 256) ? (p.ln_g + l * 1024 + tid * 4) : (p.ln_b + l * 1024 + (tid - 256) * 4);
;         *(f32x4*)(GB + tid * 4) = *(const f32x4*)gsrc;
.Lpo1_join:
.LBB0_100:
	s_waitcnt vmcnt(0)
	v_add_u32_e32 v0, 0x11000, v140
	s_barrier
	v_lshrrev_b32_e32 v210, 6, v212
	v_and_b32_e32 v211, 63, v212
	s_nop 1
	v_readfirstlane_b32 s90, v210
	s_nop 3
	s_cmp_lg_u64 s[10:11], 0
	s_cbranch_scc1 .Le1_el1
	s_lshl_b32 s40, s34, 18
	s_lshl_b32 s91, s90, 13
	s_add_u32 s96, s52, s40
	s_addc_u32 s97, s53, 0
	s_add_u32 s96, s96, s91
	s_addc_u32 s97, s97, 0
	s_lshl_b32 s40, s90, 1
	v_xor_b32_e32 v208, s40, v211
	v_lshlrev_b32_e32 v208, 4, v208
	s_add_u32 s40, s40, 1
	v_xor_b32_e32 v209, s40, v211
	v_lshlrev_b32_e32 v209, 4, v209
	s_add_u32 s92, s96, 0x0
	s_addc_u32 s93, s97, 0
	s_add_u32 s40, s91, 0x0
	s_mov_b32 m0, s40
	s_nop 0
	global_load_lds_dwordx4 v208, s[92:93]
	global_load_lds_dwordx4 v208, s[92:93] offset:1024
	global_load_lds_dwordx4 v208, s[92:93] offset:2048
	global_load_lds_dwordx4 v208, s[92:93] offset:3072
	s_add_u32 s92, s96, 0x1000
	s_addc_u32 s93, s97, 0
	s_add_u32 s40, s91, 0x1000
	s_mov_b32 m0, s40
	s_nop 0
	global_load_lds_dwordx4 v209, s[92:93]
	global_load_lds_dwordx4 v209, s[92:93] offset:1024
	global_load_lds_dwordx4 v209, s[92:93] offset:2048
	global_load_lds_dwordx4 v209, s[92:93] offset:3072
	s_branch .Le1_ejoin
.Le1_el1:
	s_lshr_b32 s40, s34, 1
	s_lshl_b32 s40, s40, 18
	s_and_b32 s94, s34, 1
	s_lshl_b32 s94, s94, 12
	s_add_u32 s40, s40, s94
	s_lshl_b32 s91, s90, 12
	s_lshl_b32 s94, s90, 15
	s_add_u32 s96, s56, s40
	s_addc_u32 s97, s57, 0
	s_add_u32 s96, s96, s94
	s_addc_u32 s97, s97, 0
	v_lshlrev_b32_e32 v208, 4, v211
	s_add_u32 s92, s96, 0
	s_addc_u32 s93, s97, 0
	s_mov_b32 m0, s91
	s_nop 0
	global_load_lds_dwordx4 v208, s[92:93]
	s_add_u32 s92, s92, 0x2000
	s_addc_u32 s93, s93, 0
	s_add_u32 m0, m0, 0x400
	s_nop 0
	global_load_lds_dwordx4 v208, s[92:93]
	s_add_u32 s92, s92, 0x2000
	s_addc_u32 s93, s93, 0
	s_add_u32 m0, m0, 0x400
	s_nop 0
	global_load_lds_dwordx4 v208, s[92:93]
	s_add_u32 s92, s92, 0x2000
	s_addc_u32 s93, s93, 0
	s_add_u32 m0, m0, 0x400
	s_nop 0
	global_load_lds_dwordx4 v208, s[92:93]
.Le1_ejoin:
	v_add_u32_e32 v134, v0, v141
	v_add_u32_e32 v0, v0, v139
	ds_read_b128 v[130:133], v134 offset:4096
	ds_read_b128 v[138:141], v0
	ds_read_b128 v[142:145], v134 offset:5120
	ds_read_b128 v[146:149], v0 offset:1024
	ds_read_b128 v[150:153], v134 offset:6144
	ds_read_b128 v[154:157], v134 offset:7168
	ds_read_b128 v[158:161], v134 offset:8192
	ds_read_b128 v[162:165], v134 offset:9216
	ds_read_b128 v[166:169], v134 offset:10240
	ds_read_b128 v[170:173], v134 offset:11264
	ds_read_b128 v[174:177], v0 offset:2048
	ds_read_b128 v[178:181], v0 offset:3072
	s_waitcnt lgkmcnt(0)
	v_mfma_f32_16x16x32_bf16 v[98:101], v[130:133], v[138:141], v[98:101]
	v_and_b32_e32 v197, 63, v136
	v_ashrrev_i32_e32 v236, 6, v136
	v_mfma_f32_16x16x32_bf16 v[94:97], v[142:145], v[138:141], v[94:97]
	v_mfma_f32_16x16x32_bf16 v[90:93], v[150:153], v[138:141], v[90:93]
	v_mfma_f32_16x16x32_bf16 v[86:89], v[154:157], v[138:141], v[86:89]
	v_mfma_f32_16x16x32_bf16 v[82:85], v[158:161], v[138:141], v[82:85]
	v_mfma_f32_16x16x32_bf16 v[78:81], v[162:165], v[138:141], v[78:81]
	v_mfma_f32_16x16x32_bf16 v[74:77], v[166:169], v[138:141], v[74:77]
	v_mfma_f32_16x16x32_bf16 v[70:73], v[170:173], v[138:141], v[70:73]
	v_mfma_f32_16x16x32_bf16 v[126:129], v[130:133], v[146:149], v[126:129]
	v_mfma_f32_16x16x32_bf16 v[122:125], v[142:145], v[146:149], v[122:125]
	v_mfma_f32_16x16x32_bf16 v[118:121], v[150:153], v[146:149], v[118:121]
	v_mfma_f32_16x16x32_bf16 v[114:117], v[154:157], v[146:149], v[114:117]
	v_mfma_f32_16x16x32_bf16 v[110:113], v[158:161], v[146:149], v[110:113]
	v_mfma_f32_16x16x32_bf16 v[106:109], v[162:165], v[146:149], v[106:109]
	v_mfma_f32_16x16x32_bf16 v[102:105], v[166:169], v[146:149], v[102:105]
	v_mfma_f32_16x16x32_bf16 v[66:69], v[170:173], v[146:149], v[66:69]
	v_mfma_f32_16x16x32_bf16 v[34:37], v[130:133], v[174:177], v[34:37]
	v_mfma_f32_16x16x32_bf16 v[30:33], v[142:145], v[174:177], v[30:33]
	v_mfma_f32_16x16x32_bf16 v[26:29], v[150:153], v[174:177], v[26:29]
	v_mfma_f32_16x16x32_bf16 v[22:25], v[154:157], v[174:177], v[22:25]
	v_mfma_f32_16x16x32_bf16 v[18:21], v[158:161], v[174:177], v[18:21]
	v_mfma_f32_16x16x32_bf16 v[14:17], v[162:165], v[174:177], v[14:17]
	v_mfma_f32_16x16x32_bf16 v[10:13], v[166:169], v[174:177], v[10:13]
	v_mfma_f32_16x16x32_bf16 v[6:9], v[170:173], v[174:177], v[6:9]
	v_mfma_f32_16x16x32_bf16 v[62:65], v[130:133], v[178:181], v[62:65]
	v_mfma_f32_16x16x32_bf16 v[58:61], v[142:145], v[178:181], v[58:61]
	v_mfma_f32_16x16x32_bf16 v[54:57], v[150:153], v[178:181], v[54:57]
	v_mfma_f32_16x16x32_bf16 v[50:53], v[154:157], v[178:181], v[50:53]
	v_mfma_f32_16x16x32_bf16 v[46:49], v[158:161], v[178:181], v[46:49]
	v_mfma_f32_16x16x32_bf16 v[42:45], v[162:165], v[178:181], v[42:45]
	v_mfma_f32_16x16x32_bf16 v[38:41], v[166:169], v[178:181], v[38:41]
	v_mfma_f32_16x16x32_bf16 v[2:5], v[170:173], v[178:181], v[2:5]
	s_barrier
	s_not_b64 s[6:7], s[10:11]
	v_and_b32_e32 v138, 15, v212
	v_bfe_u32 v139, v212, 4, 2
	v_lshrrev_b32_e32 v140, 6, v212
	v_and_b32_e32 v141, 63, v212
	v_readfirstlane_b32 s90, v140
	v_and_b32_e32 v142, 0xff, v212
	v_lshlrev_b32_e32 v142, 4, v142
	s_cmp_lt_u32 s90, 4
	s_cselect_b32 s92, s14, s12
	s_cselect_b32 s93, s15, s13
	s_nop 3
	global_load_dwordx4 v[176:179], v142, s[92:93]
	v_lshlrev_b32_e32 v143, 4, v212
	v_add_u32_e32 v143, 0x20000, v143
	v_lshlrev_b32_e32 v134, 6, v138
	v_add_u32_e32 v135, 0x22000, v134
	v_lshl_add_u32 v134, v140, 3, v135
	v_lshlrev_b32_e32 v136, 9, v140
	v_lshl_add_u32 v136, v139, 4, v136
	v_add_u32_e32 v136, 0x20000, v136
	s_cmp_lg_u64 s[10:11], 0
	s_cbranch_scc1 .Le1_l1
; DI float bf2f(unsigned b) { return __uint_as_float(b << 16); }
; template <int N> DI void wait_vm() { asm volatile("s_waitcnt vmcnt(%0)" ::"n"(N) : "memory"); }
; DI void unit_O(const Params& p, char* lds, int l, int tile, int glu_tiles, int tile_b) {
;     ...
; #pragma unroll
;     for (int half = 0; half < 2; ++half) {
;         if (half == 0) wait_vm<0>();
;         else wait_vm<8>();
;         __syncthreads();
;         float s2[2], ss2[2];
; #pragma unroll
;         for (int mh = 0; mh < 2; ++mh) {
;             const int mt = half * 2 + mh, rl = mh * 16 + l15;
;             float s = 0.f, ss = 0.f;
; #pragma unroll
;             for (int nt = 0; nt < 8; ++nt) {
;                 f32x4 xr;
;                 if (l == 0) {
;                     const int chunk = wid * 32 + nt * 4 + quad;
;                     xr = *(const f32x4*)(XR + rl * 4096 + ((chunk ^ l15) << 4));
;                 } else {
;                     const u32x2 hb = *(const u32x2*)(XR + ((wid * 4 + (nt >> 1)) * 32 + rl) * 64 + (nt & 1) * 32 + quad * 8);
;                     xr = (f32x4){bf2f(hb[0] & 0xffffu), bf2f(hb[0] >> 16), bf2f(hb[1] & 0xffffu), bf2f(hb[1] >> 16)};
;                 }
; #pragma unroll
;                 for (int i = 0; i < 4; ++i) { const float v = acc[mt][nt][i] + DN_ALPHA * xr[i]; acc[mt][nt][i] = v; s += v; ss += v * v; }
;             }
;             s2[mh] = s; ss2[mh] = ss;
;         }
; #pragma unroll
;         for (int mh = 0; mh < 2; ++mh) { s2[mh] += __shfl_xor(s2[mh], 16); ss2[mh] += __shfl_xor(ss2[mh], 16); }
; #pragma unroll
;         for (int mh = 0; mh < 2; ++mh) { s2[mh] += __shfl_xor(s2[mh], 32); ss2[mh] += __shfl_xor(ss2[mh], 32); }
;         if (quad == 0) {
; #pragma unroll
;             for (int mh = 0; mh < 2; ++mh) *(f32x2*)&red[((mh * 16 + l15) * 8 + wid) * 2] = (f32x2){s2[mh], ss2[mh]};
;         }
	v_lshlrev_b32_e32 v133, 12, v138
	v_lshl_add_u32 v133, v140, 9, v133
	v_add_u32_e32 v200, 0, v139
	v_xor_b32_e32 v200, v200, v138
	v_lshl_add_u32 v200, v200, 4, v133
	v_add_u32_e32 v204, 0x10000, v200
	v_add_u32_e32 v201, 4, v139
	v_xor_b32_e32 v201, v201, v138
	v_lshl_add_u32 v201, v201, 4, v133
	v_add_u32_e32 v205, 0x10000, v201
	v_add_u32_e32 v202, 8, v139
	v_xor_b32_e32 v202, v202, v138
	v_lshl_add_u32 v202, v202, 4, v133
	v_add_u32_e32 v206, 0x10000, v202
	v_add_u32_e32 v203, 12, v139
	v_xor_b32_e32 v203, v203, v138
	v_lshl_add_u32 v203, v203, 4, v133
	v_add_u32_e32 v207, 0x10000, v203
	v_and_b32_e32 v137, 1, v139
	v_lshlrev_b32_e32 v137, 5, v137
	v_lshrrev_b32_e32 v130, 1, v139
	v_lshl_or_b32 v137, v130, 4, v137
	v_lshl_or_b32 v137, v138, 6, v137
	v_lshl_or_b32 v137, v140, 15, v137
	s_lshr_b32 s40, s34, 1
	s_lshl_b32 s40, s40, 18
	s_and_b32 s46, s34, 1
	s_lshl_b32 s46, s46, 12
	s_add_u32 s40, s40, s46
	s_add_u32 s78, s56, s40
	s_addc_u32 s79, s57, 0
	s_add_u32 s92, s96, 0x10000
	s_addc_u32 s93, s97, 0
	s_add_u32 s40, s91, 0x10000
	s_mov_b32 m0, s40
	s_nop 0
	global_load_lds_dwordx4 v208, s[92:93]
	global_load_lds_dwordx4 v208, s[92:93] offset:1024
	global_load_lds_dwordx4 v208, s[92:93] offset:2048
	global_load_lds_dwordx4 v208, s[92:93] offset:3072
	s_add_u32 s92, s96, 0x11000
	s_addc_u32 s93, s97, 0
	s_add_u32 s40, s91, 0x11000
	s_mov_b32 m0, s40
	s_nop 0
	global_load_lds_dwordx4 v209, s[92:93]
	global_load_lds_dwordx4 v209, s[92:93] offset:1024
	global_load_lds_dwordx4 v209, s[92:93] offset:2048
	global_load_lds_dwordx4 v209, s[92:93] offset:3072
	s_waitcnt vmcnt(8)
	ds_write_b128 v143, v[176:179]
	s_waitcnt vmcnt(8) lgkmcnt(0)
	s_barrier
	ds_read_b128 v[144:147], v200
	ds_read_b128 v[148:151], v201
	ds_read_b128 v[152:155], v202
	ds_read_b128 v[156:159], v203
	ds_read_b128 v[160:163], v200 offset:256
	ds_read_b128 v[164:167], v201 offset:256
	ds_read_b128 v[168:171], v202 offset:256
	ds_read_b128 v[172:175], v203 offset:256
	s_waitcnt lgkmcnt(7)
	v_fmac_f32_e32 v98, s58, v144
	v_fmac_f32_e32 v99, s58, v145
	v_fmac_f32_e32 v100, s58, v146
	v_fmac_f32_e32 v101, s58, v147
	v_mov_b32_e32 v196, v98
	v_mul_f32_e32 v197, v98, v98
	v_mov_b32_e32 v130, v99
	v_mul_f32_e32 v142, v99, v99
	v_add_f32_e32 v196, v196, v100
	v_fmac_f32_e32 v197, v100, v100
	v_add_f32_e32 v130, v130, v101
	v_fmac_f32_e32 v142, v101, v101
	s_waitcnt lgkmcnt(6)
	v_fmac_f32_e32 v94, s58, v148
	v_fmac_f32_e32 v95, s58, v149
	v_fmac_f32_e32 v96, s58, v150
	v_fmac_f32_e32 v97, s58, v151
	v_add_f32_e32 v196, v196, v94
	v_fmac_f32_e32 v197, v94, v94
	v_add_f32_e32 v130, v130, v95
	v_fmac_f32_e32 v142, v95, v95
	v_add_f32_e32 v196, v196, v96
	v_fmac_f32_e32 v197, v96, v96
	v_add_f32_e32 v130, v130, v97
	v_fmac_f32_e32 v142, v97, v97
	s_waitcnt lgkmcnt(5)
	v_fmac_f32_e32 v90, s58, v152
	v_fmac_f32_e32 v91, s58, v153
	v_fmac_f32_e32 v92, s58, v154
	v_fmac_f32_e32 v93, s58, v155
	v_add_f32_e32 v196, v196, v90
	v_fmac_f32_e32 v197, v90, v90
	v_add_f32_e32 v130, v130, v91
	v_fmac_f32_e32 v142, v91, v91
	v_add_f32_e32 v196, v196, v92
	v_fmac_f32_e32 v197, v92, v92
	v_add_f32_e32 v130, v130, v93
	v_fmac_f32_e32 v142, v93, v93
	s_waitcnt lgkmcnt(4)
	v_fmac_f32_e32 v86, s58, v156
	v_fmac_f32_e32 v87, s58, v157
	v_fmac_f32_e32 v88, s58, v158
	v_fmac_f32_e32 v89, s58, v159
	v_add_f32_e32 v196, v196, v86
	v_fmac_f32_e32 v197, v86, v86
	v_add_f32_e32 v130, v130, v87
	v_fmac_f32_e32 v142, v87, v87
	v_add_f32_e32 v196, v196, v88
	v_fmac_f32_e32 v197, v88, v88
	v_add_f32_e32 v130, v130, v89
	v_fmac_f32_e32 v142, v89, v89
	s_waitcnt lgkmcnt(3)
	v_fmac_f32_e32 v82, s58, v160
	v_fmac_f32_e32 v83, s58, v161
	v_fmac_f32_e32 v84, s58, v162
	v_fmac_f32_e32 v85, s58, v163
	v_add_f32_e32 v196, v196, v82
	v_fmac_f32_e32 v197, v82, v82
	v_add_f32_e32 v130, v130, v83
	v_fmac_f32_e32 v142, v83, v83
	v_add_f32_e32 v196, v196, v84
	v_fmac_f32_e32 v197, v84, v84
	v_add_f32_e32 v130, v130, v85
	v_fmac_f32_e32 v142, v85, v85
	s_waitcnt lgkmcnt(2)
	v_fmac_f32_e32 v78, s58, v164
	v_fmac_f32_e32 v79, s58, v165
	v_fmac_f32_e32 v80, s58, v166
	v_fmac_f32_e32 v81, s58, v167
	v_add_f32_e32 v196, v196, v78
	v_fmac_f32_e32 v197, v78, v78
	v_add_f32_e32 v130, v130, v79
	v_fmac_f32_e32 v142, v79, v79
	v_add_f32_e32 v196, v196, v80
	v_fmac_f32_e32 v197, v80, v80
	v_add_f32_e32 v130, v130, v81
	v_fmac_f32_e32 v142, v81, v81
	s_waitcnt lgkmcnt(1)
	v_fmac_f32_e32 v74, s58, v168
	v_fmac_f32_e32 v75, s58, v169
	v_fmac_f32_e32 v76, s58, v170
	v_fmac_f32_e32 v77, s58, v171
	v_add_f32_e32 v196, v196, v74
	v_fmac_f32_e32 v197, v74, v74
	v_add_f32_e32 v130, v130, v75
	v_fmac_f32_e32 v142, v75, v75
	v_add_f32_e32 v196, v196, v76
	v_fmac_f32_e32 v197, v76, v76
	v_add_f32_e32 v130, v130, v77
	v_fmac_f32_e32 v142, v77, v77
	s_waitcnt lgkmcnt(0)
	v_fmac_f32_e32 v70, s58, v172
	v_fmac_f32_e32 v71, s58, v173
	v_fmac_f32_e32 v72, s58, v174
	v_fmac_f32_e32 v73, s58, v175
	v_add_f32_e32 v196, v196, v70
	v_fmac_f32_e32 v197, v70, v70
	v_add_f32_e32 v130, v130, v71
	v_fmac_f32_e32 v142, v71, v71
	v_add_f32_e32 v196, v196, v72
	v_fmac_f32_e32 v197, v72, v72
	v_add_f32_e32 v130, v130, v73
	v_fmac_f32_e32 v142, v73, v73
	v_add_f32_e32 v196, v196, v130
	v_add_f32_e32 v197, v197, v142
	v_mov_b32_e32 v198, v196
	v_mov_b32_e32 v199, v197
	s_nop 1
	v_permlane16_swap_b32 v198, v196
	v_permlane16_swap_b32 v199, v197
	v_add_f32_e32 v196, v196, v198
	v_add_f32_e32 v197, v197, v199
	v_mov_b32_e32 v198, v196
	v_mov_b32_e32 v199, v197
	s_nop 1
	v_permlane32_swap_b32 v198, v196
	v_permlane32_swap_b32 v199, v197
	v_add_f32_e32 v196, v196, v198
	v_add_f32_e32 v197, v197, v199
	s_mov_b64 exec, 0xffff
	ds_write_b64 v134, v[196:197]
	s_mov_b64 exec, -1
	s_waitcnt lgkmcnt(0)
	s_barrier
; DI unsigned pk2(float lo, float hi) { const f32x2 v = {lo, hi}; const bf16x2_t b = __builtin_convertvector(v, bf16x2_t); return __builtin_bit_cast(unsigned, b); }
; DI void unit_O(const Params& p, char* lds, int l, int tile, int glu_tiles, int tile_b) {
;     ...
;     auto issue_x = [&](int half) {
;         if (l == 0) {
; #pragma unroll 1
;             for (int i = 0; i < 16; ++i) {
;                 const int pc = (wid * 16 + i + xrot) & 127, row = pc >> 2, phys = (pc & 3) * 64 + lane, logical = phys ^ (row & 15);
;                 __builtin_amdgcn_global_load_lds((const unsigned*)(xres + (r0 + half * 32 + row) * 1024 + logical * 4), (unsigned*)(XR + pc * 1024 + lane * 16), 16, 0, 0);
;             }
;         } else {
; #pragma unroll 1
;             for (int i = 0; i < 8; ++i) {
;                 const int pc = (wid * 8 + i + (xrot >> 1)) & 63, kt = pc >> 1, sub = pc & 1;
;                 __builtin_amdgcn_global_load_lds((const unsigned*)(xbres + ((size_t)kt * 128 + half * 32) * 32 + sub * 512 + lane * 8), (unsigned*)(XR + pc * 1024 + lane * 16), 16, 0, 0);
;             }
;         }
;     ...
;         for (int mh = 0; mh < 2; ++mh) {
;             const int mt = half * 2 + mh, rl = mh * 16 + l15, row = mt * 16 + l15;
;             float s = 0.f, ss = 0.f;
; #pragma unroll
;             for (int w = 0; w < 4; ++w) { const f32x4 v = *(const f32x4*)&red[rl * 16 + 4 * w]; s += v[0] + v[2]; ss += v[1] + v[3]; }
;             const float mu = s * (1.f / 1024.f);
;             const float var = ss * (1.f / 1024.f) - mu * mu;
;             const float rs = rsqrtf(var + LN_EPS);
;             float* orow = xo + (r0 + row) * 1024 + wid * 128 + quad * 4;
;             bf16_t* brow = xbo + xb_off((int)r0 + row, wid * 128) + quad * 4;
;             const float* gp = GB + wid * 128 + quad * 4;
; #pragma unroll
;             for (int nt = 0; nt < 8; ++nt) {
;                 const f32x4 g = *(const f32x4*)(gp + nt * 16), bb = *(const f32x4*)(gp + 1024 + nt * 16);
;                 f32x4 o;
; #pragma unroll
;                 for (int i = 0; i < 4; ++i) o[i] = (acc[mt][nt][i] - mu) * rs * g[i] + bb[i];
;                 if (l == 0) *(u32x2*)(brow + (nt >> 1) * 4096 + (nt & 1) * 16) = (u32x2){pk2(o[0], o[1]), pk2(o[2], o[3])};
;                 else *(f32x4*)(orow + nt * 16) = o;
;             }
;         }
	s_add_u32 s92, s96, 0x20000
	s_addc_u32 s93, s97, 0
	s_add_u32 s40, s91, 0x0
	s_mov_b32 m0, s40
	s_nop 0
	global_load_lds_dwordx4 v208, s[92:93]
	global_load_lds_dwordx4 v208, s[92:93] offset:1024
	global_load_lds_dwordx4 v208, s[92:93] offset:2048
	global_load_lds_dwordx4 v208, s[92:93] offset:3072
	s_add_u32 s92, s96, 0x21000
	s_addc_u32 s93, s97, 0
	s_add_u32 s40, s91, 0x1000
	s_mov_b32 m0, s40
	s_nop 0
	global_load_lds_dwordx4 v209, s[92:93]
	global_load_lds_dwordx4 v209, s[92:93] offset:1024
	global_load_lds_dwordx4 v209, s[92:93] offset:2048
	global_load_lds_dwordx4 v209, s[92:93] offset:3072
	ds_read_b128 v[160:163], v135 offset:0
	ds_read_b128 v[164:167], v135 offset:16
	ds_read_b128 v[168:171], v135 offset:32
	ds_read_b128 v[172:175], v135 offset:48
	s_waitcnt lgkmcnt(0)
	v_add_f32_e32 v160, v160, v162
	v_add_f32_e32 v161, v161, v163
	v_add_f32_e32 v164, v164, v166
	v_add_f32_e32 v165, v165, v167
	v_add_f32_e32 v168, v168, v170
	v_add_f32_e32 v169, v169, v171
	v_add_f32_e32 v172, v172, v174
	v_add_f32_e32 v173, v173, v175
	v_add_f32_e32 v160, v160, v164
	v_add_f32_e32 v161, v161, v165
	v_add_f32_e32 v168, v168, v172
	v_add_f32_e32 v169, v169, v173
	v_add_f32_e32 v160, v160, v168
	v_add_f32_e32 v161, v161, v169
	v_mul_f32_e32 v192, 0x3a800000, v160
	v_mul_f32_e32 v193, 0x3a800000, v161
	v_fma_f32 v193, -v192, v192, v193
	v_add_f32_e32 v193, 0x3727c5ac, v193
	v_rsq_f32_e32 v193, v193
	s_nop 0
	s_add_u32 s94, s78, 0x0
	s_addc_u32 s95, s79, 0
	ds_read_b128 v[176:179], v136
	ds_read_b128 v[180:183], v136 offset:4096
	ds_read_b128 v[184:187], v136 offset:64
	ds_read_b128 v[188:191], v136 offset:4160
	s_waitcnt lgkmcnt(2)
	v_sub_f32_e32 v98, v98, v192
	v_mul_f32_e32 v98, v98, v193
	v_fma_f32 v98, v176, v98, v180
	v_sub_f32_e32 v99, v99, v192
	v_mul_f32_e32 v99, v99, v193
	v_fma_f32 v99, v177, v99, v181
	v_sub_f32_e32 v100, v100, v192
	v_mul_f32_e32 v100, v100, v193
	v_fma_f32 v100, v178, v100, v182
	v_sub_f32_e32 v101, v101, v192
	v_mul_f32_e32 v101, v101, v193
	v_fma_f32 v101, v179, v101, v183
	v_cvt_pk_bf16_f32 v144, v98, v99
	v_cvt_pk_bf16_f32 v145, v100, v101
	ds_read_b128 v[176:179], v136 offset:128
	ds_read_b128 v[180:183], v136 offset:4224
	s_waitcnt lgkmcnt(2)
	v_sub_f32_e32 v94, v94, v192
	v_mul_f32_e32 v94, v94, v193
	v_fma_f32 v94, v184, v94, v188
	v_sub_f32_e32 v95, v95, v192
	v_mul_f32_e32 v95, v95, v193
	v_fma_f32 v95, v185, v95, v189
	v_sub_f32_e32 v96, v96, v192
	v_mul_f32_e32 v96, v96, v193
	v_fma_f32 v96, v186, v96, v190
	v_sub_f32_e32 v97, v97, v192
	v_mul_f32_e32 v97, v97, v193
	v_fma_f32 v97, v187, v97, v191
	v_cvt_pk_bf16_f32 v146, v94, v95
	v_cvt_pk_bf16_f32 v147, v96, v97
	s_nop 1
	v_permlane16_swap_b32 v144, v146
	v_permlane16_swap_b32 v145, v147
	global_store_dwordx4 v137, v[144:147], s[94:95] sc1
	s_add_u32 s94, s94, 0x2000
	s_addc_u32 s95, s95, 0
	ds_read_b128 v[184:187], v136 offset:192
	ds_read_b128 v[188:191], v136 offset:4288
	s_waitcnt lgkmcnt(2)
	v_sub_f32_e32 v90, v90, v192
	v_mul_f32_e32 v90, v90, v193
	v_fma_f32 v90, v176, v90, v180
	v_sub_f32_e32 v91, v91, v192
	v_mul_f32_e32 v91, v91, v193
	v_fma_f32 v91, v177, v91, v181
	v_sub_f32_e32 v92, v92, v192
	v_mul_f32_e32 v92, v92, v193
	v_fma_f32 v92, v178, v92, v182
	v_sub_f32_e32 v93, v93, v192
	v_mul_f32_e32 v93, v93, v193
	v_fma_f32 v93, v179, v93, v183
	v_cvt_pk_bf16_f32 v152, v90, v91
	v_cvt_pk_bf16_f32 v153, v92, v93
	ds_read_b128 v[176:179], v136 offset:256
	ds_read_b128 v[180:183], v136 offset:4352
	s_waitcnt lgkmcnt(2)
	v_sub_f32_e32 v86, v86, v192
	v_mul_f32_e32 v86, v86, v193
	v_fma_f32 v86, v184, v86, v188
	v_sub_f32_e32 v87, v87, v192
	v_mul_f32_e32 v87, v87, v193
	v_fma_f32 v87, v185, v87, v189
	v_sub_f32_e32 v88, v88, v192
	v_mul_f32_e32 v88, v88, v193
	v_fma_f32 v88, v186, v88, v190
	v_sub_f32_e32 v89, v89, v192
	v_mul_f32_e32 v89, v89, v193
	v_fma_f32 v89, v187, v89, v191
	v_cvt_pk_bf16_f32 v154, v86, v87
	v_cvt_pk_bf16_f32 v155, v88, v89
	s_nop 1
	v_permlane16_swap_b32 v152, v154
	v_permlane16_swap_b32 v153, v155
	global_store_dwordx4 v137, v[152:155], s[94:95] sc1
	s_add_u32 s94, s94, 0x2000
	s_addc_u32 s95, s95, 0
	ds_read_b128 v[184:187], v136 offset:320
	ds_read_b128 v[188:191], v136 offset:4416
	s_waitcnt lgkmcnt(2)
	v_sub_f32_e32 v82, v82, v192
	v_mul_f32_e32 v82, v82, v193
	v_fma_f32 v82, v176, v82, v180
	v_sub_f32_e32 v83, v83, v192
	v_mul_f32_e32 v83, v83, v193
	v_fma_f32 v83, v177, v83, v181
	v_sub_f32_e32 v84, v84, v192
	v_mul_f32_e32 v84, v84, v193
	v_fma_f32 v84, v178, v84, v182
	v_sub_f32_e32 v85, v85, v192
	v_mul_f32_e32 v85, v85, v193
	v_fma_f32 v85, v179, v85, v183
	v_cvt_pk_bf16_f32 v144, v82, v83
	v_cvt_pk_bf16_f32 v145, v84, v85
	ds_read_b128 v[176:179], v136 offset:384
	ds_read_b128 v[180:183], v136 offset:4480
	s_waitcnt lgkmcnt(2)
	v_sub_f32_e32 v78, v78, v192
	v_mul_f32_e32 v78, v78, v193
	v_fma_f32 v78, v184, v78, v188
	v_sub_f32_e32 v79, v79, v192
	v_mul_f32_e32 v79, v79, v193
	v_fma_f32 v79, v185, v79, v189
	v_sub_f32_e32 v80, v80, v192
	v_mul_f32_e32 v80, v80, v193
	v_fma_f32 v80, v186, v80, v190
	v_sub_f32_e32 v81, v81, v192
	v_mul_f32_e32 v81, v81, v193
	v_fma_f32 v81, v187, v81, v191
	v_cvt_pk_bf16_f32 v146, v78, v79
	v_cvt_pk_bf16_f32 v147, v80, v81
	s_nop 1
	v_permlane16_swap_b32 v144, v146
	v_permlane16_swap_b32 v145, v147
	global_store_dwordx4 v137, v[144:147], s[94:95] sc1
	s_add_u32 s94, s94, 0x2000
	s_addc_u32 s95, s95, 0
	ds_read_b128 v[184:187], v136 offset:448
	ds_read_b128 v[188:191], v136 offset:4544
	s_waitcnt lgkmcnt(2)
	v_sub_f32_e32 v74, v74, v192
	v_mul_f32_e32 v74, v74, v193
	v_fma_f32 v74, v176, v74, v180
	v_sub_f32_e32 v75, v75, v192
	v_mul_f32_e32 v75, v75, v193
	v_fma_f32 v75, v177, v75, v181
	v_sub_f32_e32 v76, v76, v192
	v_mul_f32_e32 v76, v76, v193
	v_fma_f32 v76, v178, v76, v182
	v_sub_f32_e32 v77, v77, v192
	v_mul_f32_e32 v77, v77, v193
	v_fma_f32 v77, v179, v77, v183
	v_cvt_pk_bf16_f32 v152, v74, v75
	v_cvt_pk_bf16_f32 v153, v76, v77
	s_waitcnt lgkmcnt(0)
	v_sub_f32_e32 v70, v70, v192
	v_mul_f32_e32 v70, v70, v193
	v_fma_f32 v70, v184, v70, v188
	v_sub_f32_e32 v71, v71, v192
	v_mul_f32_e32 v71, v71, v193
	v_fma_f32 v71, v185, v71, v189
	v_sub_f32_e32 v72, v72, v192
	v_mul_f32_e32 v72, v72, v193
	v_fma_f32 v72, v186, v72, v190
	v_sub_f32_e32 v73, v73, v192
	v_mul_f32_e32 v73, v73, v193
	v_fma_f32 v73, v187, v73, v191
	v_cvt_pk_bf16_f32 v154, v70, v71
	v_cvt_pk_bf16_f32 v155, v72, v73
	s_nop 1
	v_permlane16_swap_b32 v152, v154
	v_permlane16_swap_b32 v153, v155
	global_store_dwordx4 v137, v[152:155], s[94:95] sc1
	s_waitcnt vmcnt(12) lgkmcnt(0)
	s_barrier
; DI float bf2f(unsigned b) { return __uint_as_float(b << 16); }
; DI void unit_O(const Params& p, char* lds, int l, int tile, int glu_tiles, int tile_b) {
;     ...
;         float s2[2], ss2[2];
; #pragma unroll
;         for (int mh = 0; mh < 2; ++mh) {
;             const int mt = half * 2 + mh, rl = mh * 16 + l15;
;             float s = 0.f, ss = 0.f;
; #pragma unroll
;             for (int nt = 0; nt < 8; ++nt) {
;                 f32x4 xr;
;                 if (l == 0) {
;                     const int chunk = wid * 32 + nt * 4 + quad;
;                     xr = *(const f32x4*)(XR + rl * 4096 + ((chunk ^ l15) << 4));
;                 } else {
;                     const u32x2 hb = *(const u32x2*)(XR + ((wid * 4 + (nt >> 1)) * 32 + rl) * 64 + (nt & 1) * 32 + quad * 8);
;                     xr = (f32x4){bf2f(hb[0] & 0xffffu), bf2f(hb[0] >> 16), bf2f(hb[1] & 0xffffu), bf2f(hb[1] >> 16)};
;                 }
; #pragma unroll
;                 for (int i = 0; i < 4; ++i) { const float v = acc[mt][nt][i] + DN_ALPHA * xr[i]; acc[mt][nt][i] = v; s += v; ss += v * v; }
;             }
;             s2[mh] = s; ss2[mh] = ss;
;         }
; #pragma unroll
;         for (int mh = 0; mh < 2; ++mh) { s2[mh] += __shfl_xor(s2[mh], 16); ss2[mh] += __shfl_xor(ss2[mh], 16); }
; #pragma unroll
;         for (int mh = 0; mh < 2; ++mh) { s2[mh] += __shfl_xor(s2[mh], 32); ss2[mh] += __shfl_xor(ss2[mh], 32); }
;         if (quad == 0) {
; #pragma unroll
;             for (int mh = 0; mh < 2; ++mh) *(f32x2*)&red[((mh * 16 + l15) * 8 + wid) * 2] = (f32x2){s2[mh], ss2[mh]};
;         }
;         __syncthreads();
;         if (half == 0) issue_x(1);
; #pragma unroll
;         for (int mh = 0; mh < 2; ++mh) {
;             const int mt = half * 2 + mh, rl = mh * 16 + l15, row = mt * 16 + l15;
;             float s = 0.f, ss = 0.f;
; #pragma unroll
;             for (int w = 0; w < 4; ++w) { const f32x4 v = *(const f32x4*)&red[rl * 16 + 4 * w]; s += v[0] + v[2]; ss += v[1] + v[3]; }
;             const float mu = s * (1.f / 1024.f);
;             const float var = ss * (1.f / 1024.f) - mu * mu;
;             const float rs = rsqrtf(var + LN_EPS);
	ds_read_b128 v[144:147], v204
	ds_read_b128 v[148:151], v205
	ds_read_b128 v[152:155], v206
	ds_read_b128 v[156:159], v207
	ds_read_b128 v[160:163], v204 offset:256
	ds_read_b128 v[164:167], v205 offset:256
	ds_read_b128 v[168:171], v206 offset:256
	ds_read_b128 v[172:175], v207 offset:256
	s_waitcnt lgkmcnt(7)
	v_fmac_f32_e32 v126, s58, v144
	v_fmac_f32_e32 v127, s58, v145
	v_fmac_f32_e32 v128, s58, v146
	v_fmac_f32_e32 v129, s58, v147
	v_mov_b32_e32 v196, v126
	v_mul_f32_e32 v197, v126, v126
	v_mov_b32_e32 v130, v127
	v_mul_f32_e32 v142, v127, v127
	v_add_f32_e32 v196, v196, v128
	v_fmac_f32_e32 v197, v128, v128
	v_add_f32_e32 v130, v130, v129
	v_fmac_f32_e32 v142, v129, v129
	s_waitcnt lgkmcnt(6)
	v_fmac_f32_e32 v122, s58, v148
	v_fmac_f32_e32 v123, s58, v149
	v_fmac_f32_e32 v124, s58, v150
	v_fmac_f32_e32 v125, s58, v151
	v_add_f32_e32 v196, v196, v122
	v_fmac_f32_e32 v197, v122, v122
	v_add_f32_e32 v130, v130, v123
	v_fmac_f32_e32 v142, v123, v123
	v_add_f32_e32 v196, v196, v124
	v_fmac_f32_e32 v197, v124, v124
	v_add_f32_e32 v130, v130, v125
	v_fmac_f32_e32 v142, v125, v125
	s_waitcnt lgkmcnt(5)
	v_fmac_f32_e32 v118, s58, v152
	v_fmac_f32_e32 v119, s58, v153
	v_fmac_f32_e32 v120, s58, v154
	v_fmac_f32_e32 v121, s58, v155
	v_add_f32_e32 v196, v196, v118
	v_fmac_f32_e32 v197, v118, v118
	v_add_f32_e32 v130, v130, v119
	v_fmac_f32_e32 v142, v119, v119
	v_add_f32_e32 v196, v196, v120
	v_fmac_f32_e32 v197, v120, v120
	v_add_f32_e32 v130, v130, v121
	v_fmac_f32_e32 v142, v121, v121
	s_waitcnt lgkmcnt(4)
	v_fmac_f32_e32 v114, s58, v156
	v_fmac_f32_e32 v115, s58, v157
	v_fmac_f32_e32 v116, s58, v158
	v_fmac_f32_e32 v117, s58, v159
	v_add_f32_e32 v196, v196, v114
	v_fmac_f32_e32 v197, v114, v114
	v_add_f32_e32 v130, v130, v115
	v_fmac_f32_e32 v142, v115, v115
	v_add_f32_e32 v196, v196, v116
	v_fmac_f32_e32 v197, v116, v116
	v_add_f32_e32 v130, v130, v117
	v_fmac_f32_e32 v142, v117, v117
	s_waitcnt lgkmcnt(3)
	v_fmac_f32_e32 v110, s58, v160
	v_fmac_f32_e32 v111, s58, v161
	v_fmac_f32_e32 v112, s58, v162
	v_fmac_f32_e32 v113, s58, v163
	v_add_f32_e32 v196, v196, v110
	v_fmac_f32_e32 v197, v110, v110
	v_add_f32_e32 v130, v130, v111
	v_fmac_f32_e32 v142, v111, v111
	v_add_f32_e32 v196, v196, v112
	v_fmac_f32_e32 v197, v112, v112
	v_add_f32_e32 v130, v130, v113
	v_fmac_f32_e32 v142, v113, v113
	s_waitcnt lgkmcnt(2)
	v_fmac_f32_e32 v106, s58, v164
	v_fmac_f32_e32 v107, s58, v165
	v_fmac_f32_e32 v108, s58, v166
	v_fmac_f32_e32 v109, s58, v167
	v_add_f32_e32 v196, v196, v106
	v_fmac_f32_e32 v197, v106, v106
	v_add_f32_e32 v130, v130, v107
	v_fmac_f32_e32 v142, v107, v107
	v_add_f32_e32 v196, v196, v108
	v_fmac_f32_e32 v197, v108, v108
	v_add_f32_e32 v130, v130, v109
	v_fmac_f32_e32 v142, v109, v109
	s_waitcnt lgkmcnt(1)
	v_fmac_f32_e32 v102, s58, v168
	v_fmac_f32_e32 v103, s58, v169
	v_fmac_f32_e32 v104, s58, v170
	v_fmac_f32_e32 v105, s58, v171
	v_add_f32_e32 v196, v196, v102
	v_fmac_f32_e32 v197, v102, v102
	v_add_f32_e32 v130, v130, v103
	v_fmac_f32_e32 v142, v103, v103
	v_add_f32_e32 v196, v196, v104
	v_fmac_f32_e32 v197, v104, v104
	v_add_f32_e32 v130, v130, v105
	v_fmac_f32_e32 v142, v105, v105
	s_waitcnt lgkmcnt(0)
	v_fmac_f32_e32 v66, s58, v172
	v_fmac_f32_e32 v67, s58, v173
	v_fmac_f32_e32 v68, s58, v174
	v_fmac_f32_e32 v69, s58, v175
	v_add_f32_e32 v196, v196, v66
	v_fmac_f32_e32 v197, v66, v66
	v_add_f32_e32 v130, v130, v67
	v_fmac_f32_e32 v142, v67, v67
	v_add_f32_e32 v196, v196, v68
	v_fmac_f32_e32 v197, v68, v68
	v_add_f32_e32 v130, v130, v69
	v_fmac_f32_e32 v142, v69, v69
	v_add_f32_e32 v196, v196, v130
	v_add_f32_e32 v197, v197, v142
	v_mov_b32_e32 v198, v196
	v_mov_b32_e32 v199, v197
	s_nop 1
	v_permlane16_swap_b32 v198, v196
	v_permlane16_swap_b32 v199, v197
	v_add_f32_e32 v196, v196, v198
	v_add_f32_e32 v197, v197, v199
	v_mov_b32_e32 v198, v196
	v_mov_b32_e32 v199, v197
	s_nop 1
	v_permlane32_swap_b32 v198, v196
	v_permlane32_swap_b32 v199, v197
	v_add_f32_e32 v196, v196, v198
	v_add_f32_e32 v197, v197, v199
	s_mov_b64 exec, 0xffff
	ds_write_b64 v134, v[196:197]
	s_mov_b64 exec, -1
	s_waitcnt lgkmcnt(0)
	s_barrier
	s_add_u32 s92, s96, 0x30000
	s_addc_u32 s93, s97, 0
	s_add_u32 s40, s91, 0x10000
	s_mov_b32 m0, s40
	s_nop 0
	global_load_lds_dwordx4 v208, s[92:93]
	global_load_lds_dwordx4 v208, s[92:93] offset:1024
	global_load_lds_dwordx4 v208, s[92:93] offset:2048
	global_load_lds_dwordx4 v208, s[92:93] offset:3072
	s_add_u32 s92, s96, 0x31000
	s_addc_u32 s93, s97, 0
	s_add_u32 s40, s91, 0x11000
	s_mov_b32 m0, s40
	s_nop 0
	global_load_lds_dwordx4 v209, s[92:93]
	global_load_lds_dwordx4 v209, s[92:93] offset:1024
	global_load_lds_dwordx4 v209, s[92:93] offset:2048
	global_load_lds_dwordx4 v209, s[92:93] offset:3072
	ds_read_b128 v[160:163], v135 offset:0
	ds_read_b128 v[164:167], v135 offset:16
	ds_read_b128 v[168:171], v135 offset:32
	ds_read_b128 v[172:175], v135 offset:48
	s_waitcnt lgkmcnt(0)
	v_add_f32_e32 v160, v160, v162
	v_add_f32_e32 v161, v161, v163
	v_add_f32_e32 v164, v164, v166
	v_add_f32_e32 v165, v165, v167
	v_add_f32_e32 v168, v168, v170
	v_add_f32_e32 v169, v169, v171
	v_add_f32_e32 v172, v172, v174
	v_add_f32_e32 v173, v173, v175
	v_add_f32_e32 v160, v160, v164
	v_add_f32_e32 v161, v161, v165
	v_add_f32_e32 v168, v168, v172
	v_add_f32_e32 v169, v169, v173
	v_add_f32_e32 v160, v160, v168
	v_add_f32_e32 v161, v161, v169
	v_mul_f32_e32 v192, 0x3a800000, v160
	v_mul_f32_e32 v193, 0x3a800000, v161
	v_fma_f32 v193, -v192, v192, v193
	v_add_f32_e32 v193, 0x3727c5ac, v193
	v_rsq_f32_e32 v193, v193
	s_nop 0
	s_add_u32 s94, s78, 0x400
	s_addc_u32 s95, s79, 0
	ds_read_b128 v[176:179], v136
	ds_read_b128 v[180:183], v136 offset:4096
	ds_read_b128 v[184:187], v136 offset:64
	ds_read_b128 v[188:191], v136 offset:4160
	s_waitcnt lgkmcnt(2)
; DI unsigned pk2(float lo, float hi) { const f32x2 v = {lo, hi}; const bf16x2_t b = __builtin_convertvector(v, bf16x2_t); return __builtin_bit_cast(unsigned, b); }
; DI size_t xb_off(int tok, int col) { return ((size_t)(((tok >> 7) * 32 + (col >> 5)) * 128 + (tok & 127))) * 32 + (col & 31); }
; DI void unit_O(const Params& p, char* lds, int l, int tile, int glu_tiles, int tile_b) {
;     ...
;             float* orow = xo + (r0 + row) * 1024 + wid * 128 + quad * 4;
;             bf16_t* brow = xbo + xb_off((int)r0 + row, wid * 128) + quad * 4;
;             const float* gp = GB + wid * 128 + quad * 4;
; #pragma unroll
;             for (int nt = 0; nt < 8; ++nt) {
;                 const f32x4 g = *(const f32x4*)(gp + nt * 16), bb = *(const f32x4*)(gp + 1024 + nt * 16);
;                 f32x4 o;
; #pragma unroll
;                 for (int i = 0; i < 4; ++i) o[i] = (acc[mt][nt][i] - mu) * rs * g[i] + bb[i];
;                 if (l == 0) *(u32x2*)(brow + (nt >> 1) * 4096 + (nt & 1) * 16) = (u32x2){pk2(o[0], o[1]), pk2(o[2], o[3])};
;                 else *(f32x4*)(orow + nt * 16) = o;
;             }
;         }
	v_sub_f32_e32 v126, v126, v192
	v_mul_f32_e32 v126, v126, v193
	v_fma_f32 v126, v176, v126, v180
	v_sub_f32_e32 v127, v127, v192
	v_mul_f32_e32 v127, v127, v193
	v_fma_f32 v127, v177, v127, v181
	v_sub_f32_e32 v128, v128, v192
	v_mul_f32_e32 v128, v128, v193
	v_fma_f32 v128, v178, v128, v182
	v_sub_f32_e32 v129, v129, v192
	v_mul_f32_e32 v129, v129, v193
	v_fma_f32 v129, v179, v129, v183
	v_cvt_pk_bf16_f32 v144, v126, v127
	v_cvt_pk_bf16_f32 v145, v128, v129
	ds_read_b128 v[176:179], v136 offset:128
	ds_read_b128 v[180:183], v136 offset:4224
	s_waitcnt lgkmcnt(2)
	v_sub_f32_e32 v122, v122, v192
	v_mul_f32_e32 v122, v122, v193
	v_fma_f32 v122, v184, v122, v188
	v_sub_f32_e32 v123, v123, v192
	v_mul_f32_e32 v123, v123, v193
	v_fma_f32 v123, v185, v123, v189
	v_sub_f32_e32 v124, v124, v192
	v_mul_f32_e32 v124, v124, v193
	v_fma_f32 v124, v186, v124, v190
	v_sub_f32_e32 v125, v125, v192
	v_mul_f32_e32 v125, v125, v193
	v_fma_f32 v125, v187, v125, v191
	v_cvt_pk_bf16_f32 v146, v122, v123
	v_cvt_pk_bf16_f32 v147, v124, v125
	s_nop 1
	v_permlane16_swap_b32 v144, v146
	v_permlane16_swap_b32 v145, v147
	global_store_dwordx4 v137, v[144:147], s[94:95] sc1
	s_add_u32 s94, s94, 0x2000
	s_addc_u32 s95, s95, 0
	ds_read_b128 v[184:187], v136 offset:192
	ds_read_b128 v[188:191], v136 offset:4288
	s_waitcnt lgkmcnt(2)
	v_sub_f32_e32 v118, v118, v192
	v_mul_f32_e32 v118, v118, v193
	v_fma_f32 v118, v176, v118, v180
	v_sub_f32_e32 v119, v119, v192
	v_mul_f32_e32 v119, v119, v193
	v_fma_f32 v119, v177, v119, v181
	v_sub_f32_e32 v120, v120, v192
	v_mul_f32_e32 v120, v120, v193
	v_fma_f32 v120, v178, v120, v182
	v_sub_f32_e32 v121, v121, v192
	v_mul_f32_e32 v121, v121, v193
	v_fma_f32 v121, v179, v121, v183
	v_cvt_pk_bf16_f32 v152, v118, v119
	v_cvt_pk_bf16_f32 v153, v120, v121
	ds_read_b128 v[176:179], v136 offset:256
	ds_read_b128 v[180:183], v136 offset:4352
	s_waitcnt lgkmcnt(2)
	v_sub_f32_e32 v114, v114, v192
	v_mul_f32_e32 v114, v114, v193
	v_fma_f32 v114, v184, v114, v188
	v_sub_f32_e32 v115, v115, v192
	v_mul_f32_e32 v115, v115, v193
	v_fma_f32 v115, v185, v115, v189
	v_sub_f32_e32 v116, v116, v192
	v_mul_f32_e32 v116, v116, v193
	v_fma_f32 v116, v186, v116, v190
	v_sub_f32_e32 v117, v117, v192
	v_mul_f32_e32 v117, v117, v193
	v_fma_f32 v117, v187, v117, v191
	v_cvt_pk_bf16_f32 v154, v114, v115
	v_cvt_pk_bf16_f32 v155, v116, v117
	s_nop 1
	v_permlane16_swap_b32 v152, v154
	v_permlane16_swap_b32 v153, v155
	global_store_dwordx4 v137, v[152:155], s[94:95] sc1
	s_add_u32 s94, s94, 0x2000
	s_addc_u32 s95, s95, 0
	ds_read_b128 v[184:187], v136 offset:320
	ds_read_b128 v[188:191], v136 offset:4416
	s_waitcnt lgkmcnt(2)
	v_sub_f32_e32 v110, v110, v192
	v_mul_f32_e32 v110, v110, v193
	v_fma_f32 v110, v176, v110, v180
	v_sub_f32_e32 v111, v111, v192
	v_mul_f32_e32 v111, v111, v193
	v_fma_f32 v111, v177, v111, v181
	v_sub_f32_e32 v112, v112, v192
	v_mul_f32_e32 v112, v112, v193
	v_fma_f32 v112, v178, v112, v182
	v_sub_f32_e32 v113, v113, v192
	v_mul_f32_e32 v113, v113, v193
	v_fma_f32 v113, v179, v113, v183
	v_cvt_pk_bf16_f32 v144, v110, v111
	v_cvt_pk_bf16_f32 v145, v112, v113
	ds_read_b128 v[176:179], v136 offset:384
	ds_read_b128 v[180:183], v136 offset:4480
	s_waitcnt lgkmcnt(2)
	v_sub_f32_e32 v106, v106, v192
	v_mul_f32_e32 v106, v106, v193
	v_fma_f32 v106, v184, v106, v188
	v_sub_f32_e32 v107, v107, v192
	v_mul_f32_e32 v107, v107, v193
	v_fma_f32 v107, v185, v107, v189
	v_sub_f32_e32 v108, v108, v192
	v_mul_f32_e32 v108, v108, v193
	v_fma_f32 v108, v186, v108, v190
	v_sub_f32_e32 v109, v109, v192
	v_mul_f32_e32 v109, v109, v193
	v_fma_f32 v109, v187, v109, v191
	v_cvt_pk_bf16_f32 v146, v106, v107
	v_cvt_pk_bf16_f32 v147, v108, v109
	s_nop 1
	v_permlane16_swap_b32 v144, v146
	v_permlane16_swap_b32 v145, v147
	global_store_dwordx4 v137, v[144:147], s[94:95] sc1
	s_add_u32 s94, s94, 0x2000
	s_addc_u32 s95, s95, 0
	ds_read_b128 v[184:187], v136 offset:448
	ds_read_b128 v[188:191], v136 offset:4544
	s_waitcnt lgkmcnt(2)
	v_sub_f32_e32 v102, v102, v192
	v_mul_f32_e32 v102, v102, v193
	v_fma_f32 v102, v176, v102, v180
	v_sub_f32_e32 v103, v103, v192
	v_mul_f32_e32 v103, v103, v193
	v_fma_f32 v103, v177, v103, v181
	v_sub_f32_e32 v104, v104, v192
	v_mul_f32_e32 v104, v104, v193
	v_fma_f32 v104, v178, v104, v182
	v_sub_f32_e32 v105, v105, v192
	v_mul_f32_e32 v105, v105, v193
	v_fma_f32 v105, v179, v105, v183
	v_cvt_pk_bf16_f32 v152, v102, v103
	v_cvt_pk_bf16_f32 v153, v104, v105
	s_waitcnt lgkmcnt(0)
	v_sub_f32_e32 v66, v66, v192
	v_mul_f32_e32 v66, v66, v193
	v_fma_f32 v66, v184, v66, v188
	v_sub_f32_e32 v67, v67, v192
	v_mul_f32_e32 v67, v67, v193
	v_fma_f32 v67, v185, v67, v189
	v_sub_f32_e32 v68, v68, v192
	v_mul_f32_e32 v68, v68, v193
	v_fma_f32 v68, v186, v68, v190
	v_sub_f32_e32 v69, v69, v192
	v_mul_f32_e32 v69, v69, v193
	v_fma_f32 v69, v187, v69, v191
	v_cvt_pk_bf16_f32 v154, v66, v67
	v_cvt_pk_bf16_f32 v155, v68, v69
	s_nop 1
	v_permlane16_swap_b32 v152, v154
	v_permlane16_swap_b32 v153, v155
	global_store_dwordx4 v137, v[152:155], s[94:95] sc1
	s_waitcnt vmcnt(16) lgkmcnt(0)
	s_barrier
; DI void unit_O(const Params& p, char* lds, int l, int tile, int glu_tiles, int tile_b) {
;     ...
;         float s2[2], ss2[2];
; #pragma unroll
;         for (int mh = 0; mh < 2; ++mh) {
;             const int mt = half * 2 + mh, rl = mh * 16 + l15;
;             float s = 0.f, ss = 0.f;
; #pragma unroll
;             for (int nt = 0; nt < 8; ++nt) {
;                 f32x4 xr;
;                 if (l == 0) {
;                     const int chunk = wid * 32 + nt * 4 + quad;
;                     xr = *(const f32x4*)(XR + rl * 4096 + ((chunk ^ l15) << 4));
;                 } else {
;                     const u32x2 hb = *(const u32x2*)(XR + ((wid * 4 + (nt >> 1)) * 32 + rl) * 64 + (nt & 1) * 32 + quad * 8);
;                     xr = (f32x4){bf2f(hb[0] & 0xffffu), bf2f(hb[0] >> 16), bf2f(hb[1] & 0xffffu), bf2f(hb[1] >> 16)};
;                 }
; #pragma unroll
;                 for (int i = 0; i < 4; ++i) { const float v = acc[mt][nt][i] + DN_ALPHA * xr[i]; acc[mt][nt][i] = v; s += v; ss += v * v; }
;             }
;             s2[mh] = s; ss2[mh] = ss;
;         }
; #pragma unroll
;         for (int mh = 0; mh < 2; ++mh) { s2[mh] += __shfl_xor(s2[mh], 16); ss2[mh] += __shfl_xor(ss2[mh], 16); }
; #pragma unroll
;         for (int mh = 0; mh < 2; ++mh) { s2[mh] += __shfl_xor(s2[mh], 32); ss2[mh] += __shfl_xor(ss2[mh], 32); }
;         if (quad == 0) {
; #pragma unroll
;             for (int mh = 0; mh < 2; ++mh) *(f32x2*)&red[((mh * 16 + l15) * 8 + wid) * 2] = (f32x2){s2[mh], ss2[mh]};
;         }
;         __syncthreads();
;         if (half == 0) issue_x(1);
; #pragma unroll
;         for (int mh = 0; mh < 2; ++mh) {
;             const int mt = half * 2 + mh, rl = mh * 16 + l15, row = mt * 16 + l15;
;             float s = 0.f, ss = 0.f;
; #pragma unroll
;             for (int w = 0; w < 4; ++w) { const f32x4 v = *(const f32x4*)&red[rl * 16 + 4 * w]; s += v[0] + v[2]; ss += v[1] + v[3]; }
;             const float mu = s * (1.f / 1024.f);
;             const float var = ss * (1.f / 1024.f) - mu * mu;
;             const float rs = rsqrtf(var + LN_EPS);
;             float* orow = xo + (r0 + row) * 1024 + wid * 128 + quad * 4;
;             bf16_t* brow = xbo + xb_off((int)r0 + row, wid * 128) + quad * 4;
;             const float* gp = GB + wid * 128 + quad * 4;
; #pragma unroll
;             for (int nt = 0; nt < 8; ++nt) {
	ds_read_b128 v[144:147], v200
	ds_read_b128 v[148:151], v201
	ds_read_b128 v[152:155], v202
	ds_read_b128 v[156:159], v203
	ds_read_b128 v[160:163], v200 offset:256
	ds_read_b128 v[164:167], v201 offset:256
	ds_read_b128 v[168:171], v202 offset:256
	ds_read_b128 v[172:175], v203 offset:256
	s_waitcnt lgkmcnt(7)
	v_fmac_f32_e32 v34, s58, v144
	v_fmac_f32_e32 v35, s58, v145
	v_fmac_f32_e32 v36, s58, v146
	v_fmac_f32_e32 v37, s58, v147
	v_mov_b32_e32 v196, v34
	v_mul_f32_e32 v197, v34, v34
	v_mov_b32_e32 v130, v35
	v_mul_f32_e32 v142, v35, v35
	v_add_f32_e32 v196, v196, v36
	v_fmac_f32_e32 v197, v36, v36
	v_add_f32_e32 v130, v130, v37
	v_fmac_f32_e32 v142, v37, v37
	s_waitcnt lgkmcnt(6)
	v_fmac_f32_e32 v30, s58, v148
	v_fmac_f32_e32 v31, s58, v149
	v_fmac_f32_e32 v32, s58, v150
	v_fmac_f32_e32 v33, s58, v151
	v_add_f32_e32 v196, v196, v30
	v_fmac_f32_e32 v197, v30, v30
	v_add_f32_e32 v130, v130, v31
	v_fmac_f32_e32 v142, v31, v31
	v_add_f32_e32 v196, v196, v32
	v_fmac_f32_e32 v197, v32, v32
	v_add_f32_e32 v130, v130, v33
	v_fmac_f32_e32 v142, v33, v33
	s_waitcnt lgkmcnt(5)
	v_fmac_f32_e32 v26, s58, v152
	v_fmac_f32_e32 v27, s58, v153
	v_fmac_f32_e32 v28, s58, v154
	v_fmac_f32_e32 v29, s58, v155
	v_add_f32_e32 v196, v196, v26
	v_fmac_f32_e32 v197, v26, v26
	v_add_f32_e32 v130, v130, v27
	v_fmac_f32_e32 v142, v27, v27
	v_add_f32_e32 v196, v196, v28
	v_fmac_f32_e32 v197, v28, v28
	v_add_f32_e32 v130, v130, v29
	v_fmac_f32_e32 v142, v29, v29
	s_waitcnt lgkmcnt(4)
	v_fmac_f32_e32 v22, s58, v156
	v_fmac_f32_e32 v23, s58, v157
	v_fmac_f32_e32 v24, s58, v158
	v_fmac_f32_e32 v25, s58, v159
	v_add_f32_e32 v196, v196, v22
	v_fmac_f32_e32 v197, v22, v22
	v_add_f32_e32 v130, v130, v23
	v_fmac_f32_e32 v142, v23, v23
	v_add_f32_e32 v196, v196, v24
	v_fmac_f32_e32 v197, v24, v24
	v_add_f32_e32 v130, v130, v25
	v_fmac_f32_e32 v142, v25, v25
	s_waitcnt lgkmcnt(3)
	v_fmac_f32_e32 v18, s58, v160
	v_fmac_f32_e32 v19, s58, v161
	v_fmac_f32_e32 v20, s58, v162
	v_fmac_f32_e32 v21, s58, v163
	v_add_f32_e32 v196, v196, v18
	v_fmac_f32_e32 v197, v18, v18
	v_add_f32_e32 v130, v130, v19
	v_fmac_f32_e32 v142, v19, v19
	v_add_f32_e32 v196, v196, v20
	v_fmac_f32_e32 v197, v20, v20
	v_add_f32_e32 v130, v130, v21
	v_fmac_f32_e32 v142, v21, v21
	s_waitcnt lgkmcnt(2)
	v_fmac_f32_e32 v14, s58, v164
	v_fmac_f32_e32 v15, s58, v165
	v_fmac_f32_e32 v16, s58, v166
	v_fmac_f32_e32 v17, s58, v167
	v_add_f32_e32 v196, v196, v14
	v_fmac_f32_e32 v197, v14, v14
	v_add_f32_e32 v130, v130, v15
	v_fmac_f32_e32 v142, v15, v15
	v_add_f32_e32 v196, v196, v16
	v_fmac_f32_e32 v197, v16, v16
	v_add_f32_e32 v130, v130, v17
	v_fmac_f32_e32 v142, v17, v17
	s_waitcnt lgkmcnt(1)
	v_fmac_f32_e32 v10, s58, v168
	v_fmac_f32_e32 v11, s58, v169
	v_fmac_f32_e32 v12, s58, v170
	v_fmac_f32_e32 v13, s58, v171
	v_add_f32_e32 v196, v196, v10
	v_fmac_f32_e32 v197, v10, v10
	v_add_f32_e32 v130, v130, v11
	v_fmac_f32_e32 v142, v11, v11
	v_add_f32_e32 v196, v196, v12
	v_fmac_f32_e32 v197, v12, v12
	v_add_f32_e32 v130, v130, v13
	v_fmac_f32_e32 v142, v13, v13
	s_waitcnt lgkmcnt(0)
	v_fmac_f32_e32 v6, s58, v172
	v_fmac_f32_e32 v7, s58, v173
	v_fmac_f32_e32 v8, s58, v174
	v_fmac_f32_e32 v9, s58, v175
	v_add_f32_e32 v196, v196, v6
	v_fmac_f32_e32 v197, v6, v6
	v_add_f32_e32 v130, v130, v7
	v_fmac_f32_e32 v142, v7, v7
	v_add_f32_e32 v196, v196, v8
	v_fmac_f32_e32 v197, v8, v8
	v_add_f32_e32 v130, v130, v9
	v_fmac_f32_e32 v142, v9, v9
	v_add_f32_e32 v196, v196, v130
	v_add_f32_e32 v197, v197, v142
	v_mov_b32_e32 v198, v196
	v_mov_b32_e32 v199, v197
	s_nop 1
	v_permlane16_swap_b32 v198, v196
	v_permlane16_swap_b32 v199, v197
	v_add_f32_e32 v196, v196, v198
	v_add_f32_e32 v197, v197, v199
	v_mov_b32_e32 v198, v196
	v_mov_b32_e32 v199, v197
	s_nop 1
	v_permlane32_swap_b32 v198, v196
	v_permlane32_swap_b32 v199, v197
	v_add_f32_e32 v196, v196, v198
	v_add_f32_e32 v197, v197, v199
	s_mov_b64 exec, 0xffff
	ds_write_b64 v134, v[196:197]
	s_mov_b64 exec, -1
	s_waitcnt lgkmcnt(0)
	s_barrier
	ds_read_b128 v[160:163], v135 offset:0
	ds_read_b128 v[164:167], v135 offset:16
	ds_read_b128 v[168:171], v135 offset:32
	ds_read_b128 v[172:175], v135 offset:48
	s_waitcnt lgkmcnt(0)
	v_add_f32_e32 v160, v160, v162
	v_add_f32_e32 v161, v161, v163
	v_add_f32_e32 v164, v164, v166
	v_add_f32_e32 v165, v165, v167
	v_add_f32_e32 v168, v168, v170
	v_add_f32_e32 v169, v169, v171
	v_add_f32_e32 v172, v172, v174
	v_add_f32_e32 v173, v173, v175
	v_add_f32_e32 v160, v160, v164
	v_add_f32_e32 v161, v161, v165
	v_add_f32_e32 v168, v168, v172
	v_add_f32_e32 v169, v169, v173
	v_add_f32_e32 v160, v160, v168
	v_add_f32_e32 v161, v161, v169
	v_mul_f32_e32 v192, 0x3a800000, v160
	v_mul_f32_e32 v193, 0x3a800000, v161
	v_fma_f32 v193, -v192, v192, v193
	v_add_f32_e32 v193, 0x3727c5ac, v193
	v_rsq_f32_e32 v193, v193
	s_nop 0
	s_add_u32 s94, s78, 0x800
	s_addc_u32 s95, s79, 0
	ds_read_b128 v[176:179], v136
	ds_read_b128 v[180:183], v136 offset:4096
	ds_read_b128 v[184:187], v136 offset:64
	ds_read_b128 v[188:191], v136 offset:4160
	s_waitcnt lgkmcnt(2)
	v_sub_f32_e32 v34, v34, v192
	v_mul_f32_e32 v34, v34, v193
	v_fma_f32 v34, v176, v34, v180
	v_sub_f32_e32 v35, v35, v192
	v_mul_f32_e32 v35, v35, v193
	v_fma_f32 v35, v177, v35, v181
	v_sub_f32_e32 v36, v36, v192
	v_mul_f32_e32 v36, v36, v193
	v_fma_f32 v36, v178, v36, v182
	v_sub_f32_e32 v37, v37, v192
	v_mul_f32_e32 v37, v37, v193
	v_fma_f32 v37, v179, v37, v183
	v_cvt_pk_bf16_f32 v144, v34, v35
	v_cvt_pk_bf16_f32 v145, v36, v37
	ds_read_b128 v[176:179], v136 offset:128
	ds_read_b128 v[180:183], v136 offset:4224
	s_waitcnt lgkmcnt(2)
; DI unsigned pk2(float lo, float hi) { const f32x2 v = {lo, hi}; const bf16x2_t b = __builtin_convertvector(v, bf16x2_t); return __builtin_bit_cast(unsigned, b); }
; DI void unit_O(const Params& p, char* lds, int l, int tile, int glu_tiles, int tile_b) {
;     ...
; #pragma unroll
;             for (int nt = 0; nt < 8; ++nt) {
;                 const f32x4 g = *(const f32x4*)(gp + nt * 16), bb = *(const f32x4*)(gp + 1024 + nt * 16);
;                 f32x4 o;
; #pragma unroll
;                 for (int i = 0; i < 4; ++i) o[i] = (acc[mt][nt][i] - mu) * rs * g[i] + bb[i];
;                 if (l == 0) *(u32x2*)(brow + (nt >> 1) * 4096 + (nt & 1) * 16) = (u32x2){pk2(o[0], o[1]), pk2(o[2], o[3])};
;                 else *(f32x4*)(orow + nt * 16) = o;
;             }
;         }
	v_sub_f32_e32 v30, v30, v192
	v_mul_f32_e32 v30, v30, v193
	v_fma_f32 v30, v184, v30, v188
	v_sub_f32_e32 v31, v31, v192
	v_mul_f32_e32 v31, v31, v193
	v_fma_f32 v31, v185, v31, v189
	v_sub_f32_e32 v32, v32, v192
	v_mul_f32_e32 v32, v32, v193
	v_fma_f32 v32, v186, v32, v190
	v_sub_f32_e32 v33, v33, v192
	v_mul_f32_e32 v33, v33, v193
	v_fma_f32 v33, v187, v33, v191
	v_cvt_pk_bf16_f32 v146, v30, v31
	v_cvt_pk_bf16_f32 v147, v32, v33
	s_nop 1
	v_permlane16_swap_b32 v144, v146
	v_permlane16_swap_b32 v145, v147
	global_store_dwordx4 v137, v[144:147], s[94:95] sc1
	s_add_u32 s94, s94, 0x2000
	s_addc_u32 s95, s95, 0
	ds_read_b128 v[184:187], v136 offset:192
	ds_read_b128 v[188:191], v136 offset:4288
	s_waitcnt lgkmcnt(2)
	v_sub_f32_e32 v26, v26, v192
	v_mul_f32_e32 v26, v26, v193
	v_fma_f32 v26, v176, v26, v180
	v_sub_f32_e32 v27, v27, v192
	v_mul_f32_e32 v27, v27, v193
	v_fma_f32 v27, v177, v27, v181
	v_sub_f32_e32 v28, v28, v192
	v_mul_f32_e32 v28, v28, v193
	v_fma_f32 v28, v178, v28, v182
	v_sub_f32_e32 v29, v29, v192
	v_mul_f32_e32 v29, v29, v193
	v_fma_f32 v29, v179, v29, v183
	v_cvt_pk_bf16_f32 v152, v26, v27
	v_cvt_pk_bf16_f32 v153, v28, v29
	ds_read_b128 v[176:179], v136 offset:256
	ds_read_b128 v[180:183], v136 offset:4352
	s_waitcnt lgkmcnt(2)
	v_sub_f32_e32 v22, v22, v192
	v_mul_f32_e32 v22, v22, v193
	v_fma_f32 v22, v184, v22, v188
	v_sub_f32_e32 v23, v23, v192
	v_mul_f32_e32 v23, v23, v193
	v_fma_f32 v23, v185, v23, v189
	v_sub_f32_e32 v24, v24, v192
	v_mul_f32_e32 v24, v24, v193
	v_fma_f32 v24, v186, v24, v190
	v_sub_f32_e32 v25, v25, v192
	v_mul_f32_e32 v25, v25, v193
	v_fma_f32 v25, v187, v25, v191
	v_cvt_pk_bf16_f32 v154, v22, v23
	v_cvt_pk_bf16_f32 v155, v24, v25
	s_nop 1
	v_permlane16_swap_b32 v152, v154
	v_permlane16_swap_b32 v153, v155
	global_store_dwordx4 v137, v[152:155], s[94:95] sc1
	s_add_u32 s94, s94, 0x2000
	s_addc_u32 s95, s95, 0
	ds_read_b128 v[184:187], v136 offset:320
	ds_read_b128 v[188:191], v136 offset:4416
	s_waitcnt lgkmcnt(2)
	v_sub_f32_e32 v18, v18, v192
	v_mul_f32_e32 v18, v18, v193
	v_fma_f32 v18, v176, v18, v180
	v_sub_f32_e32 v19, v19, v192
	v_mul_f32_e32 v19, v19, v193
	v_fma_f32 v19, v177, v19, v181
	v_sub_f32_e32 v20, v20, v192
	v_mul_f32_e32 v20, v20, v193
	v_fma_f32 v20, v178, v20, v182
	v_sub_f32_e32 v21, v21, v192
	v_mul_f32_e32 v21, v21, v193
	v_fma_f32 v21, v179, v21, v183
	v_cvt_pk_bf16_f32 v144, v18, v19
	v_cvt_pk_bf16_f32 v145, v20, v21
	ds_read_b128 v[176:179], v136 offset:384
	ds_read_b128 v[180:183], v136 offset:4480
	s_waitcnt lgkmcnt(2)
	v_sub_f32_e32 v14, v14, v192
	v_mul_f32_e32 v14, v14, v193
	v_fma_f32 v14, v184, v14, v188
	v_sub_f32_e32 v15, v15, v192
	v_mul_f32_e32 v15, v15, v193
	v_fma_f32 v15, v185, v15, v189
	v_sub_f32_e32 v16, v16, v192
	v_mul_f32_e32 v16, v16, v193
	v_fma_f32 v16, v186, v16, v190
	v_sub_f32_e32 v17, v17, v192
	v_mul_f32_e32 v17, v17, v193
	v_fma_f32 v17, v187, v17, v191
	v_cvt_pk_bf16_f32 v146, v14, v15
	v_cvt_pk_bf16_f32 v147, v16, v17
	s_nop 1
	v_permlane16_swap_b32 v144, v146
	v_permlane16_swap_b32 v145, v147
	global_store_dwordx4 v137, v[144:147], s[94:95] sc1
	s_add_u32 s94, s94, 0x2000
	s_addc_u32 s95, s95, 0
	ds_read_b128 v[184:187], v136 offset:448
	ds_read_b128 v[188:191], v136 offset:4544
	s_waitcnt lgkmcnt(2)
	v_sub_f32_e32 v10, v10, v192
	v_mul_f32_e32 v10, v10, v193
	v_fma_f32 v10, v176, v10, v180
	v_sub_f32_e32 v11, v11, v192
	v_mul_f32_e32 v11, v11, v193
	v_fma_f32 v11, v177, v11, v181
	v_sub_f32_e32 v12, v12, v192
	v_mul_f32_e32 v12, v12, v193
	v_fma_f32 v12, v178, v12, v182
	v_sub_f32_e32 v13, v13, v192
	v_mul_f32_e32 v13, v13, v193
	v_fma_f32 v13, v179, v13, v183
	v_cvt_pk_bf16_f32 v152, v10, v11
	v_cvt_pk_bf16_f32 v153, v12, v13
	s_waitcnt lgkmcnt(0)
	v_sub_f32_e32 v6, v6, v192
	v_mul_f32_e32 v6, v6, v193
	v_fma_f32 v6, v184, v6, v188
	v_sub_f32_e32 v7, v7, v192
	v_mul_f32_e32 v7, v7, v193
	v_fma_f32 v7, v185, v7, v189
	v_sub_f32_e32 v8, v8, v192
	v_mul_f32_e32 v8, v8, v193
	v_fma_f32 v8, v186, v8, v190
	v_sub_f32_e32 v9, v9, v192
	v_mul_f32_e32 v9, v9, v193
	v_fma_f32 v9, v187, v9, v191
	v_cvt_pk_bf16_f32 v154, v6, v7
	v_cvt_pk_bf16_f32 v155, v8, v9
	s_nop 1
	v_permlane16_swap_b32 v152, v154
	v_permlane16_swap_b32 v153, v155
	global_store_dwordx4 v137, v[152:155], s[94:95] sc1
	s_waitcnt vmcnt(8) lgkmcnt(0)
	s_barrier
; DI void unit_O(const Params& p, char* lds, int l, int tile, int glu_tiles, int tile_b) {
;     ...
;         float s2[2], ss2[2];
; #pragma unroll
;         for (int mh = 0; mh < 2; ++mh) {
;             const int mt = half * 2 + mh, rl = mh * 16 + l15;
;             float s = 0.f, ss = 0.f;
; #pragma unroll
;             for (int nt = 0; nt < 8; ++nt) {
;                 f32x4 xr;
;                 if (l == 0) {
;                     const int chunk = wid * 32 + nt * 4 + quad;
;                     xr = *(const f32x4*)(XR + rl * 4096 + ((chunk ^ l15) << 4));
;                 } else {
;                     const u32x2 hb = *(const u32x2*)(XR + ((wid * 4 + (nt >> 1)) * 32 + rl) * 64 + (nt & 1) * 32 + quad * 8);
;                     xr = (f32x4){bf2f(hb[0] & 0xffffu), bf2f(hb[0] >> 16), bf2f(hb[1] & 0xffffu), bf2f(hb[1] >> 16)};
;                 }
; #pragma unroll
;                 for (int i = 0; i < 4; ++i) { const float v = acc[mt][nt][i] + DN_ALPHA * xr[i]; acc[mt][nt][i] = v; s += v; ss += v * v; }
;             }
;             s2[mh] = s; ss2[mh] = ss;
;         }
; #pragma unroll
;         for (int mh = 0; mh < 2; ++mh) { s2[mh] += __shfl_xor(s2[mh], 16); ss2[mh] += __shfl_xor(ss2[mh], 16); }
; #pragma unroll
;         for (int mh = 0; mh < 2; ++mh) { s2[mh] += __shfl_xor(s2[mh], 32); ss2[mh] += __shfl_xor(ss2[mh], 32); }
;         if (quad == 0) {
; #pragma unroll
;             for (int mh = 0; mh < 2; ++mh) *(f32x2*)&red[((mh * 16 + l15) * 8 + wid) * 2] = (f32x2){s2[mh], ss2[mh]};
;         }
;         __syncthreads();
;         if (half == 0) issue_x(1);
; #pragma unroll
;         for (int mh = 0; mh < 2; ++mh) {
;             const int mt = half * 2 + mh, rl = mh * 16 + l15, row = mt * 16 + l15;
;             float s = 0.f, ss = 0.f;
; #pragma unroll
;             for (int w = 0; w < 4; ++w) { const f32x4 v = *(const f32x4*)&red[rl * 16 + 4 * w]; s += v[0] + v[2]; ss += v[1] + v[3]; }
;             const float mu = s * (1.f / 1024.f);
;             const float var = ss * (1.f / 1024.f) - mu * mu;
;             const float rs = rsqrtf(var + LN_EPS);
;             float* orow = xo + (r0 + row) * 1024 + wid * 128 + quad * 4;
;             bf16_t* brow = xbo + xb_off((int)r0 + row, wid * 128) + quad * 4;
;             const float* gp = GB + wid * 128 + quad * 4;
; #pragma unroll
;             for (int nt = 0; nt < 8; ++nt) {
	ds_read_b128 v[144:147], v204
	ds_read_b128 v[148:151], v205
	ds_read_b128 v[152:155], v206
	ds_read_b128 v[156:159], v207
	ds_read_b128 v[160:163], v204 offset:256
	ds_read_b128 v[164:167], v205 offset:256
	ds_read_b128 v[168:171], v206 offset:256
	ds_read_b128 v[172:175], v207 offset:256
	s_waitcnt lgkmcnt(7)
	v_fmac_f32_e32 v62, s58, v144
	v_fmac_f32_e32 v63, s58, v145
	v_fmac_f32_e32 v64, s58, v146
	v_fmac_f32_e32 v65, s58, v147
	v_mov_b32_e32 v196, v62
	v_mul_f32_e32 v197, v62, v62
	v_mov_b32_e32 v130, v63
	v_mul_f32_e32 v142, v63, v63
	v_add_f32_e32 v196, v196, v64
	v_fmac_f32_e32 v197, v64, v64
	v_add_f32_e32 v130, v130, v65
	v_fmac_f32_e32 v142, v65, v65
	s_waitcnt lgkmcnt(6)
	v_fmac_f32_e32 v58, s58, v148
	v_fmac_f32_e32 v59, s58, v149
	v_fmac_f32_e32 v60, s58, v150
	v_fmac_f32_e32 v61, s58, v151
	v_add_f32_e32 v196, v196, v58
	v_fmac_f32_e32 v197, v58, v58
	v_add_f32_e32 v130, v130, v59
	v_fmac_f32_e32 v142, v59, v59
	v_add_f32_e32 v196, v196, v60
	v_fmac_f32_e32 v197, v60, v60
	v_add_f32_e32 v130, v130, v61
	v_fmac_f32_e32 v142, v61, v61
	s_waitcnt lgkmcnt(5)
	v_fmac_f32_e32 v54, s58, v152
	v_fmac_f32_e32 v55, s58, v153
	v_fmac_f32_e32 v56, s58, v154
	v_fmac_f32_e32 v57, s58, v155
	v_add_f32_e32 v196, v196, v54
	v_fmac_f32_e32 v197, v54, v54
	v_add_f32_e32 v130, v130, v55
	v_fmac_f32_e32 v142, v55, v55
	v_add_f32_e32 v196, v196, v56
	v_fmac_f32_e32 v197, v56, v56
	v_add_f32_e32 v130, v130, v57
	v_fmac_f32_e32 v142, v57, v57
	s_waitcnt lgkmcnt(4)
	v_fmac_f32_e32 v50, s58, v156
	v_fmac_f32_e32 v51, s58, v157
	v_fmac_f32_e32 v52, s58, v158
	v_fmac_f32_e32 v53, s58, v159
	v_add_f32_e32 v196, v196, v50
	v_fmac_f32_e32 v197, v50, v50
	v_add_f32_e32 v130, v130, v51
	v_fmac_f32_e32 v142, v51, v51
	v_add_f32_e32 v196, v196, v52
	v_fmac_f32_e32 v197, v52, v52
	v_add_f32_e32 v130, v130, v53
	v_fmac_f32_e32 v142, v53, v53
	s_waitcnt lgkmcnt(3)
	v_fmac_f32_e32 v46, s58, v160
	v_fmac_f32_e32 v47, s58, v161
	v_fmac_f32_e32 v48, s58, v162
	v_fmac_f32_e32 v49, s58, v163
	v_add_f32_e32 v196, v196, v46
	v_fmac_f32_e32 v197, v46, v46
	v_add_f32_e32 v130, v130, v47
	v_fmac_f32_e32 v142, v47, v47
	v_add_f32_e32 v196, v196, v48
	v_fmac_f32_e32 v197, v48, v48
	v_add_f32_e32 v130, v130, v49
	v_fmac_f32_e32 v142, v49, v49
	s_waitcnt lgkmcnt(2)
	v_fmac_f32_e32 v42, s58, v164
	v_fmac_f32_e32 v43, s58, v165
	v_fmac_f32_e32 v44, s58, v166
	v_fmac_f32_e32 v45, s58, v167
	v_add_f32_e32 v196, v196, v42
	v_fmac_f32_e32 v197, v42, v42
	v_add_f32_e32 v130, v130, v43
	v_fmac_f32_e32 v142, v43, v43
	v_add_f32_e32 v196, v196, v44
	v_fmac_f32_e32 v197, v44, v44
	v_add_f32_e32 v130, v130, v45
	v_fmac_f32_e32 v142, v45, v45
	s_waitcnt lgkmcnt(1)
	v_fmac_f32_e32 v38, s58, v168
	v_fmac_f32_e32 v39, s58, v169
	v_fmac_f32_e32 v40, s58, v170
	v_fmac_f32_e32 v41, s58, v171
	v_add_f32_e32 v196, v196, v38
	v_fmac_f32_e32 v197, v38, v38
	v_add_f32_e32 v130, v130, v39
	v_fmac_f32_e32 v142, v39, v39
	v_add_f32_e32 v196, v196, v40
	v_fmac_f32_e32 v197, v40, v40
	v_add_f32_e32 v130, v130, v41
	v_fmac_f32_e32 v142, v41, v41
	s_waitcnt lgkmcnt(0)
	v_fmac_f32_e32 v2, s58, v172
	v_fmac_f32_e32 v3, s58, v173
	v_fmac_f32_e32 v4, s58, v174
	v_fmac_f32_e32 v5, s58, v175
	v_add_f32_e32 v196, v196, v2
	v_fmac_f32_e32 v197, v2, v2
	v_add_f32_e32 v130, v130, v3
	v_fmac_f32_e32 v142, v3, v3
	v_add_f32_e32 v196, v196, v4
	v_fmac_f32_e32 v197, v4, v4
	v_add_f32_e32 v130, v130, v5
	v_fmac_f32_e32 v142, v5, v5
	v_add_f32_e32 v196, v196, v130
	v_add_f32_e32 v197, v197, v142
	v_mov_b32_e32 v198, v196
	v_mov_b32_e32 v199, v197
	s_nop 1
	v_permlane16_swap_b32 v198, v196
	v_permlane16_swap_b32 v199, v197
	v_add_f32_e32 v196, v196, v198
	v_add_f32_e32 v197, v197, v199
	v_mov_b32_e32 v198, v196
	v_mov_b32_e32 v199, v197
	s_nop 1
	v_permlane32_swap_b32 v198, v196
	v_permlane32_swap_b32 v199, v197
	v_add_f32_e32 v196, v196, v198
	v_add_f32_e32 v197, v197, v199
	s_mov_b64 exec, 0xffff
	ds_write_b64 v134, v[196:197]
	s_mov_b64 exec, -1
	s_waitcnt lgkmcnt(0)
	s_barrier
	ds_read_b128 v[160:163], v135 offset:0
	ds_read_b128 v[164:167], v135 offset:16
	ds_read_b128 v[168:171], v135 offset:32
	ds_read_b128 v[172:175], v135 offset:48
	s_waitcnt lgkmcnt(0)
	v_add_f32_e32 v160, v160, v162
	v_add_f32_e32 v161, v161, v163
	v_add_f32_e32 v164, v164, v166
	v_add_f32_e32 v165, v165, v167
	v_add_f32_e32 v168, v168, v170
	v_add_f32_e32 v169, v169, v171
	v_add_f32_e32 v172, v172, v174
	v_add_f32_e32 v173, v173, v175
	v_add_f32_e32 v160, v160, v164
	v_add_f32_e32 v161, v161, v165
	v_add_f32_e32 v168, v168, v172
	v_add_f32_e32 v169, v169, v173
	v_add_f32_e32 v160, v160, v168
	v_add_f32_e32 v161, v161, v169
	v_mul_f32_e32 v192, 0x3a800000, v160
	v_mul_f32_e32 v193, 0x3a800000, v161
	v_fma_f32 v193, -v192, v192, v193
	v_add_f32_e32 v193, 0x3727c5ac, v193
	v_rsq_f32_e32 v193, v193
	s_nop 0
	s_add_u32 s94, s78, 0xc00
	s_addc_u32 s95, s79, 0
	ds_read_b128 v[176:179], v136
	ds_read_b128 v[180:183], v136 offset:4096
	ds_read_b128 v[184:187], v136 offset:64
	ds_read_b128 v[188:191], v136 offset:4160
	s_waitcnt lgkmcnt(2)
	v_sub_f32_e32 v62, v62, v192
	v_mul_f32_e32 v62, v62, v193
	v_fma_f32 v62, v176, v62, v180
	v_sub_f32_e32 v63, v63, v192
	v_mul_f32_e32 v63, v63, v193
	v_fma_f32 v63, v177, v63, v181
	v_sub_f32_e32 v64, v64, v192
	v_mul_f32_e32 v64, v64, v193
	v_fma_f32 v64, v178, v64, v182
	v_sub_f32_e32 v65, v65, v192
	v_mul_f32_e32 v65, v65, v193
	v_fma_f32 v65, v179, v65, v183
	v_cvt_pk_bf16_f32 v144, v62, v63
	v_cvt_pk_bf16_f32 v145, v64, v65
	ds_read_b128 v[176:179], v136 offset:128
	ds_read_b128 v[180:183], v136 offset:4224
	s_waitcnt lgkmcnt(2)
; DI unsigned pk2(float lo, float hi) { const f32x2 v = {lo, hi}; const bf16x2_t b = __builtin_convertvector(v, bf16x2_t); return __builtin_bit_cast(unsigned, b); }
; DI void unit_O(const Params& p, char* lds, int l, int tile, int glu_tiles, int tile_b) {
;     ...
; #pragma unroll
;             for (int nt = 0; nt < 8; ++nt) {
;                 const f32x4 g = *(const f32x4*)(gp + nt * 16), bb = *(const f32x4*)(gp + 1024 + nt * 16);
;                 f32x4 o;
; #pragma unroll
;                 for (int i = 0; i < 4; ++i) o[i] = (acc[mt][nt][i] - mu) * rs * g[i] + bb[i];
;                 if (l == 0) *(u32x2*)(brow + (nt >> 1) * 4096 + (nt & 1) * 16) = (u32x2){pk2(o[0], o[1]), pk2(o[2], o[3])};
;                 else *(f32x4*)(orow + nt * 16) = o;
;             }
;         }
	v_sub_f32_e32 v58, v58, v192
	v_mul_f32_e32 v58, v58, v193
	v_fma_f32 v58, v184, v58, v188
	v_sub_f32_e32 v59, v59, v192
	v_mul_f32_e32 v59, v59, v193
	v_fma_f32 v59, v185, v59, v189
	v_sub_f32_e32 v60, v60, v192
	v_mul_f32_e32 v60, v60, v193
	v_fma_f32 v60, v186, v60, v190
	v_sub_f32_e32 v61, v61, v192
	v_mul_f32_e32 v61, v61, v193
	v_fma_f32 v61, v187, v61, v191
	v_cvt_pk_bf16_f32 v146, v58, v59
	v_cvt_pk_bf16_f32 v147, v60, v61
	s_nop 1
	v_permlane16_swap_b32 v144, v146
	v_permlane16_swap_b32 v145, v147
	global_store_dwordx4 v137, v[144:147], s[94:95] sc1
	s_add_u32 s94, s94, 0x2000
	s_addc_u32 s95, s95, 0
	ds_read_b128 v[184:187], v136 offset:192
	ds_read_b128 v[188:191], v136 offset:4288
	s_waitcnt lgkmcnt(2)
	v_sub_f32_e32 v54, v54, v192
	v_mul_f32_e32 v54, v54, v193
	v_fma_f32 v54, v176, v54, v180
	v_sub_f32_e32 v55, v55, v192
	v_mul_f32_e32 v55, v55, v193
	v_fma_f32 v55, v177, v55, v181
	v_sub_f32_e32 v56, v56, v192
	v_mul_f32_e32 v56, v56, v193
	v_fma_f32 v56, v178, v56, v182
	v_sub_f32_e32 v57, v57, v192
	v_mul_f32_e32 v57, v57, v193
	v_fma_f32 v57, v179, v57, v183
	v_cvt_pk_bf16_f32 v152, v54, v55
	v_cvt_pk_bf16_f32 v153, v56, v57
	ds_read_b128 v[176:179], v136 offset:256
	ds_read_b128 v[180:183], v136 offset:4352
	s_waitcnt lgkmcnt(2)
	v_sub_f32_e32 v50, v50, v192
	v_mul_f32_e32 v50, v50, v193
	v_fma_f32 v50, v184, v50, v188
	v_sub_f32_e32 v51, v51, v192
	v_mul_f32_e32 v51, v51, v193
	v_fma_f32 v51, v185, v51, v189
	v_sub_f32_e32 v52, v52, v192
	v_mul_f32_e32 v52, v52, v193
	v_fma_f32 v52, v186, v52, v190
	v_sub_f32_e32 v53, v53, v192
	v_mul_f32_e32 v53, v53, v193
	v_fma_f32 v53, v187, v53, v191
	v_cvt_pk_bf16_f32 v154, v50, v51
	v_cvt_pk_bf16_f32 v155, v52, v53
	s_nop 1
	v_permlane16_swap_b32 v152, v154
	v_permlane16_swap_b32 v153, v155
	global_store_dwordx4 v137, v[152:155], s[94:95] sc1
	s_add_u32 s94, s94, 0x2000
	s_addc_u32 s95, s95, 0
	ds_read_b128 v[184:187], v136 offset:320
	ds_read_b128 v[188:191], v136 offset:4416
	s_waitcnt lgkmcnt(2)
	v_sub_f32_e32 v46, v46, v192
	v_mul_f32_e32 v46, v46, v193
	v_fma_f32 v46, v176, v46, v180
	v_sub_f32_e32 v47, v47, v192
	v_mul_f32_e32 v47, v47, v193
	v_fma_f32 v47, v177, v47, v181
	v_sub_f32_e32 v48, v48, v192
	v_mul_f32_e32 v48, v48, v193
	v_fma_f32 v48, v178, v48, v182
	v_sub_f32_e32 v49, v49, v192
	v_mul_f32_e32 v49, v49, v193
	v_fma_f32 v49, v179, v49, v183
	v_cvt_pk_bf16_f32 v144, v46, v47
	v_cvt_pk_bf16_f32 v145, v48, v49
	ds_read_b128 v[176:179], v136 offset:384
	ds_read_b128 v[180:183], v136 offset:4480
	s_waitcnt lgkmcnt(2)
	v_sub_f32_e32 v42, v42, v192
	v_mul_f32_e32 v42, v42, v193
	v_fma_f32 v42, v184, v42, v188
	v_sub_f32_e32 v43, v43, v192
	v_mul_f32_e32 v43, v43, v193
	v_fma_f32 v43, v185, v43, v189
	v_sub_f32_e32 v44, v44, v192
	v_mul_f32_e32 v44, v44, v193
	v_fma_f32 v44, v186, v44, v190
	v_sub_f32_e32 v45, v45, v192
	v_mul_f32_e32 v45, v45, v193
	v_fma_f32 v45, v187, v45, v191
	v_cvt_pk_bf16_f32 v146, v42, v43
	v_cvt_pk_bf16_f32 v147, v44, v45
	s_nop 1
	v_permlane16_swap_b32 v144, v146
	v_permlane16_swap_b32 v145, v147
	global_store_dwordx4 v137, v[144:147], s[94:95] sc1
	s_add_u32 s94, s94, 0x2000
	s_addc_u32 s95, s95, 0
	ds_read_b128 v[184:187], v136 offset:448
	ds_read_b128 v[188:191], v136 offset:4544
	s_waitcnt lgkmcnt(2)
	v_sub_f32_e32 v38, v38, v192
	v_mul_f32_e32 v38, v38, v193
	v_fma_f32 v38, v176, v38, v180
	v_sub_f32_e32 v39, v39, v192
	v_mul_f32_e32 v39, v39, v193
	v_fma_f32 v39, v177, v39, v181
	v_sub_f32_e32 v40, v40, v192
	v_mul_f32_e32 v40, v40, v193
	v_fma_f32 v40, v178, v40, v182
	v_sub_f32_e32 v41, v41, v192
	v_mul_f32_e32 v41, v41, v193
	v_fma_f32 v41, v179, v41, v183
	v_cvt_pk_bf16_f32 v152, v38, v39
	v_cvt_pk_bf16_f32 v153, v40, v41
	s_waitcnt lgkmcnt(0)
	v_sub_f32_e32 v2, v2, v192
	v_mul_f32_e32 v2, v2, v193
	v_fma_f32 v2, v184, v2, v188
	v_sub_f32_e32 v3, v3, v192
	v_mul_f32_e32 v3, v3, v193
	v_fma_f32 v3, v185, v3, v189
	v_sub_f32_e32 v4, v4, v192
	v_mul_f32_e32 v4, v4, v193
	v_fma_f32 v4, v186, v4, v190
	v_sub_f32_e32 v5, v5, v192
	v_mul_f32_e32 v5, v5, v193
	v_fma_f32 v5, v187, v5, v191
	v_cvt_pk_bf16_f32 v154, v2, v3
	v_cvt_pk_bf16_f32 v155, v4, v5
	s_nop 1
	v_permlane16_swap_b32 v152, v154
	v_permlane16_swap_b32 v153, v155
	global_store_dwordx4 v137, v[152:155], s[94:95] sc1
	s_branch .Le1_done
; DI void unit_O(const Params& p, char* lds, int l, int tile, int glu_tiles, int tile_b) {
;     ...
;     auto issue_x = [&](int half) {
;         if (l == 0) {
; #pragma unroll 1
;             for (int i = 0; i < 16; ++i) {
;                 const int pc = (wid * 16 + i + xrot) & 127, row = pc >> 2, phys = (pc & 3) * 64 + lane, logical = phys ^ (row & 15);
;                 __builtin_amdgcn_global_load_lds((const unsigned*)(xres + (r0 + half * 32 + row) * 1024 + logical * 4), (unsigned*)(XR + pc * 1024 + lane * 16), 16, 0, 0);
;             }
;         } else {
; #pragma unroll 1
;             for (int i = 0; i < 8; ++i) {
;                 const int pc = (wid * 8 + i + (xrot >> 1)) & 63, kt = pc >> 1, sub = pc & 1;
;                 __builtin_amdgcn_global_load_lds((const unsigned*)(xbres + ((size_t)kt * 128 + half * 32) * 32 + sub * 512 + lane * 8), (unsigned*)(XR + pc * 1024 + lane * 16), 16, 0, 0);
;             }
;         }
;     ...
;         float s2[2], ss2[2];
; #pragma unroll
;         for (int mh = 0; mh < 2; ++mh) {
;             const int mt = half * 2 + mh, rl = mh * 16 + l15;
;             float s = 0.f, ss = 0.f;
; #pragma unroll
;             for (int nt = 0; nt < 8; ++nt) {
;                 f32x4 xr;
;                 if (l == 0) {
;                     const int chunk = wid * 32 + nt * 4 + quad;
;                     xr = *(const f32x4*)(XR + rl * 4096 + ((chunk ^ l15) << 4));
;                 } else {
;                     const u32x2 hb = *(const u32x2*)(XR + ((wid * 4 + (nt >> 1)) * 32 + rl) * 64 + (nt & 1) * 32 + quad * 8);
;                     xr = (f32x4){bf2f(hb[0] & 0xffffu), bf2f(hb[0] >> 16), bf2f(hb[1] & 0xffffu), bf2f(hb[1] >> 16)};
;                 }
; #pragma unroll
;                 for (int i = 0; i < 4; ++i) { const float v = acc[mt][nt][i] + DN_ALPHA * xr[i]; acc[mt][nt][i] = v; s += v; ss += v * v; }
;             }
;             s2[mh] = s; ss2[mh] = ss;
;         }
; #pragma unroll
;         for (int mh = 0; mh < 2; ++mh) { s2[mh] += __shfl_xor(s2[mh], 16); ss2[mh] += __shfl_xor(ss2[mh], 16); }
; #pragma unroll
;         for (int mh = 0; mh < 2; ++mh) { s2[mh] += __shfl_xor(s2[mh], 32); ss2[mh] += __shfl_xor(ss2[mh], 32); }
;         if (quad == 0) {
; #pragma unroll
;             for (int mh = 0; mh < 2; ++mh) *(f32x2*)&red[((mh * 16 + l15) * 8 + wid) * 2] = (f32x2){s2[mh], ss2[mh]};
;         }
.Le1_l1:
	v_lshlrev_b32_e32 v133, 12, v140
	v_lshl_add_u32 v133, v138, 6, v133
	v_lshl_add_u32 v133, v139, 3, v133
	v_lshlrev_b32_e32 v137, 12, v138
	v_lshl_add_u32 v137, v140, 9, v137
	v_lshl_add_u32 v137, v139, 4, v137
	s_lshl_b32 s40, s34, 18
	s_add_u32 s78, s16, s40
	s_addc_u32 s79, s17, 0
	s_add_u32 s92, s96, 0x400
	s_addc_u32 s93, s97, 0
	s_add_u32 s40, s91, 0x8000
	s_mov_b32 m0, s40
	s_nop 0
	global_load_lds_dwordx4 v208, s[92:93]
	s_add_u32 s92, s92, 0x2000
	s_addc_u32 s93, s93, 0
	s_add_u32 m0, m0, 0x400
	s_nop 0
	global_load_lds_dwordx4 v208, s[92:93]
	s_add_u32 s92, s92, 0x2000
	s_addc_u32 s93, s93, 0
	s_add_u32 m0, m0, 0x400
	s_nop 0
	global_load_lds_dwordx4 v208, s[92:93]
	s_add_u32 s92, s92, 0x2000
	s_addc_u32 s93, s93, 0
	s_add_u32 m0, m0, 0x400
	s_nop 0
	global_load_lds_dwordx4 v208, s[92:93]
	s_waitcnt vmcnt(4)
	ds_write_b128 v143, v[176:179]
	s_waitcnt vmcnt(4) lgkmcnt(0)
	s_barrier
	ds_read_b64 v[180:181], v133 offset:0
	ds_read_b64 v[182:183], v133 offset:32
	ds_read_b64 v[184:185], v133 offset:1024
	ds_read_b64 v[186:187], v133 offset:1056
	ds_read_b64 v[188:189], v133 offset:2048
	ds_read_b64 v[190:191], v133 offset:2080
	ds_read_b64 v[192:193], v133 offset:3072
	ds_read_b64 v[194:195], v133 offset:3104
	s_waitcnt lgkmcnt(7)
	v_lshlrev_b32_e32 v144, 16, v180
	v_and_b32_e32 v145, 0xffff0000, v180
	v_lshlrev_b32_e32 v146, 16, v181
	v_and_b32_e32 v147, 0xffff0000, v181
	v_fmac_f32_e32 v98, s58, v144
	v_fmac_f32_e32 v99, s58, v145
	v_fmac_f32_e32 v100, s58, v146
	v_fmac_f32_e32 v101, s58, v147
	v_mov_b32_e32 v196, v98
	v_mul_f32_e32 v197, v98, v98
	v_mov_b32_e32 v130, v99
	v_mul_f32_e32 v142, v99, v99
	v_add_f32_e32 v196, v196, v100
	v_fmac_f32_e32 v197, v100, v100
	v_add_f32_e32 v130, v130, v101
	v_fmac_f32_e32 v142, v101, v101
	s_waitcnt lgkmcnt(6)
	v_lshlrev_b32_e32 v148, 16, v182
	v_and_b32_e32 v149, 0xffff0000, v182
	v_lshlrev_b32_e32 v150, 16, v183
	v_and_b32_e32 v151, 0xffff0000, v183
	v_fmac_f32_e32 v94, s58, v148
	v_fmac_f32_e32 v95, s58, v149
	v_fmac_f32_e32 v96, s58, v150
	v_fmac_f32_e32 v97, s58, v151
	v_add_f32_e32 v196, v196, v94
	v_fmac_f32_e32 v197, v94, v94
	v_add_f32_e32 v130, v130, v95
	v_fmac_f32_e32 v142, v95, v95
	v_add_f32_e32 v196, v196, v96
	v_fmac_f32_e32 v197, v96, v96
	v_add_f32_e32 v130, v130, v97
	v_fmac_f32_e32 v142, v97, v97
	s_waitcnt lgkmcnt(5)
	v_lshlrev_b32_e32 v152, 16, v184
	v_and_b32_e32 v153, 0xffff0000, v184
	v_lshlrev_b32_e32 v154, 16, v185
	v_and_b32_e32 v155, 0xffff0000, v185
	v_fmac_f32_e32 v90, s58, v152
	v_fmac_f32_e32 v91, s58, v153
	v_fmac_f32_e32 v92, s58, v154
	v_fmac_f32_e32 v93, s58, v155
	v_add_f32_e32 v196, v196, v90
	v_fmac_f32_e32 v197, v90, v90
	v_add_f32_e32 v130, v130, v91
	v_fmac_f32_e32 v142, v91, v91
	v_add_f32_e32 v196, v196, v92
	v_fmac_f32_e32 v197, v92, v92
	v_add_f32_e32 v130, v130, v93
	v_fmac_f32_e32 v142, v93, v93
	s_waitcnt lgkmcnt(4)
	v_lshlrev_b32_e32 v156, 16, v186
	v_and_b32_e32 v157, 0xffff0000, v186
	v_lshlrev_b32_e32 v158, 16, v187
	v_and_b32_e32 v159, 0xffff0000, v187
	v_fmac_f32_e32 v86, s58, v156
	v_fmac_f32_e32 v87, s58, v157
	v_fmac_f32_e32 v88, s58, v158
	v_fmac_f32_e32 v89, s58, v159
	v_add_f32_e32 v196, v196, v86
	v_fmac_f32_e32 v197, v86, v86
	v_add_f32_e32 v130, v130, v87
	v_fmac_f32_e32 v142, v87, v87
	v_add_f32_e32 v196, v196, v88
	v_fmac_f32_e32 v197, v88, v88
	v_add_f32_e32 v130, v130, v89
	v_fmac_f32_e32 v142, v89, v89
	s_waitcnt lgkmcnt(3)
	v_lshlrev_b32_e32 v160, 16, v188
	v_and_b32_e32 v161, 0xffff0000, v188
	v_lshlrev_b32_e32 v162, 16, v189
	v_and_b32_e32 v163, 0xffff0000, v189
	v_fmac_f32_e32 v82, s58, v160
	v_fmac_f32_e32 v83, s58, v161
	v_fmac_f32_e32 v84, s58, v162
	v_fmac_f32_e32 v85, s58, v163
	v_add_f32_e32 v196, v196, v82
	v_fmac_f32_e32 v197, v82, v82
	v_add_f32_e32 v130, v130, v83
	v_fmac_f32_e32 v142, v83, v83
	v_add_f32_e32 v196, v196, v84
	v_fmac_f32_e32 v197, v84, v84
	v_add_f32_e32 v130, v130, v85
	v_fmac_f32_e32 v142, v85, v85
	s_waitcnt lgkmcnt(2)
	v_lshlrev_b32_e32 v164, 16, v190
	v_and_b32_e32 v165, 0xffff0000, v190
	v_lshlrev_b32_e32 v166, 16, v191
	v_and_b32_e32 v167, 0xffff0000, v191
	v_fmac_f32_e32 v78, s58, v164
	v_fmac_f32_e32 v79, s58, v165
	v_fmac_f32_e32 v80, s58, v166
	v_fmac_f32_e32 v81, s58, v167
	v_add_f32_e32 v196, v196, v78
	v_fmac_f32_e32 v197, v78, v78
	v_add_f32_e32 v130, v130, v79
	v_fmac_f32_e32 v142, v79, v79
	v_add_f32_e32 v196, v196, v80
	v_fmac_f32_e32 v197, v80, v80
	v_add_f32_e32 v130, v130, v81
	v_fmac_f32_e32 v142, v81, v81
	s_waitcnt lgkmcnt(1)
	v_lshlrev_b32_e32 v168, 16, v192
	v_and_b32_e32 v169, 0xffff0000, v192
	v_lshlrev_b32_e32 v170, 16, v193
	v_and_b32_e32 v171, 0xffff0000, v193
	v_fmac_f32_e32 v74, s58, v168
	v_fmac_f32_e32 v75, s58, v169
	v_fmac_f32_e32 v76, s58, v170
	v_fmac_f32_e32 v77, s58, v171
	v_add_f32_e32 v196, v196, v74
	v_fmac_f32_e32 v197, v74, v74
	v_add_f32_e32 v130, v130, v75
	v_fmac_f32_e32 v142, v75, v75
	v_add_f32_e32 v196, v196, v76
	v_fmac_f32_e32 v197, v76, v76
	v_add_f32_e32 v130, v130, v77
	v_fmac_f32_e32 v142, v77, v77
	s_waitcnt lgkmcnt(0)
	v_lshlrev_b32_e32 v172, 16, v194
	v_and_b32_e32 v173, 0xffff0000, v194
	v_lshlrev_b32_e32 v174, 16, v195
	v_and_b32_e32 v175, 0xffff0000, v195
	v_fmac_f32_e32 v70, s58, v172
	v_fmac_f32_e32 v71, s58, v173
	v_fmac_f32_e32 v72, s58, v174
	v_fmac_f32_e32 v73, s58, v175
	v_add_f32_e32 v196, v196, v70
	v_fmac_f32_e32 v197, v70, v70
	v_add_f32_e32 v130, v130, v71
	v_fmac_f32_e32 v142, v71, v71
	v_add_f32_e32 v196, v196, v72
	v_fmac_f32_e32 v197, v72, v72
	v_add_f32_e32 v130, v130, v73
	v_fmac_f32_e32 v142, v73, v73
	v_add_f32_e32 v196, v196, v130
	v_add_f32_e32 v197, v197, v142
	v_mov_b32_e32 v198, v196
	v_mov_b32_e32 v199, v197
	s_nop 1
	v_permlane16_swap_b32 v198, v196
	v_permlane16_swap_b32 v199, v197
	v_add_f32_e32 v196, v196, v198
	v_add_f32_e32 v197, v197, v199
	v_mov_b32_e32 v198, v196
	v_mov_b32_e32 v199, v197
	s_nop 1
	v_permlane32_swap_b32 v198, v196
	v_permlane32_swap_b32 v199, v197
	v_add_f32_e32 v196, v196, v198
	v_add_f32_e32 v197, v197, v199
	s_mov_b64 exec, 0xffff
	ds_write_b64 v134, v[196:197]
	s_mov_b64 exec, -1
	s_waitcnt lgkmcnt(0)
	s_barrier
; DI unsigned pk2(float lo, float hi) { const f32x2 v = {lo, hi}; const bf16x2_t b = __builtin_convertvector(v, bf16x2_t); return __builtin_bit_cast(unsigned, b); }
; DI size_t xb_off(int tok, int col) { return ((size_t)(((tok >> 7) * 32 + (col >> 5)) * 128 + (tok & 127))) * 32 + (col & 31); }
; DI void unit_O(const Params& p, char* lds, int l, int tile, int glu_tiles, int tile_b) {
;     ...
;         if (half == 0) issue_x(1);
; #pragma unroll
;         for (int mh = 0; mh < 2; ++mh) {
;             const int mt = half * 2 + mh, rl = mh * 16 + l15, row = mt * 16 + l15;
;             float s = 0.f, ss = 0.f;
; #pragma unroll
;             for (int w = 0; w < 4; ++w) { const f32x4 v = *(const f32x4*)&red[rl * 16 + 4 * w]; s += v[0] + v[2]; ss += v[1] + v[3]; }
;             const float mu = s * (1.f / 1024.f);
;             const float var = ss * (1.f / 1024.f) - mu * mu;
;             const float rs = rsqrtf(var + LN_EPS);
;             float* orow = xo + (r0 + row) * 1024 + wid * 128 + quad * 4;
;             bf16_t* brow = xbo + xb_off((int)r0 + row, wid * 128) + quad * 4;
;             const float* gp = GB + wid * 128 + quad * 4;
; #pragma unroll
;             for (int nt = 0; nt < 8; ++nt) {
;                 const f32x4 g = *(const f32x4*)(gp + nt * 16), bb = *(const f32x4*)(gp + 1024 + nt * 16);
;                 f32x4 o;
; #pragma unroll
;                 for (int i = 0; i < 4; ++i) o[i] = (acc[mt][nt][i] - mu) * rs * g[i] + bb[i];
;                 if (l == 0) *(u32x2*)(brow + (nt >> 1) * 4096 + (nt & 1) * 16) = (u32x2){pk2(o[0], o[1]), pk2(o[2], o[3])};
;                 else *(f32x4*)(orow + nt * 16) = o;
;             }
;         }
	s_add_u32 s92, s96, 0x800
	s_addc_u32 s93, s97, 0
	s_add_u32 s40, s91, 0x0
	s_mov_b32 m0, s40
	s_nop 0
	global_load_lds_dwordx4 v208, s[92:93]
	s_add_u32 s92, s92, 0x2000
	s_addc_u32 s93, s93, 0
	s_add_u32 m0, m0, 0x400
	s_nop 0
	global_load_lds_dwordx4 v208, s[92:93]
	s_add_u32 s92, s92, 0x2000
	s_addc_u32 s93, s93, 0
	s_add_u32 m0, m0, 0x400
	s_nop 0
	global_load_lds_dwordx4 v208, s[92:93]
	s_add_u32 s92, s92, 0x2000
	s_addc_u32 s93, s93, 0
	s_add_u32 m0, m0, 0x400
	s_nop 0
	global_load_lds_dwordx4 v208, s[92:93]
	ds_read_b128 v[160:163], v135 offset:0
	ds_read_b128 v[164:167], v135 offset:16
	ds_read_b128 v[168:171], v135 offset:32
	ds_read_b128 v[172:175], v135 offset:48
	s_waitcnt lgkmcnt(0)
	v_add_f32_e32 v160, v160, v162
	v_add_f32_e32 v161, v161, v163
	v_add_f32_e32 v164, v164, v166
	v_add_f32_e32 v165, v165, v167
	v_add_f32_e32 v168, v168, v170
	v_add_f32_e32 v169, v169, v171
	v_add_f32_e32 v172, v172, v174
	v_add_f32_e32 v173, v173, v175
	v_add_f32_e32 v160, v160, v164
	v_add_f32_e32 v161, v161, v165
	v_add_f32_e32 v168, v168, v172
	v_add_f32_e32 v169, v169, v173
	v_add_f32_e32 v160, v160, v168
	v_add_f32_e32 v161, v161, v169
	v_mul_f32_e32 v192, 0x3a800000, v160
	v_mul_f32_e32 v193, 0x3a800000, v161
	v_fma_f32 v193, -v192, v192, v193
	v_add_f32_e32 v193, 0x3727c5ac, v193
	v_rsq_f32_e32 v193, v193
	s_nop 0
	s_add_u32 s94, s78, 0x0
	s_addc_u32 s95, s79, 0
	ds_read_b128 v[176:179], v136
	ds_read_b128 v[180:183], v136 offset:4096
	ds_read_b128 v[184:187], v136 offset:64
	ds_read_b128 v[188:191], v136 offset:4160
	s_waitcnt lgkmcnt(2)
	v_sub_f32_e32 v98, v98, v192
	v_mul_f32_e32 v98, v98, v193
	v_fma_f32 v98, v176, v98, v180
	v_sub_f32_e32 v99, v99, v192
	v_mul_f32_e32 v99, v99, v193
	v_fma_f32 v99, v177, v99, v181
	v_sub_f32_e32 v100, v100, v192
	v_mul_f32_e32 v100, v100, v193
	v_fma_f32 v100, v178, v100, v182
	v_sub_f32_e32 v101, v101, v192
	v_mul_f32_e32 v101, v101, v193
	v_fma_f32 v101, v179, v101, v183
	global_store_dwordx4 v137, v[98:101], s[94:95]
	ds_read_b128 v[176:179], v136 offset:128
	ds_read_b128 v[180:183], v136 offset:4224
	s_waitcnt lgkmcnt(2)
	v_sub_f32_e32 v94, v94, v192
	v_mul_f32_e32 v94, v94, v193
	v_fma_f32 v94, v184, v94, v188
	v_sub_f32_e32 v95, v95, v192
	v_mul_f32_e32 v95, v95, v193
	v_fma_f32 v95, v185, v95, v189
	v_sub_f32_e32 v96, v96, v192
	v_mul_f32_e32 v96, v96, v193
	v_fma_f32 v96, v186, v96, v190
	v_sub_f32_e32 v97, v97, v192
	v_mul_f32_e32 v97, v97, v193
	v_fma_f32 v97, v187, v97, v191
	global_store_dwordx4 v137, v[94:97], s[94:95] offset:64
	ds_read_b128 v[184:187], v136 offset:192
	ds_read_b128 v[188:191], v136 offset:4288
	s_waitcnt lgkmcnt(2)
	v_sub_f32_e32 v90, v90, v192
	v_mul_f32_e32 v90, v90, v193
	v_fma_f32 v90, v176, v90, v180
	v_sub_f32_e32 v91, v91, v192
	v_mul_f32_e32 v91, v91, v193
	v_fma_f32 v91, v177, v91, v181
	v_sub_f32_e32 v92, v92, v192
	v_mul_f32_e32 v92, v92, v193
	v_fma_f32 v92, v178, v92, v182
	v_sub_f32_e32 v93, v93, v192
	v_mul_f32_e32 v93, v93, v193
	v_fma_f32 v93, v179, v93, v183
	global_store_dwordx4 v137, v[90:93], s[94:95] offset:128
	ds_read_b128 v[176:179], v136 offset:256
	ds_read_b128 v[180:183], v136 offset:4352
	s_waitcnt lgkmcnt(2)
	v_sub_f32_e32 v86, v86, v192
	v_mul_f32_e32 v86, v86, v193
	v_fma_f32 v86, v184, v86, v188
	v_sub_f32_e32 v87, v87, v192
	v_mul_f32_e32 v87, v87, v193
	v_fma_f32 v87, v185, v87, v189
	v_sub_f32_e32 v88, v88, v192
	v_mul_f32_e32 v88, v88, v193
	v_fma_f32 v88, v186, v88, v190
	v_sub_f32_e32 v89, v89, v192
	v_mul_f32_e32 v89, v89, v193
	v_fma_f32 v89, v187, v89, v191
	global_store_dwordx4 v137, v[86:89], s[94:95] offset:192
	ds_read_b128 v[184:187], v136 offset:320
	ds_read_b128 v[188:191], v136 offset:4416
	s_waitcnt lgkmcnt(2)
	v_sub_f32_e32 v82, v82, v192
	v_mul_f32_e32 v82, v82, v193
	v_fma_f32 v82, v176, v82, v180
	v_sub_f32_e32 v83, v83, v192
	v_mul_f32_e32 v83, v83, v193
	v_fma_f32 v83, v177, v83, v181
	v_sub_f32_e32 v84, v84, v192
	v_mul_f32_e32 v84, v84, v193
	v_fma_f32 v84, v178, v84, v182
	v_sub_f32_e32 v85, v85, v192
	v_mul_f32_e32 v85, v85, v193
	v_fma_f32 v85, v179, v85, v183
	global_store_dwordx4 v137, v[82:85], s[94:95] offset:256
	ds_read_b128 v[176:179], v136 offset:384
	ds_read_b128 v[180:183], v136 offset:4480
	s_waitcnt lgkmcnt(2)
	v_sub_f32_e32 v78, v78, v192
	v_mul_f32_e32 v78, v78, v193
	v_fma_f32 v78, v184, v78, v188
	v_sub_f32_e32 v79, v79, v192
	v_mul_f32_e32 v79, v79, v193
	v_fma_f32 v79, v185, v79, v189
	v_sub_f32_e32 v80, v80, v192
	v_mul_f32_e32 v80, v80, v193
	v_fma_f32 v80, v186, v80, v190
	v_sub_f32_e32 v81, v81, v192
	v_mul_f32_e32 v81, v81, v193
	v_fma_f32 v81, v187, v81, v191
	global_store_dwordx4 v137, v[78:81], s[94:95] offset:320
	ds_read_b128 v[184:187], v136 offset:448
	ds_read_b128 v[188:191], v136 offset:4544
	s_waitcnt lgkmcnt(2)
	v_sub_f32_e32 v74, v74, v192
	v_mul_f32_e32 v74, v74, v193
	v_fma_f32 v74, v176, v74, v180
	v_sub_f32_e32 v75, v75, v192
	v_mul_f32_e32 v75, v75, v193
	v_fma_f32 v75, v177, v75, v181
	v_sub_f32_e32 v76, v76, v192
	v_mul_f32_e32 v76, v76, v193
	v_fma_f32 v76, v178, v76, v182
	v_sub_f32_e32 v77, v77, v192
	v_mul_f32_e32 v77, v77, v193
	v_fma_f32 v77, v179, v77, v183
	global_store_dwordx4 v137, v[74:77], s[94:95] offset:384
	s_waitcnt lgkmcnt(0)
	v_sub_f32_e32 v70, v70, v192
	v_mul_f32_e32 v70, v70, v193
	v_fma_f32 v70, v184, v70, v188
	v_sub_f32_e32 v71, v71, v192
	v_mul_f32_e32 v71, v71, v193
	v_fma_f32 v71, v185, v71, v189
	v_sub_f32_e32 v72, v72, v192
	v_mul_f32_e32 v72, v72, v193
	v_fma_f32 v72, v186, v72, v190
	v_sub_f32_e32 v73, v73, v192
	v_mul_f32_e32 v73, v73, v193
	v_fma_f32 v73, v187, v73, v191
	global_store_dwordx4 v137, v[70:73], s[94:95] offset:448
	s_waitcnt vmcnt(12) lgkmcnt(0)
	s_barrier
; DI float bf2f(unsigned b) { return __uint_as_float(b << 16); }
; DI void unit_O(const Params& p, char* lds, int l, int tile, int glu_tiles, int tile_b) {
;     ...
;         float s2[2], ss2[2];
; #pragma unroll
;         for (int mh = 0; mh < 2; ++mh) {
;             const int mt = half * 2 + mh, rl = mh * 16 + l15;
;             float s = 0.f, ss = 0.f;
; #pragma unroll
;             for (int nt = 0; nt < 8; ++nt) {
;                 f32x4 xr;
;                 if (l == 0) {
;                     const int chunk = wid * 32 + nt * 4 + quad;
;                     xr = *(const f32x4*)(XR + rl * 4096 + ((chunk ^ l15) << 4));
;                 } else {
;                     const u32x2 hb = *(const u32x2*)(XR + ((wid * 4 + (nt >> 1)) * 32 + rl) * 64 + (nt & 1) * 32 + quad * 8);
;                     xr = (f32x4){bf2f(hb[0] & 0xffffu), bf2f(hb[0] >> 16), bf2f(hb[1] & 0xffffu), bf2f(hb[1] >> 16)};
;                 }
; #pragma unroll
;                 for (int i = 0; i < 4; ++i) { const float v = acc[mt][nt][i] + DN_ALPHA * xr[i]; acc[mt][nt][i] = v; s += v; ss += v * v; }
;             }
;             s2[mh] = s; ss2[mh] = ss;
;         }
; #pragma unroll
;         for (int mh = 0; mh < 2; ++mh) { s2[mh] += __shfl_xor(s2[mh], 16); ss2[mh] += __shfl_xor(ss2[mh], 16); }
; #pragma unroll
;         for (int mh = 0; mh < 2; ++mh) { s2[mh] += __shfl_xor(s2[mh], 32); ss2[mh] += __shfl_xor(ss2[mh], 32); }
;         if (quad == 0) {
; #pragma unroll
;             for (int mh = 0; mh < 2; ++mh) *(f32x2*)&red[((mh * 16 + l15) * 8 + wid) * 2] = (f32x2){s2[mh], ss2[mh]};
;         }
	ds_read_b64 v[180:181], v133 offset:32768
	ds_read_b64 v[182:183], v133 offset:32800
	ds_read_b64 v[184:185], v133 offset:33792
	ds_read_b64 v[186:187], v133 offset:33824
	ds_read_b64 v[188:189], v133 offset:34816
	ds_read_b64 v[190:191], v133 offset:34848
	ds_read_b64 v[192:193], v133 offset:35840
	ds_read_b64 v[194:195], v133 offset:35872
	s_waitcnt lgkmcnt(7)
	v_lshlrev_b32_e32 v144, 16, v180
	v_and_b32_e32 v145, 0xffff0000, v180
	v_lshlrev_b32_e32 v146, 16, v181
	v_and_b32_e32 v147, 0xffff0000, v181
	v_fmac_f32_e32 v126, s58, v144
	v_fmac_f32_e32 v127, s58, v145
	v_fmac_f32_e32 v128, s58, v146
	v_fmac_f32_e32 v129, s58, v147
	v_mov_b32_e32 v196, v126
	v_mul_f32_e32 v197, v126, v126
	v_mov_b32_e32 v130, v127
	v_mul_f32_e32 v142, v127, v127
	v_add_f32_e32 v196, v196, v128
	v_fmac_f32_e32 v197, v128, v128
	v_add_f32_e32 v130, v130, v129
	v_fmac_f32_e32 v142, v129, v129
	s_waitcnt lgkmcnt(6)
	v_lshlrev_b32_e32 v148, 16, v182
	v_and_b32_e32 v149, 0xffff0000, v182
	v_lshlrev_b32_e32 v150, 16, v183
	v_and_b32_e32 v151, 0xffff0000, v183
	v_fmac_f32_e32 v122, s58, v148
	v_fmac_f32_e32 v123, s58, v149
	v_fmac_f32_e32 v124, s58, v150
	v_fmac_f32_e32 v125, s58, v151
	v_add_f32_e32 v196, v196, v122
	v_fmac_f32_e32 v197, v122, v122
	v_add_f32_e32 v130, v130, v123
	v_fmac_f32_e32 v142, v123, v123
	v_add_f32_e32 v196, v196, v124
	v_fmac_f32_e32 v197, v124, v124
	v_add_f32_e32 v130, v130, v125
	v_fmac_f32_e32 v142, v125, v125
	s_waitcnt lgkmcnt(5)
	v_lshlrev_b32_e32 v152, 16, v184
	v_and_b32_e32 v153, 0xffff0000, v184
	v_lshlrev_b32_e32 v154, 16, v185
	v_and_b32_e32 v155, 0xffff0000, v185
	v_fmac_f32_e32 v118, s58, v152
	v_fmac_f32_e32 v119, s58, v153
	v_fmac_f32_e32 v120, s58, v154
	v_fmac_f32_e32 v121, s58, v155
	v_add_f32_e32 v196, v196, v118
	v_fmac_f32_e32 v197, v118, v118
	v_add_f32_e32 v130, v130, v119
	v_fmac_f32_e32 v142, v119, v119
	v_add_f32_e32 v196, v196, v120
	v_fmac_f32_e32 v197, v120, v120
	v_add_f32_e32 v130, v130, v121
	v_fmac_f32_e32 v142, v121, v121
	s_waitcnt lgkmcnt(4)
	v_lshlrev_b32_e32 v156, 16, v186
	v_and_b32_e32 v157, 0xffff0000, v186
	v_lshlrev_b32_e32 v158, 16, v187
	v_and_b32_e32 v159, 0xffff0000, v187
	v_fmac_f32_e32 v114, s58, v156
	v_fmac_f32_e32 v115, s58, v157
	v_fmac_f32_e32 v116, s58, v158
	v_fmac_f32_e32 v117, s58, v159
	v_add_f32_e32 v196, v196, v114
	v_fmac_f32_e32 v197, v114, v114
	v_add_f32_e32 v130, v130, v115
	v_fmac_f32_e32 v142, v115, v115
	v_add_f32_e32 v196, v196, v116
	v_fmac_f32_e32 v197, v116, v116
	v_add_f32_e32 v130, v130, v117
	v_fmac_f32_e32 v142, v117, v117
	s_waitcnt lgkmcnt(3)
	v_lshlrev_b32_e32 v160, 16, v188
	v_and_b32_e32 v161, 0xffff0000, v188
	v_lshlrev_b32_e32 v162, 16, v189
	v_and_b32_e32 v163, 0xffff0000, v189
	v_fmac_f32_e32 v110, s58, v160
	v_fmac_f32_e32 v111, s58, v161
	v_fmac_f32_e32 v112, s58, v162
	v_fmac_f32_e32 v113, s58, v163
	v_add_f32_e32 v196, v196, v110
	v_fmac_f32_e32 v197, v110, v110
	v_add_f32_e32 v130, v130, v111
	v_fmac_f32_e32 v142, v111, v111
	v_add_f32_e32 v196, v196, v112
	v_fmac_f32_e32 v197, v112, v112
	v_add_f32_e32 v130, v130, v113
	v_fmac_f32_e32 v142, v113, v113
	s_waitcnt lgkmcnt(2)
	v_lshlrev_b32_e32 v164, 16, v190
	v_and_b32_e32 v165, 0xffff0000, v190
	v_lshlrev_b32_e32 v166, 16, v191
	v_and_b32_e32 v167, 0xffff0000, v191
	v_fmac_f32_e32 v106, s58, v164
	v_fmac_f32_e32 v107, s58, v165
	v_fmac_f32_e32 v108, s58, v166
	v_fmac_f32_e32 v109, s58, v167
	v_add_f32_e32 v196, v196, v106
	v_fmac_f32_e32 v197, v106, v106
	v_add_f32_e32 v130, v130, v107
	v_fmac_f32_e32 v142, v107, v107
	v_add_f32_e32 v196, v196, v108
	v_fmac_f32_e32 v197, v108, v108
	v_add_f32_e32 v130, v130, v109
	v_fmac_f32_e32 v142, v109, v109
	s_waitcnt lgkmcnt(1)
	v_lshlrev_b32_e32 v168, 16, v192
	v_and_b32_e32 v169, 0xffff0000, v192
	v_lshlrev_b32_e32 v170, 16, v193
	v_and_b32_e32 v171, 0xffff0000, v193
	v_fmac_f32_e32 v102, s58, v168
	v_fmac_f32_e32 v103, s58, v169
	v_fmac_f32_e32 v104, s58, v170
	v_fmac_f32_e32 v105, s58, v171
	v_add_f32_e32 v196, v196, v102
	v_fmac_f32_e32 v197, v102, v102
	v_add_f32_e32 v130, v130, v103
	v_fmac_f32_e32 v142, v103, v103
	v_add_f32_e32 v196, v196, v104
	v_fmac_f32_e32 v197, v104, v104
	v_add_f32_e32 v130, v130, v105
	v_fmac_f32_e32 v142, v105, v105
	s_waitcnt lgkmcnt(0)
	v_lshlrev_b32_e32 v172, 16, v194
	v_and_b32_e32 v173, 0xffff0000, v194
	v_lshlrev_b32_e32 v174, 16, v195
	v_and_b32_e32 v175, 0xffff0000, v195
	v_fmac_f32_e32 v66, s58, v172
	v_fmac_f32_e32 v67, s58, v173
	v_fmac_f32_e32 v68, s58, v174
	v_fmac_f32_e32 v69, s58, v175
	v_add_f32_e32 v196, v196, v66
	v_fmac_f32_e32 v197, v66, v66
	v_add_f32_e32 v130, v130, v67
	v_fmac_f32_e32 v142, v67, v67
	v_add_f32_e32 v196, v196, v68
	v_fmac_f32_e32 v197, v68, v68
	v_add_f32_e32 v130, v130, v69
	v_fmac_f32_e32 v142, v69, v69
	v_add_f32_e32 v196, v196, v130
	v_add_f32_e32 v197, v197, v142
	v_mov_b32_e32 v198, v196
	v_mov_b32_e32 v199, v197
	s_nop 1
	v_permlane16_swap_b32 v198, v196
	v_permlane16_swap_b32 v199, v197
	v_add_f32_e32 v196, v196, v198
	v_add_f32_e32 v197, v197, v199
	v_mov_b32_e32 v198, v196
	v_mov_b32_e32 v199, v197
	s_nop 1
	v_permlane32_swap_b32 v198, v196
	v_permlane32_swap_b32 v199, v197
	v_add_f32_e32 v196, v196, v198
	v_add_f32_e32 v197, v197, v199
	s_mov_b64 exec, 0xffff
	ds_write_b64 v134, v[196:197]
	s_mov_b64 exec, -1
	s_waitcnt lgkmcnt(0)
	s_barrier
; DI unsigned pk2(float lo, float hi) { const f32x2 v = {lo, hi}; const bf16x2_t b = __builtin_convertvector(v, bf16x2_t); return __builtin_bit_cast(unsigned, b); }
; DI void unit_O(const Params& p, char* lds, int l, int tile, int glu_tiles, int tile_b) {
;     ...
;     auto issue_x = [&](int half) {
;         if (l == 0) {
; #pragma unroll 1
;             for (int i = 0; i < 16; ++i) {
;                 const int pc = (wid * 16 + i + xrot) & 127, row = pc >> 2, phys = (pc & 3) * 64 + lane, logical = phys ^ (row & 15);
;                 __builtin_amdgcn_global_load_lds((const unsigned*)(xres + (r0 + half * 32 + row) * 1024 + logical * 4), (unsigned*)(XR + pc * 1024 + lane * 16), 16, 0, 0);
;             }
;         } else {
; #pragma unroll 1
;             for (int i = 0; i < 8; ++i) {
;                 const int pc = (wid * 8 + i + (xrot >> 1)) & 63, kt = pc >> 1, sub = pc & 1;
;                 __builtin_amdgcn_global_load_lds((const unsigned*)(xbres + ((size_t)kt * 128 + half * 32) * 32 + sub * 512 + lane * 8), (unsigned*)(XR + pc * 1024 + lane * 16), 16, 0, 0);
;             }
;         }
;     ...
;         for (int mh = 0; mh < 2; ++mh) {
;             const int mt = half * 2 + mh, rl = mh * 16 + l15, row = mt * 16 + l15;
;             float s = 0.f, ss = 0.f;
; #pragma unroll
;             for (int w = 0; w < 4; ++w) { const f32x4 v = *(const f32x4*)&red[rl * 16 + 4 * w]; s += v[0] + v[2]; ss += v[1] + v[3]; }
;             const float mu = s * (1.f / 1024.f);
;             const float var = ss * (1.f / 1024.f) - mu * mu;
;             const float rs = rsqrtf(var + LN_EPS);
;             float* orow = xo + (r0 + row) * 1024 + wid * 128 + quad * 4;
;             bf16_t* brow = xbo + xb_off((int)r0 + row, wid * 128) + quad * 4;
;             const float* gp = GB + wid * 128 + quad * 4;
; #pragma unroll
;             for (int nt = 0; nt < 8; ++nt) {
;                 const f32x4 g = *(const f32x4*)(gp + nt * 16), bb = *(const f32x4*)(gp + 1024 + nt * 16);
;                 f32x4 o;
; #pragma unroll
;                 for (int i = 0; i < 4; ++i) o[i] = (acc[mt][nt][i] - mu) * rs * g[i] + bb[i];
;                 if (l == 0) *(u32x2*)(brow + (nt >> 1) * 4096 + (nt & 1) * 16) = (u32x2){pk2(o[0], o[1]), pk2(o[2], o[3])};
;                 else *(f32x4*)(orow + nt * 16) = o;
;             }
;         }
	s_add_u32 s92, s96, 0xc00
	s_addc_u32 s93, s97, 0
	s_add_u32 s40, s91, 0x8000
	s_mov_b32 m0, s40
	s_nop 0
	global_load_lds_dwordx4 v208, s[92:93]
	s_add_u32 s92, s92, 0x2000
	s_addc_u32 s93, s93, 0
	s_add_u32 m0, m0, 0x400
	s_nop 0
	global_load_lds_dwordx4 v208, s[92:93]
	s_add_u32 s92, s92, 0x2000
	s_addc_u32 s93, s93, 0
	s_add_u32 m0, m0, 0x400
	s_nop 0
	global_load_lds_dwordx4 v208, s[92:93]
	s_add_u32 s92, s92, 0x2000
	s_addc_u32 s93, s93, 0
	s_add_u32 m0, m0, 0x400
	s_nop 0
	global_load_lds_dwordx4 v208, s[92:93]
	ds_read_b128 v[160:163], v135 offset:0
	ds_read_b128 v[164:167], v135 offset:16
	ds_read_b128 v[168:171], v135 offset:32
	ds_read_b128 v[172:175], v135 offset:48
	s_waitcnt lgkmcnt(0)
	v_add_f32_e32 v160, v160, v162
	v_add_f32_e32 v161, v161, v163
	v_add_f32_e32 v164, v164, v166
	v_add_f32_e32 v165, v165, v167
	v_add_f32_e32 v168, v168, v170
	v_add_f32_e32 v169, v169, v171
	v_add_f32_e32 v172, v172, v174
	v_add_f32_e32 v173, v173, v175
	v_add_f32_e32 v160, v160, v164
	v_add_f32_e32 v161, v161, v165
	v_add_f32_e32 v168, v168, v172
	v_add_f32_e32 v169, v169, v173
	v_add_f32_e32 v160, v160, v168
	v_add_f32_e32 v161, v161, v169
	v_mul_f32_e32 v192, 0x3a800000, v160
	v_mul_f32_e32 v193, 0x3a800000, v161
	v_fma_f32 v193, -v192, v192, v193
	v_add_f32_e32 v193, 0x3727c5ac, v193
	v_rsq_f32_e32 v193, v193
	s_nop 0
	s_add_u32 s94, s78, 0x10000
	s_addc_u32 s95, s79, 0
	ds_read_b128 v[176:179], v136
	ds_read_b128 v[180:183], v136 offset:4096
	ds_read_b128 v[184:187], v136 offset:64
	ds_read_b128 v[188:191], v136 offset:4160
	s_waitcnt lgkmcnt(2)
	v_sub_f32_e32 v126, v126, v192
	v_mul_f32_e32 v126, v126, v193
	v_fma_f32 v126, v176, v126, v180
	v_sub_f32_e32 v127, v127, v192
	v_mul_f32_e32 v127, v127, v193
	v_fma_f32 v127, v177, v127, v181
	v_sub_f32_e32 v128, v128, v192
	v_mul_f32_e32 v128, v128, v193
	v_fma_f32 v128, v178, v128, v182
	v_sub_f32_e32 v129, v129, v192
	v_mul_f32_e32 v129, v129, v193
	v_fma_f32 v129, v179, v129, v183
	global_store_dwordx4 v137, v[126:129], s[94:95]
	ds_read_b128 v[176:179], v136 offset:128
	ds_read_b128 v[180:183], v136 offset:4224
	s_waitcnt lgkmcnt(2)
	v_sub_f32_e32 v122, v122, v192
	v_mul_f32_e32 v122, v122, v193
	v_fma_f32 v122, v184, v122, v188
	v_sub_f32_e32 v123, v123, v192
	v_mul_f32_e32 v123, v123, v193
	v_fma_f32 v123, v185, v123, v189
	v_sub_f32_e32 v124, v124, v192
	v_mul_f32_e32 v124, v124, v193
	v_fma_f32 v124, v186, v124, v190
	v_sub_f32_e32 v125, v125, v192
	v_mul_f32_e32 v125, v125, v193
	v_fma_f32 v125, v187, v125, v191
	global_store_dwordx4 v137, v[122:125], s[94:95] offset:64
	ds_read_b128 v[184:187], v136 offset:192
	ds_read_b128 v[188:191], v136 offset:4288
	s_waitcnt lgkmcnt(2)
	v_sub_f32_e32 v118, v118, v192
	v_mul_f32_e32 v118, v118, v193
	v_fma_f32 v118, v176, v118, v180
	v_sub_f32_e32 v119, v119, v192
	v_mul_f32_e32 v119, v119, v193
	v_fma_f32 v119, v177, v119, v181
	v_sub_f32_e32 v120, v120, v192
	v_mul_f32_e32 v120, v120, v193
	v_fma_f32 v120, v178, v120, v182
	v_sub_f32_e32 v121, v121, v192
	v_mul_f32_e32 v121, v121, v193
	v_fma_f32 v121, v179, v121, v183
	global_store_dwordx4 v137, v[118:121], s[94:95] offset:128
	ds_read_b128 v[176:179], v136 offset:256
	ds_read_b128 v[180:183], v136 offset:4352
	s_waitcnt lgkmcnt(2)
	v_sub_f32_e32 v114, v114, v192
	v_mul_f32_e32 v114, v114, v193
	v_fma_f32 v114, v184, v114, v188
	v_sub_f32_e32 v115, v115, v192
	v_mul_f32_e32 v115, v115, v193
	v_fma_f32 v115, v185, v115, v189
	v_sub_f32_e32 v116, v116, v192
	v_mul_f32_e32 v116, v116, v193
	v_fma_f32 v116, v186, v116, v190
	v_sub_f32_e32 v117, v117, v192
	v_mul_f32_e32 v117, v117, v193
	v_fma_f32 v117, v187, v117, v191
	global_store_dwordx4 v137, v[114:117], s[94:95] offset:192
	ds_read_b128 v[184:187], v136 offset:320
	ds_read_b128 v[188:191], v136 offset:4416
	s_waitcnt lgkmcnt(2)
	v_sub_f32_e32 v110, v110, v192
	v_mul_f32_e32 v110, v110, v193
	v_fma_f32 v110, v176, v110, v180
	v_sub_f32_e32 v111, v111, v192
	v_mul_f32_e32 v111, v111, v193
	v_fma_f32 v111, v177, v111, v181
	v_sub_f32_e32 v112, v112, v192
	v_mul_f32_e32 v112, v112, v193
	v_fma_f32 v112, v178, v112, v182
	v_sub_f32_e32 v113, v113, v192
	v_mul_f32_e32 v113, v113, v193
	v_fma_f32 v113, v179, v113, v183
	global_store_dwordx4 v137, v[110:113], s[94:95] offset:256
	ds_read_b128 v[176:179], v136 offset:384
	ds_read_b128 v[180:183], v136 offset:4480
	s_waitcnt lgkmcnt(2)
	v_sub_f32_e32 v106, v106, v192
	v_mul_f32_e32 v106, v106, v193
	v_fma_f32 v106, v184, v106, v188
	v_sub_f32_e32 v107, v107, v192
	v_mul_f32_e32 v107, v107, v193
	v_fma_f32 v107, v185, v107, v189
	v_sub_f32_e32 v108, v108, v192
	v_mul_f32_e32 v108, v108, v193
	v_fma_f32 v108, v186, v108, v190
	v_sub_f32_e32 v109, v109, v192
	v_mul_f32_e32 v109, v109, v193
	v_fma_f32 v109, v187, v109, v191
	global_store_dwordx4 v137, v[106:109], s[94:95] offset:320
	ds_read_b128 v[184:187], v136 offset:448
	ds_read_b128 v[188:191], v136 offset:4544
	s_waitcnt lgkmcnt(2)
	v_sub_f32_e32 v102, v102, v192
	v_mul_f32_e32 v102, v102, v193
	v_fma_f32 v102, v176, v102, v180
	v_sub_f32_e32 v103, v103, v192
	v_mul_f32_e32 v103, v103, v193
	v_fma_f32 v103, v177, v103, v181
	v_sub_f32_e32 v104, v104, v192
	v_mul_f32_e32 v104, v104, v193
	v_fma_f32 v104, v178, v104, v182
	v_sub_f32_e32 v105, v105, v192
	v_mul_f32_e32 v105, v105, v193
	v_fma_f32 v105, v179, v105, v183
	global_store_dwordx4 v137, v[102:105], s[94:95] offset:384
	s_waitcnt lgkmcnt(0)
	v_sub_f32_e32 v66, v66, v192
	v_mul_f32_e32 v66, v66, v193
	v_fma_f32 v66, v184, v66, v188
	v_sub_f32_e32 v67, v67, v192
	v_mul_f32_e32 v67, v67, v193
	v_fma_f32 v67, v185, v67, v189
	v_sub_f32_e32 v68, v68, v192
	v_mul_f32_e32 v68, v68, v193
	v_fma_f32 v68, v186, v68, v190
	v_sub_f32_e32 v69, v69, v192
	v_mul_f32_e32 v69, v69, v193
	v_fma_f32 v69, v187, v69, v191
	global_store_dwordx4 v137, v[66:69], s[94:95] offset:448
	s_waitcnt vmcnt(20) lgkmcnt(0)
	s_barrier
; DI float bf2f(unsigned b) { return __uint_as_float(b << 16); }
; DI void unit_O(const Params& p, char* lds, int l, int tile, int glu_tiles, int tile_b) {
;     ...
;         float s2[2], ss2[2];
; #pragma unroll
;         for (int mh = 0; mh < 2; ++mh) {
;             const int mt = half * 2 + mh, rl = mh * 16 + l15;
;             float s = 0.f, ss = 0.f;
; #pragma unroll
;             for (int nt = 0; nt < 8; ++nt) {
;                 f32x4 xr;
;                 if (l == 0) {
;                     const int chunk = wid * 32 + nt * 4 + quad;
;                     xr = *(const f32x4*)(XR + rl * 4096 + ((chunk ^ l15) << 4));
;                 } else {
;                     const u32x2 hb = *(const u32x2*)(XR + ((wid * 4 + (nt >> 1)) * 32 + rl) * 64 + (nt & 1) * 32 + quad * 8);
;                     xr = (f32x4){bf2f(hb[0] & 0xffffu), bf2f(hb[0] >> 16), bf2f(hb[1] & 0xffffu), bf2f(hb[1] >> 16)};
;                 }
; #pragma unroll
;                 for (int i = 0; i < 4; ++i) { const float v = acc[mt][nt][i] + DN_ALPHA * xr[i]; acc[mt][nt][i] = v; s += v; ss += v * v; }
;             }
;             s2[mh] = s; ss2[mh] = ss;
;         }
; #pragma unroll
;         for (int mh = 0; mh < 2; ++mh) { s2[mh] += __shfl_xor(s2[mh], 16); ss2[mh] += __shfl_xor(ss2[mh], 16); }
; #pragma unroll
;         for (int mh = 0; mh < 2; ++mh) { s2[mh] += __shfl_xor(s2[mh], 32); ss2[mh] += __shfl_xor(ss2[mh], 32); }
;         if (quad == 0) {
; #pragma unroll
;             for (int mh = 0; mh < 2; ++mh) *(f32x2*)&red[((mh * 16 + l15) * 8 + wid) * 2] = (f32x2){s2[mh], ss2[mh]};
;         }
	ds_read_b64 v[180:181], v133 offset:0
	ds_read_b64 v[182:183], v133 offset:32
	ds_read_b64 v[184:185], v133 offset:1024
	ds_read_b64 v[186:187], v133 offset:1056
	ds_read_b64 v[188:189], v133 offset:2048
	ds_read_b64 v[190:191], v133 offset:2080
	ds_read_b64 v[192:193], v133 offset:3072
	ds_read_b64 v[194:195], v133 offset:3104
	s_waitcnt lgkmcnt(7)
	v_lshlrev_b32_e32 v144, 16, v180
	v_and_b32_e32 v145, 0xffff0000, v180
	v_lshlrev_b32_e32 v146, 16, v181
	v_and_b32_e32 v147, 0xffff0000, v181
	v_fmac_f32_e32 v34, s58, v144
	v_fmac_f32_e32 v35, s58, v145
	v_fmac_f32_e32 v36, s58, v146
	v_fmac_f32_e32 v37, s58, v147
	v_mov_b32_e32 v196, v34
	v_mul_f32_e32 v197, v34, v34
	v_mov_b32_e32 v130, v35
	v_mul_f32_e32 v142, v35, v35
	v_add_f32_e32 v196, v196, v36
	v_fmac_f32_e32 v197, v36, v36
	v_add_f32_e32 v130, v130, v37
	v_fmac_f32_e32 v142, v37, v37
	s_waitcnt lgkmcnt(6)
	v_lshlrev_b32_e32 v148, 16, v182
	v_and_b32_e32 v149, 0xffff0000, v182
	v_lshlrev_b32_e32 v150, 16, v183
	v_and_b32_e32 v151, 0xffff0000, v183
	v_fmac_f32_e32 v30, s58, v148
	v_fmac_f32_e32 v31, s58, v149
	v_fmac_f32_e32 v32, s58, v150
	v_fmac_f32_e32 v33, s58, v151
	v_add_f32_e32 v196, v196, v30
	v_fmac_f32_e32 v197, v30, v30
	v_add_f32_e32 v130, v130, v31
	v_fmac_f32_e32 v142, v31, v31
	v_add_f32_e32 v196, v196, v32
	v_fmac_f32_e32 v197, v32, v32
	v_add_f32_e32 v130, v130, v33
	v_fmac_f32_e32 v142, v33, v33
	s_waitcnt lgkmcnt(5)
	v_lshlrev_b32_e32 v152, 16, v184
	v_and_b32_e32 v153, 0xffff0000, v184
	v_lshlrev_b32_e32 v154, 16, v185
	v_and_b32_e32 v155, 0xffff0000, v185
	v_fmac_f32_e32 v26, s58, v152
	v_fmac_f32_e32 v27, s58, v153
	v_fmac_f32_e32 v28, s58, v154
	v_fmac_f32_e32 v29, s58, v155
	v_add_f32_e32 v196, v196, v26
	v_fmac_f32_e32 v197, v26, v26
	v_add_f32_e32 v130, v130, v27
	v_fmac_f32_e32 v142, v27, v27
	v_add_f32_e32 v196, v196, v28
	v_fmac_f32_e32 v197, v28, v28
	v_add_f32_e32 v130, v130, v29
	v_fmac_f32_e32 v142, v29, v29
	s_waitcnt lgkmcnt(4)
	v_lshlrev_b32_e32 v156, 16, v186
	v_and_b32_e32 v157, 0xffff0000, v186
	v_lshlrev_b32_e32 v158, 16, v187
	v_and_b32_e32 v159, 0xffff0000, v187
	v_fmac_f32_e32 v22, s58, v156
	v_fmac_f32_e32 v23, s58, v157
	v_fmac_f32_e32 v24, s58, v158
	v_fmac_f32_e32 v25, s58, v159
	v_add_f32_e32 v196, v196, v22
	v_fmac_f32_e32 v197, v22, v22
	v_add_f32_e32 v130, v130, v23
	v_fmac_f32_e32 v142, v23, v23
	v_add_f32_e32 v196, v196, v24
	v_fmac_f32_e32 v197, v24, v24
	v_add_f32_e32 v130, v130, v25
	v_fmac_f32_e32 v142, v25, v25
	s_waitcnt lgkmcnt(3)
	v_lshlrev_b32_e32 v160, 16, v188
	v_and_b32_e32 v161, 0xffff0000, v188
	v_lshlrev_b32_e32 v162, 16, v189
	v_and_b32_e32 v163, 0xffff0000, v189
	v_fmac_f32_e32 v18, s58, v160
	v_fmac_f32_e32 v19, s58, v161
	v_fmac_f32_e32 v20, s58, v162
	v_fmac_f32_e32 v21, s58, v163
	v_add_f32_e32 v196, v196, v18
	v_fmac_f32_e32 v197, v18, v18
	v_add_f32_e32 v130, v130, v19
	v_fmac_f32_e32 v142, v19, v19
	v_add_f32_e32 v196, v196, v20
	v_fmac_f32_e32 v197, v20, v20
	v_add_f32_e32 v130, v130, v21
	v_fmac_f32_e32 v142, v21, v21
	s_waitcnt lgkmcnt(2)
	v_lshlrev_b32_e32 v164, 16, v190
	v_and_b32_e32 v165, 0xffff0000, v190
	v_lshlrev_b32_e32 v166, 16, v191
	v_and_b32_e32 v167, 0xffff0000, v191
	v_fmac_f32_e32 v14, s58, v164
	v_fmac_f32_e32 v15, s58, v165
	v_fmac_f32_e32 v16, s58, v166
	v_fmac_f32_e32 v17, s58, v167
	v_add_f32_e32 v196, v196, v14
	v_fmac_f32_e32 v197, v14, v14
	v_add_f32_e32 v130, v130, v15
	v_fmac_f32_e32 v142, v15, v15
	v_add_f32_e32 v196, v196, v16
	v_fmac_f32_e32 v197, v16, v16
	v_add_f32_e32 v130, v130, v17
	v_fmac_f32_e32 v142, v17, v17
	s_waitcnt lgkmcnt(1)
	v_lshlrev_b32_e32 v168, 16, v192
	v_and_b32_e32 v169, 0xffff0000, v192
	v_lshlrev_b32_e32 v170, 16, v193
	v_and_b32_e32 v171, 0xffff0000, v193
	v_fmac_f32_e32 v10, s58, v168
	v_fmac_f32_e32 v11, s58, v169
	v_fmac_f32_e32 v12, s58, v170
	v_fmac_f32_e32 v13, s58, v171
	v_add_f32_e32 v196, v196, v10
	v_fmac_f32_e32 v197, v10, v10
	v_add_f32_e32 v130, v130, v11
	v_fmac_f32_e32 v142, v11, v11
	v_add_f32_e32 v196, v196, v12
	v_fmac_f32_e32 v197, v12, v12
	v_add_f32_e32 v130, v130, v13
	v_fmac_f32_e32 v142, v13, v13
	s_waitcnt lgkmcnt(0)
	v_lshlrev_b32_e32 v172, 16, v194
	v_and_b32_e32 v173, 0xffff0000, v194
	v_lshlrev_b32_e32 v174, 16, v195
	v_and_b32_e32 v175, 0xffff0000, v195
	v_fmac_f32_e32 v6, s58, v172
	v_fmac_f32_e32 v7, s58, v173
	v_fmac_f32_e32 v8, s58, v174
	v_fmac_f32_e32 v9, s58, v175
	v_add_f32_e32 v196, v196, v6
	v_fmac_f32_e32 v197, v6, v6
	v_add_f32_e32 v130, v130, v7
	v_fmac_f32_e32 v142, v7, v7
	v_add_f32_e32 v196, v196, v8
	v_fmac_f32_e32 v197, v8, v8
	v_add_f32_e32 v130, v130, v9
	v_fmac_f32_e32 v142, v9, v9
	v_add_f32_e32 v196, v196, v130
	v_add_f32_e32 v197, v197, v142
	v_mov_b32_e32 v198, v196
	v_mov_b32_e32 v199, v197
	s_nop 1
	v_permlane16_swap_b32 v198, v196
	v_permlane16_swap_b32 v199, v197
	v_add_f32_e32 v196, v196, v198
	v_add_f32_e32 v197, v197, v199
	v_mov_b32_e32 v198, v196
	v_mov_b32_e32 v199, v197
	s_nop 1
	v_permlane32_swap_b32 v198, v196
	v_permlane32_swap_b32 v199, v197
	v_add_f32_e32 v196, v196, v198
	v_add_f32_e32 v197, v197, v199
	s_mov_b64 exec, 0xffff
	ds_write_b64 v134, v[196:197]
	s_mov_b64 exec, -1
	s_waitcnt lgkmcnt(0)
	s_barrier
; DI unsigned pk2(float lo, float hi) { const f32x2 v = {lo, hi}; const bf16x2_t b = __builtin_convertvector(v, bf16x2_t); return __builtin_bit_cast(unsigned, b); }
; DI size_t xb_off(int tok, int col) { return ((size_t)(((tok >> 7) * 32 + (col >> 5)) * 128 + (tok & 127))) * 32 + (col & 31); }
; DI void unit_O(const Params& p, char* lds, int l, int tile, int glu_tiles, int tile_b) {
;     ...
;         for (int mh = 0; mh < 2; ++mh) {
;             const int mt = half * 2 + mh, rl = mh * 16 + l15, row = mt * 16 + l15;
;             float s = 0.f, ss = 0.f;
; #pragma unroll
;             for (int w = 0; w < 4; ++w) { const f32x4 v = *(const f32x4*)&red[rl * 16 + 4 * w]; s += v[0] + v[2]; ss += v[1] + v[3]; }
;             const float mu = s * (1.f / 1024.f);
;             const float var = ss * (1.f / 1024.f) - mu * mu;
;             const float rs = rsqrtf(var + LN_EPS);
;             float* orow = xo + (r0 + row) * 1024 + wid * 128 + quad * 4;
;             bf16_t* brow = xbo + xb_off((int)r0 + row, wid * 128) + quad * 4;
;             const float* gp = GB + wid * 128 + quad * 4;
; #pragma unroll
;             for (int nt = 0; nt < 8; ++nt) {
;                 const f32x4 g = *(const f32x4*)(gp + nt * 16), bb = *(const f32x4*)(gp + 1024 + nt * 16);
;                 f32x4 o;
; #pragma unroll
;                 for (int i = 0; i < 4; ++i) o[i] = (acc[mt][nt][i] - mu) * rs * g[i] + bb[i];
;                 if (l == 0) *(u32x2*)(brow + (nt >> 1) * 4096 + (nt & 1) * 16) = (u32x2){pk2(o[0], o[1]), pk2(o[2], o[3])};
;                 else *(f32x4*)(orow + nt * 16) = o;
;             }
;         }
	ds_read_b128 v[160:163], v135 offset:0
	ds_read_b128 v[164:167], v135 offset:16
	ds_read_b128 v[168:171], v135 offset:32
	ds_read_b128 v[172:175], v135 offset:48
	s_waitcnt lgkmcnt(0)
	v_add_f32_e32 v160, v160, v162
	v_add_f32_e32 v161, v161, v163
	v_add_f32_e32 v164, v164, v166
	v_add_f32_e32 v165, v165, v167
	v_add_f32_e32 v168, v168, v170
	v_add_f32_e32 v169, v169, v171
	v_add_f32_e32 v172, v172, v174
	v_add_f32_e32 v173, v173, v175
	v_add_f32_e32 v160, v160, v164
	v_add_f32_e32 v161, v161, v165
	v_add_f32_e32 v168, v168, v172
	v_add_f32_e32 v169, v169, v173
	v_add_f32_e32 v160, v160, v168
	v_add_f32_e32 v161, v161, v169
	v_mul_f32_e32 v192, 0x3a800000, v160
	v_mul_f32_e32 v193, 0x3a800000, v161
	v_fma_f32 v193, -v192, v192, v193
	v_add_f32_e32 v193, 0x3727c5ac, v193
	v_rsq_f32_e32 v193, v193
	s_nop 0
	s_add_u32 s94, s78, 0x20000
	s_addc_u32 s95, s79, 0
	ds_read_b128 v[176:179], v136
	ds_read_b128 v[180:183], v136 offset:4096
	ds_read_b128 v[184:187], v136 offset:64
	ds_read_b128 v[188:191], v136 offset:4160
	s_waitcnt lgkmcnt(2)
	v_sub_f32_e32 v34, v34, v192
	v_mul_f32_e32 v34, v34, v193
	v_fma_f32 v34, v176, v34, v180
	v_sub_f32_e32 v35, v35, v192
	v_mul_f32_e32 v35, v35, v193
	v_fma_f32 v35, v177, v35, v181
	v_sub_f32_e32 v36, v36, v192
	v_mul_f32_e32 v36, v36, v193
	v_fma_f32 v36, v178, v36, v182
	v_sub_f32_e32 v37, v37, v192
	v_mul_f32_e32 v37, v37, v193
	v_fma_f32 v37, v179, v37, v183
	global_store_dwordx4 v137, v[34:37], s[94:95]
	ds_read_b128 v[176:179], v136 offset:128
	ds_read_b128 v[180:183], v136 offset:4224
	s_waitcnt lgkmcnt(2)
	v_sub_f32_e32 v30, v30, v192
	v_mul_f32_e32 v30, v30, v193
	v_fma_f32 v30, v184, v30, v188
	v_sub_f32_e32 v31, v31, v192
	v_mul_f32_e32 v31, v31, v193
	v_fma_f32 v31, v185, v31, v189
	v_sub_f32_e32 v32, v32, v192
	v_mul_f32_e32 v32, v32, v193
	v_fma_f32 v32, v186, v32, v190
	v_sub_f32_e32 v33, v33, v192
	v_mul_f32_e32 v33, v33, v193
	v_fma_f32 v33, v187, v33, v191
	global_store_dwordx4 v137, v[30:33], s[94:95] offset:64
	ds_read_b128 v[184:187], v136 offset:192
	ds_read_b128 v[188:191], v136 offset:4288
	s_waitcnt lgkmcnt(2)
	v_sub_f32_e32 v26, v26, v192
	v_mul_f32_e32 v26, v26, v193
	v_fma_f32 v26, v176, v26, v180
	v_sub_f32_e32 v27, v27, v192
	v_mul_f32_e32 v27, v27, v193
	v_fma_f32 v27, v177, v27, v181
	v_sub_f32_e32 v28, v28, v192
	v_mul_f32_e32 v28, v28, v193
	v_fma_f32 v28, v178, v28, v182
	v_sub_f32_e32 v29, v29, v192
	v_mul_f32_e32 v29, v29, v193
	v_fma_f32 v29, v179, v29, v183
	global_store_dwordx4 v137, v[26:29], s[94:95] offset:128
	ds_read_b128 v[176:179], v136 offset:256
	ds_read_b128 v[180:183], v136 offset:4352
	s_waitcnt lgkmcnt(2)
	v_sub_f32_e32 v22, v22, v192
	v_mul_f32_e32 v22, v22, v193
	v_fma_f32 v22, v184, v22, v188
	v_sub_f32_e32 v23, v23, v192
	v_mul_f32_e32 v23, v23, v193
	v_fma_f32 v23, v185, v23, v189
	v_sub_f32_e32 v24, v24, v192
	v_mul_f32_e32 v24, v24, v193
	v_fma_f32 v24, v186, v24, v190
	v_sub_f32_e32 v25, v25, v192
	v_mul_f32_e32 v25, v25, v193
	v_fma_f32 v25, v187, v25, v191
	global_store_dwordx4 v137, v[22:25], s[94:95] offset:192
	ds_read_b128 v[184:187], v136 offset:320
	ds_read_b128 v[188:191], v136 offset:4416
	s_waitcnt lgkmcnt(2)
	v_sub_f32_e32 v18, v18, v192
	v_mul_f32_e32 v18, v18, v193
	v_fma_f32 v18, v176, v18, v180
	v_sub_f32_e32 v19, v19, v192
	v_mul_f32_e32 v19, v19, v193
	v_fma_f32 v19, v177, v19, v181
	v_sub_f32_e32 v20, v20, v192
	v_mul_f32_e32 v20, v20, v193
	v_fma_f32 v20, v178, v20, v182
	v_sub_f32_e32 v21, v21, v192
	v_mul_f32_e32 v21, v21, v193
	v_fma_f32 v21, v179, v21, v183
	global_store_dwordx4 v137, v[18:21], s[94:95] offset:256
	ds_read_b128 v[176:179], v136 offset:384
	ds_read_b128 v[180:183], v136 offset:4480
	s_waitcnt lgkmcnt(2)
	v_sub_f32_e32 v14, v14, v192
	v_mul_f32_e32 v14, v14, v193
	v_fma_f32 v14, v184, v14, v188
	v_sub_f32_e32 v15, v15, v192
	v_mul_f32_e32 v15, v15, v193
	v_fma_f32 v15, v185, v15, v189
	v_sub_f32_e32 v16, v16, v192
	v_mul_f32_e32 v16, v16, v193
	v_fma_f32 v16, v186, v16, v190
	v_sub_f32_e32 v17, v17, v192
	v_mul_f32_e32 v17, v17, v193
	v_fma_f32 v17, v187, v17, v191
	global_store_dwordx4 v137, v[14:17], s[94:95] offset:320
	ds_read_b128 v[184:187], v136 offset:448
	ds_read_b128 v[188:191], v136 offset:4544
	s_waitcnt lgkmcnt(2)
	v_sub_f32_e32 v10, v10, v192
	v_mul_f32_e32 v10, v10, v193
	v_fma_f32 v10, v176, v10, v180
	v_sub_f32_e32 v11, v11, v192
	v_mul_f32_e32 v11, v11, v193
	v_fma_f32 v11, v177, v11, v181
	v_sub_f32_e32 v12, v12, v192
	v_mul_f32_e32 v12, v12, v193
	v_fma_f32 v12, v178, v12, v182
	v_sub_f32_e32 v13, v13, v192
	v_mul_f32_e32 v13, v13, v193
	v_fma_f32 v13, v179, v13, v183
	global_store_dwordx4 v137, v[10:13], s[94:95] offset:384
	s_waitcnt lgkmcnt(0)
	v_sub_f32_e32 v6, v6, v192
	v_mul_f32_e32 v6, v6, v193
	v_fma_f32 v6, v184, v6, v188
	v_sub_f32_e32 v7, v7, v192
	v_mul_f32_e32 v7, v7, v193
	v_fma_f32 v7, v185, v7, v189
	v_sub_f32_e32 v8, v8, v192
	v_mul_f32_e32 v8, v8, v193
	v_fma_f32 v8, v186, v8, v190
	v_sub_f32_e32 v9, v9, v192
	v_mul_f32_e32 v9, v9, v193
	v_fma_f32 v9, v187, v9, v191
	global_store_dwordx4 v137, v[6:9], s[94:95] offset:448
	s_waitcnt vmcnt(16) lgkmcnt(0)
	s_barrier
; DI float bf2f(unsigned b) { return __uint_as_float(b << 16); }
; DI void unit_O(const Params& p, char* lds, int l, int tile, int glu_tiles, int tile_b) {
;     ...
;         float s2[2], ss2[2];
; #pragma unroll
;         for (int mh = 0; mh < 2; ++mh) {
;             const int mt = half * 2 + mh, rl = mh * 16 + l15;
;             float s = 0.f, ss = 0.f;
; #pragma unroll
;             for (int nt = 0; nt < 8; ++nt) {
;                 f32x4 xr;
;                 if (l == 0) {
;                     const int chunk = wid * 32 + nt * 4 + quad;
;                     xr = *(const f32x4*)(XR + rl * 4096 + ((chunk ^ l15) << 4));
;                 } else {
;                     const u32x2 hb = *(const u32x2*)(XR + ((wid * 4 + (nt >> 1)) * 32 + rl) * 64 + (nt & 1) * 32 + quad * 8);
;                     xr = (f32x4){bf2f(hb[0] & 0xffffu), bf2f(hb[0] >> 16), bf2f(hb[1] & 0xffffu), bf2f(hb[1] >> 16)};
;                 }
; #pragma unroll
;                 for (int i = 0; i < 4; ++i) { const float v = acc[mt][nt][i] + DN_ALPHA * xr[i]; acc[mt][nt][i] = v; s += v; ss += v * v; }
;             }
;             s2[mh] = s; ss2[mh] = ss;
;         }
; #pragma unroll
;         for (int mh = 0; mh < 2; ++mh) { s2[mh] += __shfl_xor(s2[mh], 16); ss2[mh] += __shfl_xor(ss2[mh], 16); }
; #pragma unroll
;         for (int mh = 0; mh < 2; ++mh) { s2[mh] += __shfl_xor(s2[mh], 32); ss2[mh] += __shfl_xor(ss2[mh], 32); }
;         if (quad == 0) {
; #pragma unroll
;             for (int mh = 0; mh < 2; ++mh) *(f32x2*)&red[((mh * 16 + l15) * 8 + wid) * 2] = (f32x2){s2[mh], ss2[mh]};
;         }
;         __syncthreads();
	ds_read_b64 v[180:181], v133 offset:32768
	ds_read_b64 v[182:183], v133 offset:32800
	ds_read_b64 v[184:185], v133 offset:33792
	ds_read_b64 v[186:187], v133 offset:33824
	ds_read_b64 v[188:189], v133 offset:34816
	ds_read_b64 v[190:191], v133 offset:34848
	ds_read_b64 v[192:193], v133 offset:35840
	ds_read_b64 v[194:195], v133 offset:35872
	s_waitcnt lgkmcnt(7)
	v_lshlrev_b32_e32 v144, 16, v180
	v_and_b32_e32 v145, 0xffff0000, v180
	v_lshlrev_b32_e32 v146, 16, v181
	v_and_b32_e32 v147, 0xffff0000, v181
	v_fmac_f32_e32 v62, s58, v144
	v_fmac_f32_e32 v63, s58, v145
	v_fmac_f32_e32 v64, s58, v146
	v_fmac_f32_e32 v65, s58, v147
	v_mov_b32_e32 v196, v62
	v_mul_f32_e32 v197, v62, v62
	v_mov_b32_e32 v130, v63
	v_mul_f32_e32 v142, v63, v63
	v_add_f32_e32 v196, v196, v64
	v_fmac_f32_e32 v197, v64, v64
	v_add_f32_e32 v130, v130, v65
	v_fmac_f32_e32 v142, v65, v65
	s_waitcnt lgkmcnt(6)
	v_lshlrev_b32_e32 v148, 16, v182
	v_and_b32_e32 v149, 0xffff0000, v182
	v_lshlrev_b32_e32 v150, 16, v183
	v_and_b32_e32 v151, 0xffff0000, v183
	v_fmac_f32_e32 v58, s58, v148
	v_fmac_f32_e32 v59, s58, v149
	v_fmac_f32_e32 v60, s58, v150
	v_fmac_f32_e32 v61, s58, v151
	v_add_f32_e32 v196, v196, v58
	v_fmac_f32_e32 v197, v58, v58
	v_add_f32_e32 v130, v130, v59
	v_fmac_f32_e32 v142, v59, v59
	v_add_f32_e32 v196, v196, v60
	v_fmac_f32_e32 v197, v60, v60
	v_add_f32_e32 v130, v130, v61
	v_fmac_f32_e32 v142, v61, v61
	s_waitcnt lgkmcnt(5)
	v_lshlrev_b32_e32 v152, 16, v184
	v_and_b32_e32 v153, 0xffff0000, v184
	v_lshlrev_b32_e32 v154, 16, v185
	v_and_b32_e32 v155, 0xffff0000, v185
	v_fmac_f32_e32 v54, s58, v152
	v_fmac_f32_e32 v55, s58, v153
	v_fmac_f32_e32 v56, s58, v154
	v_fmac_f32_e32 v57, s58, v155
	v_add_f32_e32 v196, v196, v54
	v_fmac_f32_e32 v197, v54, v54
	v_add_f32_e32 v130, v130, v55
	v_fmac_f32_e32 v142, v55, v55
	v_add_f32_e32 v196, v196, v56
	v_fmac_f32_e32 v197, v56, v56
	v_add_f32_e32 v130, v130, v57
	v_fmac_f32_e32 v142, v57, v57
	s_waitcnt lgkmcnt(4)
	v_lshlrev_b32_e32 v156, 16, v186
	v_and_b32_e32 v157, 0xffff0000, v186
	v_lshlrev_b32_e32 v158, 16, v187
	v_and_b32_e32 v159, 0xffff0000, v187
	v_fmac_f32_e32 v50, s58, v156
	v_fmac_f32_e32 v51, s58, v157
	v_fmac_f32_e32 v52, s58, v158
	v_fmac_f32_e32 v53, s58, v159
	v_add_f32_e32 v196, v196, v50
	v_fmac_f32_e32 v197, v50, v50
	v_add_f32_e32 v130, v130, v51
	v_fmac_f32_e32 v142, v51, v51
	v_add_f32_e32 v196, v196, v52
	v_fmac_f32_e32 v197, v52, v52
	v_add_f32_e32 v130, v130, v53
	v_fmac_f32_e32 v142, v53, v53
	s_waitcnt lgkmcnt(3)
	v_lshlrev_b32_e32 v160, 16, v188
	v_and_b32_e32 v161, 0xffff0000, v188
	v_lshlrev_b32_e32 v162, 16, v189
	v_and_b32_e32 v163, 0xffff0000, v189
	v_fmac_f32_e32 v46, s58, v160
	v_fmac_f32_e32 v47, s58, v161
	v_fmac_f32_e32 v48, s58, v162
	v_fmac_f32_e32 v49, s58, v163
	v_add_f32_e32 v196, v196, v46
	v_fmac_f32_e32 v197, v46, v46
	v_add_f32_e32 v130, v130, v47
	v_fmac_f32_e32 v142, v47, v47
	v_add_f32_e32 v196, v196, v48
	v_fmac_f32_e32 v197, v48, v48
	v_add_f32_e32 v130, v130, v49
	v_fmac_f32_e32 v142, v49, v49
	s_waitcnt lgkmcnt(2)
	v_lshlrev_b32_e32 v164, 16, v190
	v_and_b32_e32 v165, 0xffff0000, v190
	v_lshlrev_b32_e32 v166, 16, v191
	v_and_b32_e32 v167, 0xffff0000, v191
	v_fmac_f32_e32 v42, s58, v164
	v_fmac_f32_e32 v43, s58, v165
	v_fmac_f32_e32 v44, s58, v166
	v_fmac_f32_e32 v45, s58, v167
	v_add_f32_e32 v196, v196, v42
	v_fmac_f32_e32 v197, v42, v42
	v_add_f32_e32 v130, v130, v43
	v_fmac_f32_e32 v142, v43, v43
	v_add_f32_e32 v196, v196, v44
	v_fmac_f32_e32 v197, v44, v44
	v_add_f32_e32 v130, v130, v45
	v_fmac_f32_e32 v142, v45, v45
	s_waitcnt lgkmcnt(1)
	v_lshlrev_b32_e32 v168, 16, v192
	v_and_b32_e32 v169, 0xffff0000, v192
	v_lshlrev_b32_e32 v170, 16, v193
	v_and_b32_e32 v171, 0xffff0000, v193
	v_fmac_f32_e32 v38, s58, v168
	v_fmac_f32_e32 v39, s58, v169
	v_fmac_f32_e32 v40, s58, v170
	v_fmac_f32_e32 v41, s58, v171
	v_add_f32_e32 v196, v196, v38
	v_fmac_f32_e32 v197, v38, v38
	v_add_f32_e32 v130, v130, v39
	v_fmac_f32_e32 v142, v39, v39
	v_add_f32_e32 v196, v196, v40
	v_fmac_f32_e32 v197, v40, v40
	v_add_f32_e32 v130, v130, v41
	v_fmac_f32_e32 v142, v41, v41
	s_waitcnt lgkmcnt(0)
	v_lshlrev_b32_e32 v172, 16, v194
	v_and_b32_e32 v173, 0xffff0000, v194
	v_lshlrev_b32_e32 v174, 16, v195
	v_and_b32_e32 v175, 0xffff0000, v195
	v_fmac_f32_e32 v2, s58, v172
	v_fmac_f32_e32 v3, s58, v173
	v_fmac_f32_e32 v4, s58, v174
	v_fmac_f32_e32 v5, s58, v175
	v_add_f32_e32 v196, v196, v2
	v_fmac_f32_e32 v197, v2, v2
	v_add_f32_e32 v130, v130, v3
	v_fmac_f32_e32 v142, v3, v3
	v_add_f32_e32 v196, v196, v4
	v_fmac_f32_e32 v197, v4, v4
	v_add_f32_e32 v130, v130, v5
	v_fmac_f32_e32 v142, v5, v5
	v_add_f32_e32 v196, v196, v130
	v_add_f32_e32 v197, v197, v142
	v_mov_b32_e32 v198, v196
	v_mov_b32_e32 v199, v197
	s_nop 1
	v_permlane16_swap_b32 v198, v196
	v_permlane16_swap_b32 v199, v197
	v_add_f32_e32 v196, v196, v198
	v_add_f32_e32 v197, v197, v199
	v_mov_b32_e32 v198, v196
	v_mov_b32_e32 v199, v197
	s_nop 1
	v_permlane32_swap_b32 v198, v196
	v_permlane32_swap_b32 v199, v197
	v_add_f32_e32 v196, v196, v198
	v_add_f32_e32 v197, v197, v199
	s_mov_b64 exec, 0xffff
	ds_write_b64 v134, v[196:197]
	s_mov_b64 exec, -1
	s_waitcnt lgkmcnt(0)
	s_barrier
; DI unsigned pk2(float lo, float hi) { const f32x2 v = {lo, hi}; const bf16x2_t b = __builtin_convertvector(v, bf16x2_t); return __builtin_bit_cast(unsigned, b); }
; DI size_t xb_off(int tok, int col) { return ((size_t)(((tok >> 7) * 32 + (col >> 5)) * 128 + (tok & 127))) * 32 + (col & 31); }
; DI void unit_O(const Params& p, char* lds, int l, int tile, int glu_tiles, int tile_b) {
;     ...
; #pragma unroll
;         for (int mh = 0; mh < 2; ++mh) {
;             const int mt = half * 2 + mh, rl = mh * 16 + l15, row = mt * 16 + l15;
;             float s = 0.f, ss = 0.f;
; #pragma unroll
;             for (int w = 0; w < 4; ++w) { const f32x4 v = *(const f32x4*)&red[rl * 16 + 4 * w]; s += v[0] + v[2]; ss += v[1] + v[3]; }
;             const float mu = s * (1.f / 1024.f);
;             const float var = ss * (1.f / 1024.f) - mu * mu;
;             const float rs = rsqrtf(var + LN_EPS);
;             float* orow = xo + (r0 + row) * 1024 + wid * 128 + quad * 4;
;             bf16_t* brow = xbo + xb_off((int)r0 + row, wid * 128) + quad * 4;
;             const float* gp = GB + wid * 128 + quad * 4;
; #pragma unroll
;             for (int nt = 0; nt < 8; ++nt) {
;                 const f32x4 g = *(const f32x4*)(gp + nt * 16), bb = *(const f32x4*)(gp + 1024 + nt * 16);
;                 f32x4 o;
; #pragma unroll
;                 for (int i = 0; i < 4; ++i) o[i] = (acc[mt][nt][i] - mu) * rs * g[i] + bb[i];
;                 if (l == 0) *(u32x2*)(brow + (nt >> 1) * 4096 + (nt & 1) * 16) = (u32x2){pk2(o[0], o[1]), pk2(o[2], o[3])};
;                 else *(f32x4*)(orow + nt * 16) = o;
;             }
;         }
	ds_read_b128 v[160:163], v135 offset:0
	ds_read_b128 v[164:167], v135 offset:16
	ds_read_b128 v[168:171], v135 offset:32
	ds_read_b128 v[172:175], v135 offset:48
	s_waitcnt lgkmcnt(0)
	v_add_f32_e32 v160, v160, v162
	v_add_f32_e32 v161, v161, v163
	v_add_f32_e32 v164, v164, v166
	v_add_f32_e32 v165, v165, v167
	v_add_f32_e32 v168, v168, v170
	v_add_f32_e32 v169, v169, v171
	v_add_f32_e32 v172, v172, v174
	v_add_f32_e32 v173, v173, v175
	v_add_f32_e32 v160, v160, v164
	v_add_f32_e32 v161, v161, v165
	v_add_f32_e32 v168, v168, v172
	v_add_f32_e32 v169, v169, v173
	v_add_f32_e32 v160, v160, v168
	v_add_f32_e32 v161, v161, v169
	v_mul_f32_e32 v192, 0x3a800000, v160
	v_mul_f32_e32 v193, 0x3a800000, v161
	v_fma_f32 v193, -v192, v192, v193
	v_add_f32_e32 v193, 0x3727c5ac, v193
	v_rsq_f32_e32 v193, v193
	s_nop 0
	s_add_u32 s94, s78, 0x30000
	s_addc_u32 s95, s79, 0
	ds_read_b128 v[176:179], v136
	ds_read_b128 v[180:183], v136 offset:4096
	ds_read_b128 v[184:187], v136 offset:64
	ds_read_b128 v[188:191], v136 offset:4160
	s_waitcnt lgkmcnt(2)
	v_sub_f32_e32 v62, v62, v192
	v_mul_f32_e32 v62, v62, v193
	v_fma_f32 v62, v176, v62, v180
	v_sub_f32_e32 v63, v63, v192
	v_mul_f32_e32 v63, v63, v193
	v_fma_f32 v63, v177, v63, v181
	v_sub_f32_e32 v64, v64, v192
	v_mul_f32_e32 v64, v64, v193
	v_fma_f32 v64, v178, v64, v182
	v_sub_f32_e32 v65, v65, v192
	v_mul_f32_e32 v65, v65, v193
	v_fma_f32 v65, v179, v65, v183
	global_store_dwordx4 v137, v[62:65], s[94:95]
	ds_read_b128 v[176:179], v136 offset:128
	ds_read_b128 v[180:183], v136 offset:4224
	s_waitcnt lgkmcnt(2)
	v_sub_f32_e32 v58, v58, v192
	v_mul_f32_e32 v58, v58, v193
	v_fma_f32 v58, v184, v58, v188
	v_sub_f32_e32 v59, v59, v192
	v_mul_f32_e32 v59, v59, v193
	v_fma_f32 v59, v185, v59, v189
	v_sub_f32_e32 v60, v60, v192
	v_mul_f32_e32 v60, v60, v193
	v_fma_f32 v60, v186, v60, v190
	v_sub_f32_e32 v61, v61, v192
	v_mul_f32_e32 v61, v61, v193
	v_fma_f32 v61, v187, v61, v191
	global_store_dwordx4 v137, v[58:61], s[94:95] offset:64
	ds_read_b128 v[184:187], v136 offset:192
	ds_read_b128 v[188:191], v136 offset:4288
	s_waitcnt lgkmcnt(2)
	v_sub_f32_e32 v54, v54, v192
	v_mul_f32_e32 v54, v54, v193
	v_fma_f32 v54, v176, v54, v180
	v_sub_f32_e32 v55, v55, v192
	v_mul_f32_e32 v55, v55, v193
	v_fma_f32 v55, v177, v55, v181
	v_sub_f32_e32 v56, v56, v192
	v_mul_f32_e32 v56, v56, v193
	v_fma_f32 v56, v178, v56, v182
	v_sub_f32_e32 v57, v57, v192
	v_mul_f32_e32 v57, v57, v193
	v_fma_f32 v57, v179, v57, v183
	global_store_dwordx4 v137, v[54:57], s[94:95] offset:128
	ds_read_b128 v[176:179], v136 offset:256
	ds_read_b128 v[180:183], v136 offset:4352
	s_waitcnt lgkmcnt(2)
	v_sub_f32_e32 v50, v50, v192
	v_mul_f32_e32 v50, v50, v193
	v_fma_f32 v50, v184, v50, v188
	v_sub_f32_e32 v51, v51, v192
	v_mul_f32_e32 v51, v51, v193
	v_fma_f32 v51, v185, v51, v189
	v_sub_f32_e32 v52, v52, v192
	v_mul_f32_e32 v52, v52, v193
	v_fma_f32 v52, v186, v52, v190
	v_sub_f32_e32 v53, v53, v192
	v_mul_f32_e32 v53, v53, v193
	v_fma_f32 v53, v187, v53, v191
	global_store_dwordx4 v137, v[50:53], s[94:95] offset:192
	ds_read_b128 v[184:187], v136 offset:320
	ds_read_b128 v[188:191], v136 offset:4416
	s_waitcnt lgkmcnt(2)
	v_sub_f32_e32 v46, v46, v192
	v_mul_f32_e32 v46, v46, v193
	v_fma_f32 v46, v176, v46, v180
	v_sub_f32_e32 v47, v47, v192
	v_mul_f32_e32 v47, v47, v193
	v_fma_f32 v47, v177, v47, v181
	v_sub_f32_e32 v48, v48, v192
	v_mul_f32_e32 v48, v48, v193
	v_fma_f32 v48, v178, v48, v182
	v_sub_f32_e32 v49, v49, v192
	v_mul_f32_e32 v49, v49, v193
	v_fma_f32 v49, v179, v49, v183
	global_store_dwordx4 v137, v[46:49], s[94:95] offset:256
	ds_read_b128 v[176:179], v136 offset:384
	ds_read_b128 v[180:183], v136 offset:4480
	s_waitcnt lgkmcnt(2)
	v_sub_f32_e32 v42, v42, v192
	v_mul_f32_e32 v42, v42, v193
	v_fma_f32 v42, v184, v42, v188
	v_sub_f32_e32 v43, v43, v192
	v_mul_f32_e32 v43, v43, v193
	v_fma_f32 v43, v185, v43, v189
	v_sub_f32_e32 v44, v44, v192
	v_mul_f32_e32 v44, v44, v193
	v_fma_f32 v44, v186, v44, v190
	v_sub_f32_e32 v45, v45, v192
	v_mul_f32_e32 v45, v45, v193
	v_fma_f32 v45, v187, v45, v191
	global_store_dwordx4 v137, v[42:45], s[94:95] offset:320
	ds_read_b128 v[184:187], v136 offset:448
	ds_read_b128 v[188:191], v136 offset:4544
	s_waitcnt lgkmcnt(2)
	v_sub_f32_e32 v38, v38, v192
	v_mul_f32_e32 v38, v38, v193
	v_fma_f32 v38, v176, v38, v180
	v_sub_f32_e32 v39, v39, v192
	v_mul_f32_e32 v39, v39, v193
	v_fma_f32 v39, v177, v39, v181
	v_sub_f32_e32 v40, v40, v192
	v_mul_f32_e32 v40, v40, v193
	v_fma_f32 v40, v178, v40, v182
	v_sub_f32_e32 v41, v41, v192
	v_mul_f32_e32 v41, v41, v193
	v_fma_f32 v41, v179, v41, v183
	global_store_dwordx4 v137, v[38:41], s[94:95] offset:384
	s_waitcnt lgkmcnt(0)
	v_sub_f32_e32 v2, v2, v192
	v_mul_f32_e32 v2, v2, v193
	v_fma_f32 v2, v184, v2, v188
	v_sub_f32_e32 v3, v3, v192
	v_mul_f32_e32 v3, v3, v193
	v_fma_f32 v3, v185, v3, v189
	v_sub_f32_e32 v4, v4, v192
	v_mul_f32_e32 v4, v4, v193
	v_fma_f32 v4, v186, v4, v190
	v_sub_f32_e32 v5, v5, v192
	v_mul_f32_e32 v5, v5, v193
	v_fma_f32 v5, v187, v5, v191
	global_store_dwordx4 v137, v[2:5], s[94:95] offset:448

;     ...
;     auto compute = [&](int cb, bool do_issue, int ikt, int ib) {
;         const char* base = lds + cb * BUF;
;         bf16x8 af[MT], bfr[NT];
; #pragma unroll
;         for (int nt = 0; nt < NT; ++nt) {
;             const int br = BM + (nt / NTS) * (BN / NSEG) + wc * (NTS * 16) + (nt % NTS) * 16;
;             bfr[nt] = *(const bf16x8*)(base + (br + l15) * 64 + rsw);
;         }
; #pragma unroll
;         for (int mt = 0; mt < MT; ++mt) af[mt] = *(const bf16x8*)(base + (wr * WM + mt * 16 + l15) * 64 + rsw);
;         constexpr int TOT = MT * NT, PER = (TOT + NIT - 1) / NIT;
; #pragma unroll
;         for (int part = 0; part < NIT; ++part) {
; #pragma unroll
;             for (int q = 0; q < PER; ++q) {
;                 const int idx = part * PER + q;
;                 if (idx < TOT) {
;                     const int mt = idx / NT, nt = idx % NT;
;                     acc[mt][nt] = SWAP ? mfma16(bfr[nt], af[mt], acc[mt][nt]) : mfma16(af[mt], bfr[nt], acc[mt][nt]);
;                 }
;             }
;             __builtin_amdgcn_sched_barrier(0);
;             if (do_issue) issue_one(ikt, ib, part);
;             __builtin_amdgcn_sched_barrier(0);
;         }
; DI void unit_O(const Params& p, char* lds, int l, int tile, int glu_tiles, int tile_b) {
;     ...
;     auto issue_x = [&](int half) {
;         if (l == 0) {
; #pragma unroll 1
;             for (int i = 0; i < 16; ++i) {
;                 const int pc = (wid * 16 + i + xrot) & 127, row = pc >> 2, phys = (pc & 3) * 64 + lane, logical = phys ^ (row & 15);
;                 __builtin_amdgcn_global_load_lds((const unsigned*)(xres + (r0 + half * 32 + row) * 1024 + logical * 4), (unsigned*)(XR + pc * 1024 + lane * 16), 16, 0, 0);
;             }
;         } else {
; #pragma unroll 1
;             for (int i = 0; i < 8; ++i) {
;                 const int pc = (wid * 8 + i + (xrot >> 1)) & 63, kt = pc >> 1, sub = pc & 1;
;                 __builtin_amdgcn_global_load_lds((const unsigned*)(xbres + ((size_t)kt * 128 + half * 32) * 32 + sub * 512 + lane * 8), (unsigned*)(XR + pc * 1024 + lane * 16), 16, 0, 0);
;             }
;         }
;     };
;     issue_x(0);
;     {
;         const float* gsrc = (tid < 256) ? (p.ln_g + l * 1024 + tid * 4) : (p.ln_b + l * 1024 + (tid - 256) * 4);
;         *(f32x4*)(GB + tid * 4) = *(const f32x4*)gsrc;
;     }
.Lpo2_join:
.LBB0_382:
	s_waitcnt vmcnt(0)
	v_add_u32_e32 v0, 0x11000, v140
	s_barrier
	v_lshrrev_b32_e32 v210, 6, v212
	v_and_b32_e32 v211, 63, v212
	s_nop 1
	v_readfirstlane_b32 s90, v210
	s_nop 3
	s_cmp_lg_u64 s[10:11], 0
	s_cbranch_scc1 .Le2_el1
	s_lshl_b32 s40, s48, 18
	s_lshl_b32 s91, s90, 13
	s_add_u32 s96, s52, s40
	s_addc_u32 s97, s53, 0
	s_add_u32 s96, s96, s91
	s_addc_u32 s97, s97, 0
	s_lshl_b32 s40, s90, 1
	v_xor_b32_e32 v208, s40, v211
	v_lshlrev_b32_e32 v208, 4, v208
	s_add_u32 s40, s40, 1
	v_xor_b32_e32 v209, s40, v211
	v_lshlrev_b32_e32 v209, 4, v209
	s_add_u32 s92, s96, 0x0
	s_addc_u32 s93, s97, 0
	s_add_u32 s40, s91, 0x0
	s_mov_b32 m0, s40
	s_nop 0
	global_load_lds_dwordx4 v208, s[92:93]
	global_load_lds_dwordx4 v208, s[92:93] offset:1024
	global_load_lds_dwordx4 v208, s[92:93] offset:2048
	global_load_lds_dwordx4 v208, s[92:93] offset:3072
	s_add_u32 s92, s96, 0x1000
	s_addc_u32 s93, s97, 0
	s_add_u32 s40, s91, 0x1000
	s_mov_b32 m0, s40
	s_nop 0
	global_load_lds_dwordx4 v209, s[92:93]
	global_load_lds_dwordx4 v209, s[92:93] offset:1024
	global_load_lds_dwordx4 v209, s[92:93] offset:2048
	global_load_lds_dwordx4 v209, s[92:93] offset:3072
	s_branch .Le2_ejoin
.Le2_el1:
	s_lshr_b32 s40, s48, 1
	s_lshl_b32 s40, s40, 18
	s_and_b32 s94, s48, 1
	s_lshl_b32 s94, s94, 12
	s_add_u32 s40, s40, s94
	s_lshl_b32 s91, s90, 12
	s_lshl_b32 s94, s90, 15
	s_add_u32 s96, s56, s40
	s_addc_u32 s97, s57, 0
	s_add_u32 s96, s96, s94
	s_addc_u32 s97, s97, 0
	v_lshlrev_b32_e32 v208, 4, v211
	s_add_u32 s92, s96, 0
	s_addc_u32 s93, s97, 0
	s_mov_b32 m0, s91
	s_nop 0
	global_load_lds_dwordx4 v208, s[92:93]
	s_add_u32 s92, s92, 0x2000
	s_addc_u32 s93, s93, 0
	s_add_u32 m0, m0, 0x400
	s_nop 0
	global_load_lds_dwordx4 v208, s[92:93]
	s_add_u32 s92, s92, 0x2000
	s_addc_u32 s93, s93, 0
	s_add_u32 m0, m0, 0x400
	s_nop 0
	global_load_lds_dwordx4 v208, s[92:93]
	s_add_u32 s92, s92, 0x2000
	s_addc_u32 s93, s93, 0
	s_add_u32 m0, m0, 0x400
	s_nop 0
	global_load_lds_dwordx4 v208, s[92:93]
.Le2_ejoin:
	v_add_u32_e32 v134, v0, v141
	v_add_u32_e32 v0, v0, v139
	ds_read_b128 v[130:133], v134 offset:4096
	ds_read_b128 v[138:141], v0
	ds_read_b128 v[142:145], v134 offset:5120
	ds_read_b128 v[146:149], v0 offset:1024
	ds_read_b128 v[150:153], v134 offset:6144
	ds_read_b128 v[154:157], v134 offset:7168
	ds_read_b128 v[158:161], v134 offset:8192
	ds_read_b128 v[162:165], v134 offset:9216
	ds_read_b128 v[166:169], v134 offset:10240
	ds_read_b128 v[170:173], v134 offset:11264
	ds_read_b128 v[174:177], v0 offset:2048
	ds_read_b128 v[178:181], v0 offset:3072
	s_waitcnt lgkmcnt(0)
	v_mfma_f32_16x16x32_bf16 v[98:101], v[130:133], v[138:141], v[98:101]
	v_and_b32_e32 v197, 63, v136
	v_ashrrev_i32_e32 v236, 6, v136
	v_mfma_f32_16x16x32_bf16 v[94:97], v[142:145], v[138:141], v[94:97]
	v_mfma_f32_16x16x32_bf16 v[90:93], v[150:153], v[138:141], v[90:93]
	v_mfma_f32_16x16x32_bf16 v[86:89], v[154:157], v[138:141], v[86:89]
	v_mfma_f32_16x16x32_bf16 v[82:85], v[158:161], v[138:141], v[82:85]
	v_mfma_f32_16x16x32_bf16 v[78:81], v[162:165], v[138:141], v[78:81]
	v_mfma_f32_16x16x32_bf16 v[74:77], v[166:169], v[138:141], v[74:77]
	v_mfma_f32_16x16x32_bf16 v[70:73], v[170:173], v[138:141], v[70:73]
	v_mfma_f32_16x16x32_bf16 v[126:129], v[130:133], v[146:149], v[126:129]
	v_mfma_f32_16x16x32_bf16 v[122:125], v[142:145], v[146:149], v[122:125]
	v_mfma_f32_16x16x32_bf16 v[118:121], v[150:153], v[146:149], v[118:121]
	v_mfma_f32_16x16x32_bf16 v[114:117], v[154:157], v[146:149], v[114:117]
	v_mfma_f32_16x16x32_bf16 v[110:113], v[158:161], v[146:149], v[110:113]
	v_mfma_f32_16x16x32_bf16 v[106:109], v[162:165], v[146:149], v[106:109]
	v_mfma_f32_16x16x32_bf16 v[102:105], v[166:169], v[146:149], v[102:105]
	v_mfma_f32_16x16x32_bf16 v[66:69], v[170:173], v[146:149], v[66:69]
	v_mfma_f32_16x16x32_bf16 v[34:37], v[130:133], v[174:177], v[34:37]
	v_mfma_f32_16x16x32_bf16 v[30:33], v[142:145], v[174:177], v[30:33]
	v_mfma_f32_16x16x32_bf16 v[26:29], v[150:153], v[174:177], v[26:29]
	v_mfma_f32_16x16x32_bf16 v[22:25], v[154:157], v[174:177], v[22:25]
	v_mfma_f32_16x16x32_bf16 v[18:21], v[158:161], v[174:177], v[18:21]
	v_mfma_f32_16x16x32_bf16 v[14:17], v[162:165], v[174:177], v[14:17]
	v_mfma_f32_16x16x32_bf16 v[10:13], v[166:169], v[174:177], v[10:13]
	v_mfma_f32_16x16x32_bf16 v[6:9], v[170:173], v[174:177], v[6:9]
	v_mfma_f32_16x16x32_bf16 v[62:65], v[130:133], v[178:181], v[62:65]
	v_mfma_f32_16x16x32_bf16 v[58:61], v[142:145], v[178:181], v[58:61]
	v_mfma_f32_16x16x32_bf16 v[54:57], v[150:153], v[178:181], v[54:57]
	v_mfma_f32_16x16x32_bf16 v[50:53], v[154:157], v[178:181], v[50:53]
	v_mfma_f32_16x16x32_bf16 v[46:49], v[158:161], v[178:181], v[46:49]
	v_mfma_f32_16x16x32_bf16 v[42:45], v[162:165], v[178:181], v[42:45]
	v_mfma_f32_16x16x32_bf16 v[38:41], v[166:169], v[178:181], v[38:41]
	v_mfma_f32_16x16x32_bf16 v[2:5], v[170:173], v[178:181], v[2:5]
	s_barrier
	s_not_b64 s[6:7], s[10:11]
	v_and_b32_e32 v138, 15, v212
	v_bfe_u32 v139, v212, 4, 2
	v_lshrrev_b32_e32 v140, 6, v212
	v_and_b32_e32 v141, 63, v212
	v_readfirstlane_b32 s90, v140
	v_and_b32_e32 v142, 0xff, v212
	v_lshlrev_b32_e32 v142, 4, v142
	s_cmp_lt_u32 s90, 4
	s_cselect_b32 s92, s14, s12
	s_cselect_b32 s93, s15, s13
	s_nop 3
	global_load_dwordx4 v[176:179], v142, s[92:93]
	v_lshlrev_b32_e32 v143, 4, v212
	v_add_u32_e32 v143, 0x20000, v143
	v_lshlrev_b32_e32 v134, 6, v138
	v_add_u32_e32 v135, 0x22000, v134
	v_lshl_add_u32 v134, v140, 3, v135
	v_lshlrev_b32_e32 v136, 9, v140
	v_lshl_add_u32 v136, v139, 4, v136
	v_add_u32_e32 v136, 0x20000, v136
	s_cmp_lg_u64 s[10:11], 0
	s_cbranch_scc1 .Le2_l1
; DI void unit_O(const Params& p, char* lds, int l, int tile, int glu_tiles, int tile_b) {
;     ...
;     auto issue_x = [&](int half) {
;         if (l == 0) {
; #pragma unroll 1
;             for (int i = 0; i < 16; ++i) {
;                 const int pc = (wid * 16 + i + xrot) & 127, row = pc >> 2, phys = (pc & 3) * 64 + lane, logical = phys ^ (row & 15);
;                 __builtin_amdgcn_global_load_lds((const unsigned*)(xres + (r0 + half * 32 + row) * 1024 + logical * 4), (unsigned*)(XR + pc * 1024 + lane * 16), 16, 0, 0);
;             }
;         } else {
; #pragma unroll 1
;             for (int i = 0; i < 8; ++i) {
;                 const int pc = (wid * 8 + i + (xrot >> 1)) & 63, kt = pc >> 1, sub = pc & 1;
;                 __builtin_amdgcn_global_load_lds((const unsigned*)(xbres + ((size_t)kt * 128 + half * 32) * 32 + sub * 512 + lane * 8), (unsigned*)(XR + pc * 1024 + lane * 16), 16, 0, 0);
;             }
;         }
;     };
;     issue_x(0);
;     {
;         const float* gsrc = (tid < 256) ? (p.ln_g + l * 1024 + tid * 4) : (p.ln_b + l * 1024 + (tid - 256) * 4);
;         *(f32x4*)(GB + tid * 4) = *(const f32x4*)gsrc;
;     }
;     float* xo = (l == 0) ? WS_PTR(float, OFF_X1) : p.out;
;     bf16_t* xbo = WS_PTR(bf16_t, OFF_XB1);
; #pragma unroll
;     for (int half = 0; half < 2; ++half) {
;         if (half == 0) wait_vm<0>();
;         else wait_vm<8>();
;         __syncthreads();
;         float s2[2], ss2[2];
; #pragma unroll
;         for (int mh = 0; mh < 2; ++mh) {
;             const int mt = half * 2 + mh, rl = mh * 16 + l15;
;             float s = 0.f, ss = 0.f;
; #pragma unroll
;             for (int nt = 0; nt < 8; ++nt) {
;                 f32x4 xr;
;                 if (l == 0) {
;                     const int chunk = wid * 32 + nt * 4 + quad;
;                     xr = *(const f32x4*)(XR + rl * 4096 + ((chunk ^ l15) << 4));
;                 } else {
;                     const u32x2 hb = *(const u32x2*)(XR + ((wid * 4 + (nt >> 1)) * 32 + rl) * 64 + (nt & 1) * 32 + quad * 8);
;                     xr = (f32x4){bf2f(hb[0] & 0xffffu), bf2f(hb[0] >> 16), bf2f(hb[1] & 0xffffu), bf2f(hb[1] >> 16)};
;                 }
; #pragma unroll
;                 for (int i = 0; i < 4; ++i) { const float v = acc[mt][nt][i] + DN_ALPHA * xr[i]; acc[mt][nt][i] = v; s += v; ss += v * v; }
;             }
;             s2[mh] = s; ss2[mh] = ss;
	v_lshlrev_b32_e32 v133, 12, v138
	v_lshl_add_u32 v133, v140, 9, v133
	v_add_u32_e32 v200, 0, v139
	v_xor_b32_e32 v200, v200, v138
	v_lshl_add_u32 v200, v200, 4, v133
	v_add_u32_e32 v204, 0x10000, v200
	v_add_u32_e32 v201, 4, v139
	v_xor_b32_e32 v201, v201, v138
	v_lshl_add_u32 v201, v201, 4, v133
	v_add_u32_e32 v205, 0x10000, v201
	v_add_u32_e32 v202, 8, v139
	v_xor_b32_e32 v202, v202, v138
	v_lshl_add_u32 v202, v202, 4, v133
	v_add_u32_e32 v206, 0x10000, v202
	v_add_u32_e32 v203, 12, v139
	v_xor_b32_e32 v203, v203, v138
	v_lshl_add_u32 v203, v203, 4, v133
	v_add_u32_e32 v207, 0x10000, v203
	v_and_b32_e32 v137, 1, v139
	v_lshlrev_b32_e32 v137, 5, v137
	v_lshrrev_b32_e32 v130, 1, v139
	v_lshl_or_b32 v137, v130, 4, v137
	v_lshl_or_b32 v137, v138, 6, v137
	v_lshl_or_b32 v137, v140, 15, v137
	s_lshr_b32 s40, s48, 1
	s_lshl_b32 s40, s40, 18
	s_and_b32 s46, s48, 1
	s_lshl_b32 s46, s46, 12
	s_add_u32 s40, s40, s46
	s_add_u32 s78, s56, s40
	s_addc_u32 s79, s57, 0
	s_add_u32 s92, s96, 0x10000
	s_addc_u32 s93, s97, 0
	s_add_u32 s40, s91, 0x10000
	s_mov_b32 m0, s40
	s_nop 0
	global_load_lds_dwordx4 v208, s[92:93]
	global_load_lds_dwordx4 v208, s[92:93] offset:1024
	global_load_lds_dwordx4 v208, s[92:93] offset:2048
	global_load_lds_dwordx4 v208, s[92:93] offset:3072
	s_add_u32 s92, s96, 0x11000
	s_addc_u32 s93, s97, 0
	s_add_u32 s40, s91, 0x11000
	s_mov_b32 m0, s40
	s_nop 0
	global_load_lds_dwordx4 v209, s[92:93]
	global_load_lds_dwordx4 v209, s[92:93] offset:1024
	global_load_lds_dwordx4 v209, s[92:93] offset:2048
	global_load_lds_dwordx4 v209, s[92:93] offset:3072
	s_waitcnt vmcnt(8)
	ds_write_b128 v143, v[176:179]
	s_waitcnt vmcnt(8) lgkmcnt(0)
	s_barrier
	ds_read_b128 v[144:147], v200
	ds_read_b128 v[148:151], v201
	ds_read_b128 v[152:155], v202
	ds_read_b128 v[156:159], v203
	ds_read_b128 v[160:163], v200 offset:256
	ds_read_b128 v[164:167], v201 offset:256
	ds_read_b128 v[168:171], v202 offset:256
	ds_read_b128 v[172:175], v203 offset:256
	s_waitcnt lgkmcnt(7)
	v_fmac_f32_e32 v98, s58, v144
	v_fmac_f32_e32 v99, s58, v145
	v_fmac_f32_e32 v100, s58, v146
	v_fmac_f32_e32 v101, s58, v147
	v_mov_b32_e32 v196, v98
	v_mul_f32_e32 v197, v98, v98
	v_mov_b32_e32 v130, v99
	v_mul_f32_e32 v142, v99, v99
	v_add_f32_e32 v196, v196, v100
	v_fmac_f32_e32 v197, v100, v100
	v_add_f32_e32 v130, v130, v101
	v_fmac_f32_e32 v142, v101, v101
	s_waitcnt lgkmcnt(6)
	v_fmac_f32_e32 v94, s58, v148
	v_fmac_f32_e32 v95, s58, v149
	v_fmac_f32_e32 v96, s58, v150
	v_fmac_f32_e32 v97, s58, v151
	v_add_f32_e32 v196, v196, v94
	v_fmac_f32_e32 v197, v94, v94
	v_add_f32_e32 v130, v130, v95
	v_fmac_f32_e32 v142, v95, v95
	v_add_f32_e32 v196, v196, v96
	v_fmac_f32_e32 v197, v96, v96
	v_add_f32_e32 v130, v130, v97
	v_fmac_f32_e32 v142, v97, v97
	s_waitcnt lgkmcnt(5)
	v_fmac_f32_e32 v90, s58, v152
	v_fmac_f32_e32 v91, s58, v153
	v_fmac_f32_e32 v92, s58, v154
	v_fmac_f32_e32 v93, s58, v155
	v_add_f32_e32 v196, v196, v90
	v_fmac_f32_e32 v197, v90, v90
	v_add_f32_e32 v130, v130, v91
	v_fmac_f32_e32 v142, v91, v91
	v_add_f32_e32 v196, v196, v92
	v_fmac_f32_e32 v197, v92, v92
	v_add_f32_e32 v130, v130, v93
	v_fmac_f32_e32 v142, v93, v93
	s_waitcnt lgkmcnt(4)
	v_fmac_f32_e32 v86, s58, v156
	v_fmac_f32_e32 v87, s58, v157
	v_fmac_f32_e32 v88, s58, v158
	v_fmac_f32_e32 v89, s58, v159
	v_add_f32_e32 v196, v196, v86
	v_fmac_f32_e32 v197, v86, v86
	v_add_f32_e32 v130, v130, v87
	v_fmac_f32_e32 v142, v87, v87
	v_add_f32_e32 v196, v196, v88
	v_fmac_f32_e32 v197, v88, v88
	v_add_f32_e32 v130, v130, v89
	v_fmac_f32_e32 v142, v89, v89
	s_waitcnt lgkmcnt(3)
	v_fmac_f32_e32 v82, s58, v160
	v_fmac_f32_e32 v83, s58, v161
	v_fmac_f32_e32 v84, s58, v162
	v_fmac_f32_e32 v85, s58, v163
	v_add_f32_e32 v196, v196, v82
	v_fmac_f32_e32 v197, v82, v82
	v_add_f32_e32 v130, v130, v83
	v_fmac_f32_e32 v142, v83, v83
	v_add_f32_e32 v196, v196, v84
	v_fmac_f32_e32 v197, v84, v84
	v_add_f32_e32 v130, v130, v85
	v_fmac_f32_e32 v142, v85, v85
	s_waitcnt lgkmcnt(2)
	v_fmac_f32_e32 v78, s58, v164
	v_fmac_f32_e32 v79, s58, v165
	v_fmac_f32_e32 v80, s58, v166
	v_fmac_f32_e32 v81, s58, v167
	v_add_f32_e32 v196, v196, v78
	v_fmac_f32_e32 v197, v78, v78
	v_add_f32_e32 v130, v130, v79
	v_fmac_f32_e32 v142, v79, v79
	v_add_f32_e32 v196, v196, v80
	v_fmac_f32_e32 v197, v80, v80
	v_add_f32_e32 v130, v130, v81
	v_fmac_f32_e32 v142, v81, v81
	s_waitcnt lgkmcnt(1)
	v_fmac_f32_e32 v74, s58, v168
	v_fmac_f32_e32 v75, s58, v169
	v_fmac_f32_e32 v76, s58, v170
	v_fmac_f32_e32 v77, s58, v171
	v_add_f32_e32 v196, v196, v74
	v_fmac_f32_e32 v197, v74, v74
	v_add_f32_e32 v130, v130, v75
	v_fmac_f32_e32 v142, v75, v75
	v_add_f32_e32 v196, v196, v76
	v_fmac_f32_e32 v197, v76, v76
	v_add_f32_e32 v130, v130, v77
	v_fmac_f32_e32 v142, v77, v77
	s_waitcnt lgkmcnt(0)
	v_fmac_f32_e32 v70, s58, v172
	v_fmac_f32_e32 v71, s58, v173
	v_fmac_f32_e32 v72, s58, v174
	v_fmac_f32_e32 v73, s58, v175
	v_add_f32_e32 v196, v196, v70
	v_fmac_f32_e32 v197, v70, v70
	v_add_f32_e32 v130, v130, v71
	v_fmac_f32_e32 v142, v71, v71
	v_add_f32_e32 v196, v196, v72
	v_fmac_f32_e32 v197, v72, v72
	v_add_f32_e32 v130, v130, v73
	v_fmac_f32_e32 v142, v73, v73
	v_add_f32_e32 v196, v196, v130
	v_add_f32_e32 v197, v197, v142
	v_mov_b32_e32 v198, v196
	v_mov_b32_e32 v199, v197
	s_nop 1
	v_permlane16_swap_b32 v198, v196
	v_permlane16_swap_b32 v199, v197
	v_add_f32_e32 v196, v196, v198
	v_add_f32_e32 v197, v197, v199
	v_mov_b32_e32 v198, v196
	v_mov_b32_e32 v199, v197
	s_nop 1
	v_permlane32_swap_b32 v198, v196
	v_permlane32_swap_b32 v199, v197
	v_add_f32_e32 v196, v196, v198
	v_add_f32_e32 v197, v197, v199
	s_mov_b64 exec, 0xffff
	ds_write_b64 v134, v[196:197]
	s_mov_b64 exec, -1
	s_waitcnt lgkmcnt(0)
	s_barrier
; DI unsigned pk2(float lo, float hi) { const f32x2 v = {lo, hi}; const bf16x2_t b = __builtin_convertvector(v, bf16x2_t); return __builtin_bit_cast(unsigned, b); }
; DI size_t xb_off(int tok, int col) { return ((size_t)(((tok >> 7) * 32 + (col >> 5)) * 128 + (tok & 127))) * 32 + (col & 31); }
; DI void unit_O(const Params& p, char* lds, int l, int tile, int glu_tiles, int tile_b) {
;     ...
;         if (half == 0) issue_x(1);
; #pragma unroll
;         for (int mh = 0; mh < 2; ++mh) {
;             const int mt = half * 2 + mh, rl = mh * 16 + l15, row = mt * 16 + l15;
;             float s = 0.f, ss = 0.f;
; #pragma unroll
;             for (int w = 0; w < 4; ++w) { const f32x4 v = *(const f32x4*)&red[rl * 16 + 4 * w]; s += v[0] + v[2]; ss += v[1] + v[3]; }
;             const float mu = s * (1.f / 1024.f);
;             const float var = ss * (1.f / 1024.f) - mu * mu;
;             const float rs = rsqrtf(var + LN_EPS);
;             float* orow = xo + (r0 + row) * 1024 + wid * 128 + quad * 4;
;             bf16_t* brow = xbo + xb_off((int)r0 + row, wid * 128) + quad * 4;
;             const float* gp = GB + wid * 128 + quad * 4;
; #pragma unroll
;             for (int nt = 0; nt < 8; ++nt) {
;                 const f32x4 g = *(const f32x4*)(gp + nt * 16), bb = *(const f32x4*)(gp + 1024 + nt * 16);
;                 f32x4 o;
; #pragma unroll
;                 for (int i = 0; i < 4; ++i) o[i] = (acc[mt][nt][i] - mu) * rs * g[i] + bb[i];
;                 if (l == 0) *(u32x2*)(brow + (nt >> 1) * 4096 + (nt & 1) * 16) = (u32x2){pk2(o[0], o[1]), pk2(o[2], o[3])};
;                 else *(f32x4*)(orow + nt * 16) = o;
;             }
;         }
	s_add_u32 s92, s96, 0x20000
	s_addc_u32 s93, s97, 0
	s_add_u32 s40, s91, 0x0
	s_mov_b32 m0, s40
	s_nop 0
	global_load_lds_dwordx4 v208, s[92:93]
	global_load_lds_dwordx4 v208, s[92:93] offset:1024
	global_load_lds_dwordx4 v208, s[92:93] offset:2048
	global_load_lds_dwordx4 v208, s[92:93] offset:3072
	s_add_u32 s92, s96, 0x21000
	s_addc_u32 s93, s97, 0
	s_add_u32 s40, s91, 0x1000
	s_mov_b32 m0, s40
	s_nop 0
	global_load_lds_dwordx4 v209, s[92:93]
	global_load_lds_dwordx4 v209, s[92:93] offset:1024
	global_load_lds_dwordx4 v209, s[92:93] offset:2048
	global_load_lds_dwordx4 v209, s[92:93] offset:3072
	ds_read_b128 v[160:163], v135 offset:0
	ds_read_b128 v[164:167], v135 offset:16
	ds_read_b128 v[168:171], v135 offset:32
	ds_read_b128 v[172:175], v135 offset:48
	s_waitcnt lgkmcnt(0)
	v_add_f32_e32 v160, v160, v162
	v_add_f32_e32 v161, v161, v163
	v_add_f32_e32 v164, v164, v166
	v_add_f32_e32 v165, v165, v167
	v_add_f32_e32 v168, v168, v170
	v_add_f32_e32 v169, v169, v171
	v_add_f32_e32 v172, v172, v174
	v_add_f32_e32 v173, v173, v175
	v_add_f32_e32 v160, v160, v164
	v_add_f32_e32 v161, v161, v165
	v_add_f32_e32 v168, v168, v172
	v_add_f32_e32 v169, v169, v173
	v_add_f32_e32 v160, v160, v168
	v_add_f32_e32 v161, v161, v169
	v_mul_f32_e32 v192, 0x3a800000, v160
	v_mul_f32_e32 v193, 0x3a800000, v161
	v_fma_f32 v193, -v192, v192, v193
	v_add_f32_e32 v193, 0x3727c5ac, v193
	v_rsq_f32_e32 v193, v193
	s_nop 0
	s_add_u32 s94, s78, 0x0
	s_addc_u32 s95, s79, 0
	ds_read_b128 v[176:179], v136
	ds_read_b128 v[180:183], v136 offset:4096
	ds_read_b128 v[184:187], v136 offset:64
	ds_read_b128 v[188:191], v136 offset:4160
	s_waitcnt lgkmcnt(2)
	v_sub_f32_e32 v98, v98, v192
	v_mul_f32_e32 v98, v98, v193
	v_fma_f32 v98, v176, v98, v180
	v_sub_f32_e32 v99, v99, v192
	v_mul_f32_e32 v99, v99, v193
	v_fma_f32 v99, v177, v99, v181
	v_sub_f32_e32 v100, v100, v192
	v_mul_f32_e32 v100, v100, v193
	v_fma_f32 v100, v178, v100, v182
	v_sub_f32_e32 v101, v101, v192
	v_mul_f32_e32 v101, v101, v193
	v_fma_f32 v101, v179, v101, v183
	v_cvt_pk_bf16_f32 v144, v98, v99
	v_cvt_pk_bf16_f32 v145, v100, v101
	ds_read_b128 v[176:179], v136 offset:128
	ds_read_b128 v[180:183], v136 offset:4224
	s_waitcnt lgkmcnt(2)
	v_sub_f32_e32 v94, v94, v192
	v_mul_f32_e32 v94, v94, v193
	v_fma_f32 v94, v184, v94, v188
	v_sub_f32_e32 v95, v95, v192
	v_mul_f32_e32 v95, v95, v193
	v_fma_f32 v95, v185, v95, v189
	v_sub_f32_e32 v96, v96, v192
	v_mul_f32_e32 v96, v96, v193
	v_fma_f32 v96, v186, v96, v190
	v_sub_f32_e32 v97, v97, v192
	v_mul_f32_e32 v97, v97, v193
	v_fma_f32 v97, v187, v97, v191
	v_cvt_pk_bf16_f32 v146, v94, v95
	v_cvt_pk_bf16_f32 v147, v96, v97
	s_nop 1
	v_permlane16_swap_b32 v144, v146
	v_permlane16_swap_b32 v145, v147
	global_store_dwordx4 v137, v[144:147], s[94:95] sc1
	s_add_u32 s94, s94, 0x2000
	s_addc_u32 s95, s95, 0
	ds_read_b128 v[184:187], v136 offset:192
	ds_read_b128 v[188:191], v136 offset:4288
	s_waitcnt lgkmcnt(2)
	v_sub_f32_e32 v90, v90, v192
	v_mul_f32_e32 v90, v90, v193
	v_fma_f32 v90, v176, v90, v180
	v_sub_f32_e32 v91, v91, v192
	v_mul_f32_e32 v91, v91, v193
	v_fma_f32 v91, v177, v91, v181
	v_sub_f32_e32 v92, v92, v192
	v_mul_f32_e32 v92, v92, v193
	v_fma_f32 v92, v178, v92, v182
	v_sub_f32_e32 v93, v93, v192
	v_mul_f32_e32 v93, v93, v193
	v_fma_f32 v93, v179, v93, v183
	v_cvt_pk_bf16_f32 v152, v90, v91
	v_cvt_pk_bf16_f32 v153, v92, v93
	ds_read_b128 v[176:179], v136 offset:256
	ds_read_b128 v[180:183], v136 offset:4352
	s_waitcnt lgkmcnt(2)
	v_sub_f32_e32 v86, v86, v192
	v_mul_f32_e32 v86, v86, v193
	v_fma_f32 v86, v184, v86, v188
	v_sub_f32_e32 v87, v87, v192
	v_mul_f32_e32 v87, v87, v193
	v_fma_f32 v87, v185, v87, v189
	v_sub_f32_e32 v88, v88, v192
	v_mul_f32_e32 v88, v88, v193
	v_fma_f32 v88, v186, v88, v190
	v_sub_f32_e32 v89, v89, v192
	v_mul_f32_e32 v89, v89, v193
	v_fma_f32 v89, v187, v89, v191
	v_cvt_pk_bf16_f32 v154, v86, v87
	v_cvt_pk_bf16_f32 v155, v88, v89
	s_nop 1
	v_permlane16_swap_b32 v152, v154
	v_permlane16_swap_b32 v153, v155
	global_store_dwordx4 v137, v[152:155], s[94:95] sc1
	s_add_u32 s94, s94, 0x2000
	s_addc_u32 s95, s95, 0
	ds_read_b128 v[184:187], v136 offset:320
	ds_read_b128 v[188:191], v136 offset:4416
	s_waitcnt lgkmcnt(2)
	v_sub_f32_e32 v82, v82, v192
	v_mul_f32_e32 v82, v82, v193
	v_fma_f32 v82, v176, v82, v180
	v_sub_f32_e32 v83, v83, v192
	v_mul_f32_e32 v83, v83, v193
	v_fma_f32 v83, v177, v83, v181
	v_sub_f32_e32 v84, v84, v192
	v_mul_f32_e32 v84, v84, v193
	v_fma_f32 v84, v178, v84, v182
	v_sub_f32_e32 v85, v85, v192
	v_mul_f32_e32 v85, v85, v193
	v_fma_f32 v85, v179, v85, v183
	v_cvt_pk_bf16_f32 v144, v82, v83
	v_cvt_pk_bf16_f32 v145, v84, v85
	ds_read_b128 v[176:179], v136 offset:384
	ds_read_b128 v[180:183], v136 offset:4480
	s_waitcnt lgkmcnt(2)
	v_sub_f32_e32 v78, v78, v192
	v_mul_f32_e32 v78, v78, v193
	v_fma_f32 v78, v184, v78, v188
	v_sub_f32_e32 v79, v79, v192
	v_mul_f32_e32 v79, v79, v193
	v_fma_f32 v79, v185, v79, v189
	v_sub_f32_e32 v80, v80, v192
	v_mul_f32_e32 v80, v80, v193
	v_fma_f32 v80, v186, v80, v190
	v_sub_f32_e32 v81, v81, v192
	v_mul_f32_e32 v81, v81, v193
	v_fma_f32 v81, v187, v81, v191
	v_cvt_pk_bf16_f32 v146, v78, v79
	v_cvt_pk_bf16_f32 v147, v80, v81
	s_nop 1
	v_permlane16_swap_b32 v144, v146
	v_permlane16_swap_b32 v145, v147
	global_store_dwordx4 v137, v[144:147], s[94:95] sc1
	s_add_u32 s94, s94, 0x2000
	s_addc_u32 s95, s95, 0
	ds_read_b128 v[184:187], v136 offset:448
	ds_read_b128 v[188:191], v136 offset:4544
	s_waitcnt lgkmcnt(2)
	v_sub_f32_e32 v74, v74, v192
	v_mul_f32_e32 v74, v74, v193
	v_fma_f32 v74, v176, v74, v180
	v_sub_f32_e32 v75, v75, v192
	v_mul_f32_e32 v75, v75, v193
	v_fma_f32 v75, v177, v75, v181
	v_sub_f32_e32 v76, v76, v192
	v_mul_f32_e32 v76, v76, v193
	v_fma_f32 v76, v178, v76, v182
	v_sub_f32_e32 v77, v77, v192
	v_mul_f32_e32 v77, v77, v193
	v_fma_f32 v77, v179, v77, v183
	v_cvt_pk_bf16_f32 v152, v74, v75
	v_cvt_pk_bf16_f32 v153, v76, v77
	s_waitcnt lgkmcnt(0)
	v_sub_f32_e32 v70, v70, v192
	v_mul_f32_e32 v70, v70, v193
	v_fma_f32 v70, v184, v70, v188
	v_sub_f32_e32 v71, v71, v192
	v_mul_f32_e32 v71, v71, v193
	v_fma_f32 v71, v185, v71, v189
	v_sub_f32_e32 v72, v72, v192
	v_mul_f32_e32 v72, v72, v193
	v_fma_f32 v72, v186, v72, v190
	v_sub_f32_e32 v73, v73, v192
	v_mul_f32_e32 v73, v73, v193
	v_fma_f32 v73, v187, v73, v191
	v_cvt_pk_bf16_f32 v154, v70, v71
	v_cvt_pk_bf16_f32 v155, v72, v73
	s_nop 1
	v_permlane16_swap_b32 v152, v154
	v_permlane16_swap_b32 v153, v155
	global_store_dwordx4 v137, v[152:155], s[94:95] sc1
	s_waitcnt vmcnt(12) lgkmcnt(0)
	s_barrier
; DI float bf2f(unsigned b) { return __uint_as_float(b << 16); }
; DI void unit_O(const Params& p, char* lds, int l, int tile, int glu_tiles, int tile_b) {
;     ...
;         float s2[2], ss2[2];
; #pragma unroll
;         for (int mh = 0; mh < 2; ++mh) {
;             const int mt = half * 2 + mh, rl = mh * 16 + l15;
;             float s = 0.f, ss = 0.f;
; #pragma unroll
;             for (int nt = 0; nt < 8; ++nt) {
;                 f32x4 xr;
;                 if (l == 0) {
;                     const int chunk = wid * 32 + nt * 4 + quad;
;                     xr = *(const f32x4*)(XR + rl * 4096 + ((chunk ^ l15) << 4));
;                 } else {
;                     const u32x2 hb = *(const u32x2*)(XR + ((wid * 4 + (nt >> 1)) * 32 + rl) * 64 + (nt & 1) * 32 + quad * 8);
;                     xr = (f32x4){bf2f(hb[0] & 0xffffu), bf2f(hb[0] >> 16), bf2f(hb[1] & 0xffffu), bf2f(hb[1] >> 16)};
;                 }
; #pragma unroll
;                 for (int i = 0; i < 4; ++i) { const float v = acc[mt][nt][i] + DN_ALPHA * xr[i]; acc[mt][nt][i] = v; s += v; ss += v * v; }
;             }
;             s2[mh] = s; ss2[mh] = ss;
;         }
; #pragma unroll
;         for (int mh = 0; mh < 2; ++mh) { s2[mh] += __shfl_xor(s2[mh], 16); ss2[mh] += __shfl_xor(ss2[mh], 16); }
; #pragma unroll
;         for (int mh = 0; mh < 2; ++mh) { s2[mh] += __shfl_xor(s2[mh], 32); ss2[mh] += __shfl_xor(ss2[mh], 32); }
;         if (quad == 0) {
; #pragma unroll
;             for (int mh = 0; mh < 2; ++mh) *(f32x2*)&red[((mh * 16 + l15) * 8 + wid) * 2] = (f32x2){s2[mh], ss2[mh]};
;         }
;         __syncthreads();
;         if (half == 0) issue_x(1);
; #pragma unroll
;         for (int mh = 0; mh < 2; ++mh) {
;             const int mt = half * 2 + mh, rl = mh * 16 + l15, row = mt * 16 + l15;
;             float s = 0.f, ss = 0.f;
; #pragma unroll
;             for (int w = 0; w < 4; ++w) { const f32x4 v = *(const f32x4*)&red[rl * 16 + 4 * w]; s += v[0] + v[2]; ss += v[1] + v[3]; }
;             const float mu = s * (1.f / 1024.f);
;             const float var = ss * (1.f / 1024.f) - mu * mu;
;             const float rs = rsqrtf(var + LN_EPS);
;             float* orow = xo + (r0 + row) * 1024 + wid * 128 + quad * 4;
	ds_read_b128 v[144:147], v204
	ds_read_b128 v[148:151], v205
	ds_read_b128 v[152:155], v206
	ds_read_b128 v[156:159], v207
	ds_read_b128 v[160:163], v204 offset:256
	ds_read_b128 v[164:167], v205 offset:256
	ds_read_b128 v[168:171], v206 offset:256
	ds_read_b128 v[172:175], v207 offset:256
	s_waitcnt lgkmcnt(7)
	v_fmac_f32_e32 v126, s58, v144
	v_fmac_f32_e32 v127, s58, v145
	v_fmac_f32_e32 v128, s58, v146
	v_fmac_f32_e32 v129, s58, v147
	v_mov_b32_e32 v196, v126
	v_mul_f32_e32 v197, v126, v126
	v_mov_b32_e32 v130, v127
	v_mul_f32_e32 v142, v127, v127
	v_add_f32_e32 v196, v196, v128
	v_fmac_f32_e32 v197, v128, v128
	v_add_f32_e32 v130, v130, v129
	v_fmac_f32_e32 v142, v129, v129
	s_waitcnt lgkmcnt(6)
	v_fmac_f32_e32 v122, s58, v148
	v_fmac_f32_e32 v123, s58, v149
	v_fmac_f32_e32 v124, s58, v150
	v_fmac_f32_e32 v125, s58, v151
	v_add_f32_e32 v196, v196, v122
	v_fmac_f32_e32 v197, v122, v122
	v_add_f32_e32 v130, v130, v123
	v_fmac_f32_e32 v142, v123, v123
	v_add_f32_e32 v196, v196, v124
	v_fmac_f32_e32 v197, v124, v124
	v_add_f32_e32 v130, v130, v125
	v_fmac_f32_e32 v142, v125, v125
	s_waitcnt lgkmcnt(5)
	v_fmac_f32_e32 v118, s58, v152
	v_fmac_f32_e32 v119, s58, v153
	v_fmac_f32_e32 v120, s58, v154
	v_fmac_f32_e32 v121, s58, v155
	v_add_f32_e32 v196, v196, v118
	v_fmac_f32_e32 v197, v118, v118
	v_add_f32_e32 v130, v130, v119
	v_fmac_f32_e32 v142, v119, v119
	v_add_f32_e32 v196, v196, v120
	v_fmac_f32_e32 v197, v120, v120
	v_add_f32_e32 v130, v130, v121
	v_fmac_f32_e32 v142, v121, v121
	s_waitcnt lgkmcnt(4)
	v_fmac_f32_e32 v114, s58, v156
	v_fmac_f32_e32 v115, s58, v157
	v_fmac_f32_e32 v116, s58, v158
	v_fmac_f32_e32 v117, s58, v159
	v_add_f32_e32 v196, v196, v114
	v_fmac_f32_e32 v197, v114, v114
	v_add_f32_e32 v130, v130, v115
	v_fmac_f32_e32 v142, v115, v115
	v_add_f32_e32 v196, v196, v116
	v_fmac_f32_e32 v197, v116, v116
	v_add_f32_e32 v130, v130, v117
	v_fmac_f32_e32 v142, v117, v117
	s_waitcnt lgkmcnt(3)
	v_fmac_f32_e32 v110, s58, v160
	v_fmac_f32_e32 v111, s58, v161
	v_fmac_f32_e32 v112, s58, v162
	v_fmac_f32_e32 v113, s58, v163
	v_add_f32_e32 v196, v196, v110
	v_fmac_f32_e32 v197, v110, v110
	v_add_f32_e32 v130, v130, v111
	v_fmac_f32_e32 v142, v111, v111
	v_add_f32_e32 v196, v196, v112
	v_fmac_f32_e32 v197, v112, v112
	v_add_f32_e32 v130, v130, v113
	v_fmac_f32_e32 v142, v113, v113
	s_waitcnt lgkmcnt(2)
	v_fmac_f32_e32 v106, s58, v164
	v_fmac_f32_e32 v107, s58, v165
	v_fmac_f32_e32 v108, s58, v166
	v_fmac_f32_e32 v109, s58, v167
	v_add_f32_e32 v196, v196, v106
	v_fmac_f32_e32 v197, v106, v106
	v_add_f32_e32 v130, v130, v107
	v_fmac_f32_e32 v142, v107, v107
	v_add_f32_e32 v196, v196, v108
	v_fmac_f32_e32 v197, v108, v108
	v_add_f32_e32 v130, v130, v109
	v_fmac_f32_e32 v142, v109, v109
	s_waitcnt lgkmcnt(1)
	v_fmac_f32_e32 v102, s58, v168
	v_fmac_f32_e32 v103, s58, v169
	v_fmac_f32_e32 v104, s58, v170
	v_fmac_f32_e32 v105, s58, v171
	v_add_f32_e32 v196, v196, v102
	v_fmac_f32_e32 v197, v102, v102
	v_add_f32_e32 v130, v130, v103
	v_fmac_f32_e32 v142, v103, v103
	v_add_f32_e32 v196, v196, v104
	v_fmac_f32_e32 v197, v104, v104
	v_add_f32_e32 v130, v130, v105
	v_fmac_f32_e32 v142, v105, v105
	s_waitcnt lgkmcnt(0)
	v_fmac_f32_e32 v66, s58, v172
	v_fmac_f32_e32 v67, s58, v173
	v_fmac_f32_e32 v68, s58, v174
	v_fmac_f32_e32 v69, s58, v175
	v_add_f32_e32 v196, v196, v66
	v_fmac_f32_e32 v197, v66, v66
	v_add_f32_e32 v130, v130, v67
	v_fmac_f32_e32 v142, v67, v67
	v_add_f32_e32 v196, v196, v68
	v_fmac_f32_e32 v197, v68, v68
	v_add_f32_e32 v130, v130, v69
	v_fmac_f32_e32 v142, v69, v69
	v_add_f32_e32 v196, v196, v130
	v_add_f32_e32 v197, v197, v142
	v_mov_b32_e32 v198, v196
	v_mov_b32_e32 v199, v197
	s_nop 1
	v_permlane16_swap_b32 v198, v196
	v_permlane16_swap_b32 v199, v197
	v_add_f32_e32 v196, v196, v198
	v_add_f32_e32 v197, v197, v199
	v_mov_b32_e32 v198, v196
	v_mov_b32_e32 v199, v197
	s_nop 1
	v_permlane32_swap_b32 v198, v196
	v_permlane32_swap_b32 v199, v197
	v_add_f32_e32 v196, v196, v198
	v_add_f32_e32 v197, v197, v199
	s_mov_b64 exec, 0xffff
	ds_write_b64 v134, v[196:197]
	s_mov_b64 exec, -1
	s_waitcnt lgkmcnt(0)
	s_barrier
	s_add_u32 s92, s96, 0x30000
	s_addc_u32 s93, s97, 0
	s_add_u32 s40, s91, 0x10000
	s_mov_b32 m0, s40
	s_nop 0
	global_load_lds_dwordx4 v208, s[92:93]
	global_load_lds_dwordx4 v208, s[92:93] offset:1024
	global_load_lds_dwordx4 v208, s[92:93] offset:2048
	global_load_lds_dwordx4 v208, s[92:93] offset:3072
	s_add_u32 s92, s96, 0x31000
	s_addc_u32 s93, s97, 0
	s_add_u32 s40, s91, 0x11000
	s_mov_b32 m0, s40
	s_nop 0
	global_load_lds_dwordx4 v209, s[92:93]
	global_load_lds_dwordx4 v209, s[92:93] offset:1024
	global_load_lds_dwordx4 v209, s[92:93] offset:2048
	global_load_lds_dwordx4 v209, s[92:93] offset:3072
	ds_read_b128 v[160:163], v135 offset:0
	ds_read_b128 v[164:167], v135 offset:16
	ds_read_b128 v[168:171], v135 offset:32
	ds_read_b128 v[172:175], v135 offset:48
	s_waitcnt lgkmcnt(0)
	v_add_f32_e32 v160, v160, v162
	v_add_f32_e32 v161, v161, v163
	v_add_f32_e32 v164, v164, v166
	v_add_f32_e32 v165, v165, v167
	v_add_f32_e32 v168, v168, v170
	v_add_f32_e32 v169, v169, v171
	v_add_f32_e32 v172, v172, v174
	v_add_f32_e32 v173, v173, v175
	v_add_f32_e32 v160, v160, v164
	v_add_f32_e32 v161, v161, v165
	v_add_f32_e32 v168, v168, v172
	v_add_f32_e32 v169, v169, v173
	v_add_f32_e32 v160, v160, v168
	v_add_f32_e32 v161, v161, v169
	v_mul_f32_e32 v192, 0x3a800000, v160
	v_mul_f32_e32 v193, 0x3a800000, v161
	v_fma_f32 v193, -v192, v192, v193
	v_add_f32_e32 v193, 0x3727c5ac, v193
	v_rsq_f32_e32 v193, v193
	s_nop 0
	s_add_u32 s94, s78, 0x400
	s_addc_u32 s95, s79, 0
	ds_read_b128 v[176:179], v136
	ds_read_b128 v[180:183], v136 offset:4096
	ds_read_b128 v[184:187], v136 offset:64
	ds_read_b128 v[188:191], v136 offset:4160
	s_waitcnt lgkmcnt(2)
; DI unsigned pk2(float lo, float hi) { const f32x2 v = {lo, hi}; const bf16x2_t b = __builtin_convertvector(v, bf16x2_t); return __builtin_bit_cast(unsigned, b); }
; DI size_t xb_off(int tok, int col) { return ((size_t)(((tok >> 7) * 32 + (col >> 5)) * 128 + (tok & 127))) * 32 + (col & 31); }
; DI void unit_O(const Params& p, char* lds, int l, int tile, int glu_tiles, int tile_b) {
;     ...
;             float* orow = xo + (r0 + row) * 1024 + wid * 128 + quad * 4;
;             bf16_t* brow = xbo + xb_off((int)r0 + row, wid * 128) + quad * 4;
;             const float* gp = GB + wid * 128 + quad * 4;
; #pragma unroll
;             for (int nt = 0; nt < 8; ++nt) {
;                 const f32x4 g = *(const f32x4*)(gp + nt * 16), bb = *(const f32x4*)(gp + 1024 + nt * 16);
;                 f32x4 o;
; #pragma unroll
;                 for (int i = 0; i < 4; ++i) o[i] = (acc[mt][nt][i] - mu) * rs * g[i] + bb[i];
;                 if (l == 0) *(u32x2*)(brow + (nt >> 1) * 4096 + (nt & 1) * 16) = (u32x2){pk2(o[0], o[1]), pk2(o[2], o[3])};
;                 else *(f32x4*)(orow + nt * 16) = o;
;             }
;         }
	v_sub_f32_e32 v126, v126, v192
	v_mul_f32_e32 v126, v126, v193
	v_fma_f32 v126, v176, v126, v180
	v_sub_f32_e32 v127, v127, v192
	v_mul_f32_e32 v127, v127, v193
	v_fma_f32 v127, v177, v127, v181
	v_sub_f32_e32 v128, v128, v192
	v_mul_f32_e32 v128, v128, v193
	v_fma_f32 v128, v178, v128, v182
	v_sub_f32_e32 v129, v129, v192
	v_mul_f32_e32 v129, v129, v193
	v_fma_f32 v129, v179, v129, v183
	v_cvt_pk_bf16_f32 v144, v126, v127
	v_cvt_pk_bf16_f32 v145, v128, v129
	ds_read_b128 v[176:179], v136 offset:128
	ds_read_b128 v[180:183], v136 offset:4224
	s_waitcnt lgkmcnt(2)
	v_sub_f32_e32 v122, v122, v192
	v_mul_f32_e32 v122, v122, v193
	v_fma_f32 v122, v184, v122, v188
	v_sub_f32_e32 v123, v123, v192
	v_mul_f32_e32 v123, v123, v193
	v_fma_f32 v123, v185, v123, v189
	v_sub_f32_e32 v124, v124, v192
	v_mul_f32_e32 v124, v124, v193
	v_fma_f32 v124, v186, v124, v190
	v_sub_f32_e32 v125, v125, v192
	v_mul_f32_e32 v125, v125, v193
	v_fma_f32 v125, v187, v125, v191
	v_cvt_pk_bf16_f32 v146, v122, v123
	v_cvt_pk_bf16_f32 v147, v124, v125
	s_nop 1
	v_permlane16_swap_b32 v144, v146
	v_permlane16_swap_b32 v145, v147
	global_store_dwordx4 v137, v[144:147], s[94:95] sc1
	s_add_u32 s94, s94, 0x2000
	s_addc_u32 s95, s95, 0
	ds_read_b128 v[184:187], v136 offset:192
	ds_read_b128 v[188:191], v136 offset:4288
	s_waitcnt lgkmcnt(2)
	v_sub_f32_e32 v118, v118, v192
	v_mul_f32_e32 v118, v118, v193
	v_fma_f32 v118, v176, v118, v180
	v_sub_f32_e32 v119, v119, v192
	v_mul_f32_e32 v119, v119, v193
	v_fma_f32 v119, v177, v119, v181
	v_sub_f32_e32 v120, v120, v192
	v_mul_f32_e32 v120, v120, v193
	v_fma_f32 v120, v178, v120, v182
	v_sub_f32_e32 v121, v121, v192
	v_mul_f32_e32 v121, v121, v193
	v_fma_f32 v121, v179, v121, v183
	v_cvt_pk_bf16_f32 v152, v118, v119
	v_cvt_pk_bf16_f32 v153, v120, v121
	ds_read_b128 v[176:179], v136 offset:256
	ds_read_b128 v[180:183], v136 offset:4352
	s_waitcnt lgkmcnt(2)
	v_sub_f32_e32 v114, v114, v192
	v_mul_f32_e32 v114, v114, v193
	v_fma_f32 v114, v184, v114, v188
	v_sub_f32_e32 v115, v115, v192
	v_mul_f32_e32 v115, v115, v193
	v_fma_f32 v115, v185, v115, v189
	v_sub_f32_e32 v116, v116, v192
	v_mul_f32_e32 v116, v116, v193
	v_fma_f32 v116, v186, v116, v190
	v_sub_f32_e32 v117, v117, v192
	v_mul_f32_e32 v117, v117, v193
	v_fma_f32 v117, v187, v117, v191
	v_cvt_pk_bf16_f32 v154, v114, v115
	v_cvt_pk_bf16_f32 v155, v116, v117
	s_nop 1
	v_permlane16_swap_b32 v152, v154
	v_permlane16_swap_b32 v153, v155
	global_store_dwordx4 v137, v[152:155], s[94:95] sc1
	s_add_u32 s94, s94, 0x2000
	s_addc_u32 s95, s95, 0
	ds_read_b128 v[184:187], v136 offset:320
	ds_read_b128 v[188:191], v136 offset:4416
	s_waitcnt lgkmcnt(2)
	v_sub_f32_e32 v110, v110, v192
	v_mul_f32_e32 v110, v110, v193
	v_fma_f32 v110, v176, v110, v180
	v_sub_f32_e32 v111, v111, v192
	v_mul_f32_e32 v111, v111, v193
	v_fma_f32 v111, v177, v111, v181
	v_sub_f32_e32 v112, v112, v192
	v_mul_f32_e32 v112, v112, v193
	v_fma_f32 v112, v178, v112, v182
	v_sub_f32_e32 v113, v113, v192
	v_mul_f32_e32 v113, v113, v193
	v_fma_f32 v113, v179, v113, v183
	v_cvt_pk_bf16_f32 v144, v110, v111
	v_cvt_pk_bf16_f32 v145, v112, v113
	ds_read_b128 v[176:179], v136 offset:384
	ds_read_b128 v[180:183], v136 offset:4480
	s_waitcnt lgkmcnt(2)
	v_sub_f32_e32 v106, v106, v192
	v_mul_f32_e32 v106, v106, v193
	v_fma_f32 v106, v184, v106, v188
	v_sub_f32_e32 v107, v107, v192
	v_mul_f32_e32 v107, v107, v193
	v_fma_f32 v107, v185, v107, v189
	v_sub_f32_e32 v108, v108, v192
	v_mul_f32_e32 v108, v108, v193
	v_fma_f32 v108, v186, v108, v190
	v_sub_f32_e32 v109, v109, v192
	v_mul_f32_e32 v109, v109, v193
	v_fma_f32 v109, v187, v109, v191
	v_cvt_pk_bf16_f32 v146, v106, v107
	v_cvt_pk_bf16_f32 v147, v108, v109
	s_nop 1
	v_permlane16_swap_b32 v144, v146
	v_permlane16_swap_b32 v145, v147
	global_store_dwordx4 v137, v[144:147], s[94:95] sc1
	s_add_u32 s94, s94, 0x2000
	s_addc_u32 s95, s95, 0
	ds_read_b128 v[184:187], v136 offset:448
	ds_read_b128 v[188:191], v136 offset:4544
	s_waitcnt lgkmcnt(2)
	v_sub_f32_e32 v102, v102, v192
	v_mul_f32_e32 v102, v102, v193
	v_fma_f32 v102, v176, v102, v180
	v_sub_f32_e32 v103, v103, v192
	v_mul_f32_e32 v103, v103, v193
	v_fma_f32 v103, v177, v103, v181
	v_sub_f32_e32 v104, v104, v192
	v_mul_f32_e32 v104, v104, v193
	v_fma_f32 v104, v178, v104, v182
	v_sub_f32_e32 v105, v105, v192
	v_mul_f32_e32 v105, v105, v193
	v_fma_f32 v105, v179, v105, v183
	v_cvt_pk_bf16_f32 v152, v102, v103
	v_cvt_pk_bf16_f32 v153, v104, v105
	s_waitcnt lgkmcnt(0)
	v_sub_f32_e32 v66, v66, v192
	v_mul_f32_e32 v66, v66, v193
	v_fma_f32 v66, v184, v66, v188
	v_sub_f32_e32 v67, v67, v192
	v_mul_f32_e32 v67, v67, v193
	v_fma_f32 v67, v185, v67, v189
	v_sub_f32_e32 v68, v68, v192
	v_mul_f32_e32 v68, v68, v193
	v_fma_f32 v68, v186, v68, v190
	v_sub_f32_e32 v69, v69, v192
	v_mul_f32_e32 v69, v69, v193
	v_fma_f32 v69, v187, v69, v191
	v_cvt_pk_bf16_f32 v154, v66, v67
	v_cvt_pk_bf16_f32 v155, v68, v69
	s_nop 1
	v_permlane16_swap_b32 v152, v154
	v_permlane16_swap_b32 v153, v155
	global_store_dwordx4 v137, v[152:155], s[94:95] sc1
	s_waitcnt vmcnt(16) lgkmcnt(0)
	s_barrier
; DI void unit_O(const Params& p, char* lds, int l, int tile, int glu_tiles, int tile_b) {
;     ...
;         float s2[2], ss2[2];
; #pragma unroll
;         for (int mh = 0; mh < 2; ++mh) {
;             const int mt = half * 2 + mh, rl = mh * 16 + l15;
;             float s = 0.f, ss = 0.f;
; #pragma unroll
;             for (int nt = 0; nt < 8; ++nt) {
;                 f32x4 xr;
;                 if (l == 0) {
;                     const int chunk = wid * 32 + nt * 4 + quad;
;                     xr = *(const f32x4*)(XR + rl * 4096 + ((chunk ^ l15) << 4));
;                 } else {
;                     const u32x2 hb = *(const u32x2*)(XR + ((wid * 4 + (nt >> 1)) * 32 + rl) * 64 + (nt & 1) * 32 + quad * 8);
;                     xr = (f32x4){bf2f(hb[0] & 0xffffu), bf2f(hb[0] >> 16), bf2f(hb[1] & 0xffffu), bf2f(hb[1] >> 16)};
;                 }
; #pragma unroll
;                 for (int i = 0; i < 4; ++i) { const float v = acc[mt][nt][i] + DN_ALPHA * xr[i]; acc[mt][nt][i] = v; s += v; ss += v * v; }
;             }
;             s2[mh] = s; ss2[mh] = ss;
;         }
; #pragma unroll
;         for (int mh = 0; mh < 2; ++mh) { s2[mh] += __shfl_xor(s2[mh], 16); ss2[mh] += __shfl_xor(ss2[mh], 16); }
; #pragma unroll
;         for (int mh = 0; mh < 2; ++mh) { s2[mh] += __shfl_xor(s2[mh], 32); ss2[mh] += __shfl_xor(ss2[mh], 32); }
;         if (quad == 0) {
; #pragma unroll
;             for (int mh = 0; mh < 2; ++mh) *(f32x2*)&red[((mh * 16 + l15) * 8 + wid) * 2] = (f32x2){s2[mh], ss2[mh]};
;         }
;         __syncthreads();
;         if (half == 0) issue_x(1);
; #pragma unroll
;         for (int mh = 0; mh < 2; ++mh) {
;             const int mt = half * 2 + mh, rl = mh * 16 + l15, row = mt * 16 + l15;
;             float s = 0.f, ss = 0.f;
; #pragma unroll
;             for (int w = 0; w < 4; ++w) { const f32x4 v = *(const f32x4*)&red[rl * 16 + 4 * w]; s += v[0] + v[2]; ss += v[1] + v[3]; }
;             const float mu = s * (1.f / 1024.f);
;             const float var = ss * (1.f / 1024.f) - mu * mu;
;             const float rs = rsqrtf(var + LN_EPS);
;             float* orow = xo + (r0 + row) * 1024 + wid * 128 + quad * 4;
;             bf16_t* brow = xbo + xb_off((int)r0 + row, wid * 128) + quad * 4;
;             const float* gp = GB + wid * 128 + quad * 4;
; #pragma unroll
;             for (int nt = 0; nt < 8; ++nt) {
	ds_read_b128 v[144:147], v200
	ds_read_b128 v[148:151], v201
	ds_read_b128 v[152:155], v202
	ds_read_b128 v[156:159], v203
	ds_read_b128 v[160:163], v200 offset:256
	ds_read_b128 v[164:167], v201 offset:256
	ds_read_b128 v[168:171], v202 offset:256
	ds_read_b128 v[172:175], v203 offset:256
	s_waitcnt lgkmcnt(7)
	v_fmac_f32_e32 v34, s58, v144
	v_fmac_f32_e32 v35, s58, v145
	v_fmac_f32_e32 v36, s58, v146
	v_fmac_f32_e32 v37, s58, v147
	v_mov_b32_e32 v196, v34
	v_mul_f32_e32 v197, v34, v34
	v_mov_b32_e32 v130, v35
	v_mul_f32_e32 v142, v35, v35
	v_add_f32_e32 v196, v196, v36
	v_fmac_f32_e32 v197, v36, v36
	v_add_f32_e32 v130, v130, v37
	v_fmac_f32_e32 v142, v37, v37
	s_waitcnt lgkmcnt(6)
	v_fmac_f32_e32 v30, s58, v148
	v_fmac_f32_e32 v31, s58, v149
	v_fmac_f32_e32 v32, s58, v150
	v_fmac_f32_e32 v33, s58, v151
	v_add_f32_e32 v196, v196, v30
	v_fmac_f32_e32 v197, v30, v30
	v_add_f32_e32 v130, v130, v31
	v_fmac_f32_e32 v142, v31, v31
	v_add_f32_e32 v196, v196, v32
	v_fmac_f32_e32 v197, v32, v32
	v_add_f32_e32 v130, v130, v33
	v_fmac_f32_e32 v142, v33, v33
	s_waitcnt lgkmcnt(5)
	v_fmac_f32_e32 v26, s58, v152
	v_fmac_f32_e32 v27, s58, v153
	v_fmac_f32_e32 v28, s58, v154
	v_fmac_f32_e32 v29, s58, v155
	v_add_f32_e32 v196, v196, v26
	v_fmac_f32_e32 v197, v26, v26
	v_add_f32_e32 v130, v130, v27
	v_fmac_f32_e32 v142, v27, v27
	v_add_f32_e32 v196, v196, v28
	v_fmac_f32_e32 v197, v28, v28
	v_add_f32_e32 v130, v130, v29
	v_fmac_f32_e32 v142, v29, v29
	s_waitcnt lgkmcnt(4)
	v_fmac_f32_e32 v22, s58, v156
	v_fmac_f32_e32 v23, s58, v157
	v_fmac_f32_e32 v24, s58, v158
	v_fmac_f32_e32 v25, s58, v159
	v_add_f32_e32 v196, v196, v22
	v_fmac_f32_e32 v197, v22, v22
	v_add_f32_e32 v130, v130, v23
	v_fmac_f32_e32 v142, v23, v23
	v_add_f32_e32 v196, v196, v24
	v_fmac_f32_e32 v197, v24, v24
	v_add_f32_e32 v130, v130, v25
	v_fmac_f32_e32 v142, v25, v25
	s_waitcnt lgkmcnt(3)
	v_fmac_f32_e32 v18, s58, v160
	v_fmac_f32_e32 v19, s58, v161
	v_fmac_f32_e32 v20, s58, v162
	v_fmac_f32_e32 v21, s58, v163
	v_add_f32_e32 v196, v196, v18
	v_fmac_f32_e32 v197, v18, v18
	v_add_f32_e32 v130, v130, v19
	v_fmac_f32_e32 v142, v19, v19
	v_add_f32_e32 v196, v196, v20
	v_fmac_f32_e32 v197, v20, v20
	v_add_f32_e32 v130, v130, v21
	v_fmac_f32_e32 v142, v21, v21
	s_waitcnt lgkmcnt(2)
	v_fmac_f32_e32 v14, s58, v164
	v_fmac_f32_e32 v15, s58, v165
	v_fmac_f32_e32 v16, s58, v166
	v_fmac_f32_e32 v17, s58, v167
	v_add_f32_e32 v196, v196, v14
	v_fmac_f32_e32 v197, v14, v14
	v_add_f32_e32 v130, v130, v15
	v_fmac_f32_e32 v142, v15, v15
	v_add_f32_e32 v196, v196, v16
	v_fmac_f32_e32 v197, v16, v16
	v_add_f32_e32 v130, v130, v17
	v_fmac_f32_e32 v142, v17, v17
	s_waitcnt lgkmcnt(1)
	v_fmac_f32_e32 v10, s58, v168
	v_fmac_f32_e32 v11, s58, v169
	v_fmac_f32_e32 v12, s58, v170
	v_fmac_f32_e32 v13, s58, v171
	v_add_f32_e32 v196, v196, v10
	v_fmac_f32_e32 v197, v10, v10
	v_add_f32_e32 v130, v130, v11
	v_fmac_f32_e32 v142, v11, v11
	v_add_f32_e32 v196, v196, v12
	v_fmac_f32_e32 v197, v12, v12
	v_add_f32_e32 v130, v130, v13
	v_fmac_f32_e32 v142, v13, v13
	s_waitcnt lgkmcnt(0)
	v_fmac_f32_e32 v6, s58, v172
	v_fmac_f32_e32 v7, s58, v173
	v_fmac_f32_e32 v8, s58, v174
	v_fmac_f32_e32 v9, s58, v175
	v_add_f32_e32 v196, v196, v6
	v_fmac_f32_e32 v197, v6, v6
	v_add_f32_e32 v130, v130, v7
	v_fmac_f32_e32 v142, v7, v7
	v_add_f32_e32 v196, v196, v8
	v_fmac_f32_e32 v197, v8, v8
	v_add_f32_e32 v130, v130, v9
	v_fmac_f32_e32 v142, v9, v9
	v_add_f32_e32 v196, v196, v130
	v_add_f32_e32 v197, v197, v142
	v_mov_b32_e32 v198, v196
	v_mov_b32_e32 v199, v197
	s_nop 1
	v_permlane16_swap_b32 v198, v196
	v_permlane16_swap_b32 v199, v197
	v_add_f32_e32 v196, v196, v198
	v_add_f32_e32 v197, v197, v199
	v_mov_b32_e32 v198, v196
	v_mov_b32_e32 v199, v197
	s_nop 1
	v_permlane32_swap_b32 v198, v196
	v_permlane32_swap_b32 v199, v197
	v_add_f32_e32 v196, v196, v198
	v_add_f32_e32 v197, v197, v199
	s_mov_b64 exec, 0xffff
	ds_write_b64 v134, v[196:197]
	s_mov_b64 exec, -1
	s_waitcnt lgkmcnt(0)
	s_barrier
	ds_read_b128 v[160:163], v135 offset:0
	ds_read_b128 v[164:167], v135 offset:16
	ds_read_b128 v[168:171], v135 offset:32
	ds_read_b128 v[172:175], v135 offset:48
	s_waitcnt lgkmcnt(0)
	v_add_f32_e32 v160, v160, v162
	v_add_f32_e32 v161, v161, v163
	v_add_f32_e32 v164, v164, v166
	v_add_f32_e32 v165, v165, v167
	v_add_f32_e32 v168, v168, v170
	v_add_f32_e32 v169, v169, v171
	v_add_f32_e32 v172, v172, v174
	v_add_f32_e32 v173, v173, v175
	v_add_f32_e32 v160, v160, v164
	v_add_f32_e32 v161, v161, v165
	v_add_f32_e32 v168, v168, v172
	v_add_f32_e32 v169, v169, v173
	v_add_f32_e32 v160, v160, v168
	v_add_f32_e32 v161, v161, v169
	v_mul_f32_e32 v192, 0x3a800000, v160
	v_mul_f32_e32 v193, 0x3a800000, v161
	v_fma_f32 v193, -v192, v192, v193
	v_add_f32_e32 v193, 0x3727c5ac, v193
	v_rsq_f32_e32 v193, v193
	s_nop 0
	s_add_u32 s94, s78, 0x800
	s_addc_u32 s95, s79, 0
	ds_read_b128 v[176:179], v136
	ds_read_b128 v[180:183], v136 offset:4096
	ds_read_b128 v[184:187], v136 offset:64
	ds_read_b128 v[188:191], v136 offset:4160
	s_waitcnt lgkmcnt(2)
	v_sub_f32_e32 v34, v34, v192
	v_mul_f32_e32 v34, v34, v193
	v_fma_f32 v34, v176, v34, v180
	v_sub_f32_e32 v35, v35, v192
	v_mul_f32_e32 v35, v35, v193
	v_fma_f32 v35, v177, v35, v181
	v_sub_f32_e32 v36, v36, v192
	v_mul_f32_e32 v36, v36, v193
	v_fma_f32 v36, v178, v36, v182
	v_sub_f32_e32 v37, v37, v192
	v_mul_f32_e32 v37, v37, v193
	v_fma_f32 v37, v179, v37, v183
	v_cvt_pk_bf16_f32 v144, v34, v35
	v_cvt_pk_bf16_f32 v145, v36, v37
	ds_read_b128 v[176:179], v136 offset:128
	ds_read_b128 v[180:183], v136 offset:4224
	s_waitcnt lgkmcnt(2)
; DI unsigned pk2(float lo, float hi) { const f32x2 v = {lo, hi}; const bf16x2_t b = __builtin_convertvector(v, bf16x2_t); return __builtin_bit_cast(unsigned, b); }
; DI size_t xb_off(int tok, int col) { return ((size_t)(((tok >> 7) * 32 + (col >> 5)) * 128 + (tok & 127))) * 32 + (col & 31); }
; DI void unit_O(const Params& p, char* lds, int l, int tile, int glu_tiles, int tile_b) {
;     ...
;             float* orow = xo + (r0 + row) * 1024 + wid * 128 + quad * 4;
;             bf16_t* brow = xbo + xb_off((int)r0 + row, wid * 128) + quad * 4;
;             const float* gp = GB + wid * 128 + quad * 4;
; #pragma unroll
;             for (int nt = 0; nt < 8; ++nt) {
;                 const f32x4 g = *(const f32x4*)(gp + nt * 16), bb = *(const f32x4*)(gp + 1024 + nt * 16);
;                 f32x4 o;
; #pragma unroll
;                 for (int i = 0; i < 4; ++i) o[i] = (acc[mt][nt][i] - mu) * rs * g[i] + bb[i];
;                 if (l == 0) *(u32x2*)(brow + (nt >> 1) * 4096 + (nt & 1) * 16) = (u32x2){pk2(o[0], o[1]), pk2(o[2], o[3])};
;                 else *(f32x4*)(orow + nt * 16) = o;
;             }
;         }
	v_sub_f32_e32 v30, v30, v192
	v_mul_f32_e32 v30, v30, v193
	v_fma_f32 v30, v184, v30, v188
	v_sub_f32_e32 v31, v31, v192
	v_mul_f32_e32 v31, v31, v193
	v_fma_f32 v31, v185, v31, v189
	v_sub_f32_e32 v32, v32, v192
	v_mul_f32_e32 v32, v32, v193
	v_fma_f32 v32, v186, v32, v190
	v_sub_f32_e32 v33, v33, v192
	v_mul_f32_e32 v33, v33, v193
	v_fma_f32 v33, v187, v33, v191
	v_cvt_pk_bf16_f32 v146, v30, v31
	v_cvt_pk_bf16_f32 v147, v32, v33
	s_nop 1
	v_permlane16_swap_b32 v144, v146
	v_permlane16_swap_b32 v145, v147
	global_store_dwordx4 v137, v[144:147], s[94:95] sc1
	s_add_u32 s94, s94, 0x2000
	s_addc_u32 s95, s95, 0
	ds_read_b128 v[184:187], v136 offset:192
	ds_read_b128 v[188:191], v136 offset:4288
	s_waitcnt lgkmcnt(2)
	v_sub_f32_e32 v26, v26, v192
	v_mul_f32_e32 v26, v26, v193
	v_fma_f32 v26, v176, v26, v180
	v_sub_f32_e32 v27, v27, v192
	v_mul_f32_e32 v27, v27, v193
	v_fma_f32 v27, v177, v27, v181
	v_sub_f32_e32 v28, v28, v192
	v_mul_f32_e32 v28, v28, v193
	v_fma_f32 v28, v178, v28, v182
	v_sub_f32_e32 v29, v29, v192
	v_mul_f32_e32 v29, v29, v193
	v_fma_f32 v29, v179, v29, v183
	v_cvt_pk_bf16_f32 v152, v26, v27
	v_cvt_pk_bf16_f32 v153, v28, v29
	ds_read_b128 v[176:179], v136 offset:256
	ds_read_b128 v[180:183], v136 offset:4352
	s_waitcnt lgkmcnt(2)
	v_sub_f32_e32 v22, v22, v192
	v_mul_f32_e32 v22, v22, v193
	v_fma_f32 v22, v184, v22, v188
	v_sub_f32_e32 v23, v23, v192
	v_mul_f32_e32 v23, v23, v193
	v_fma_f32 v23, v185, v23, v189
	v_sub_f32_e32 v24, v24, v192
	v_mul_f32_e32 v24, v24, v193
	v_fma_f32 v24, v186, v24, v190
	v_sub_f32_e32 v25, v25, v192
	v_mul_f32_e32 v25, v25, v193
	v_fma_f32 v25, v187, v25, v191
	v_cvt_pk_bf16_f32 v154, v22, v23
	v_cvt_pk_bf16_f32 v155, v24, v25
	s_nop 1
	v_permlane16_swap_b32 v152, v154
	v_permlane16_swap_b32 v153, v155
	global_store_dwordx4 v137, v[152:155], s[94:95] sc1
	s_add_u32 s94, s94, 0x2000
	s_addc_u32 s95, s95, 0
	ds_read_b128 v[184:187], v136 offset:320
	ds_read_b128 v[188:191], v136 offset:4416
	s_waitcnt lgkmcnt(2)
	v_sub_f32_e32 v18, v18, v192
	v_mul_f32_e32 v18, v18, v193
	v_fma_f32 v18, v176, v18, v180
	v_sub_f32_e32 v19, v19, v192
	v_mul_f32_e32 v19, v19, v193
	v_fma_f32 v19, v177, v19, v181
	v_sub_f32_e32 v20, v20, v192
	v_mul_f32_e32 v20, v20, v193
	v_fma_f32 v20, v178, v20, v182
	v_sub_f32_e32 v21, v21, v192
	v_mul_f32_e32 v21, v21, v193
	v_fma_f32 v21, v179, v21, v183
	v_cvt_pk_bf16_f32 v144, v18, v19
	v_cvt_pk_bf16_f32 v145, v20, v21
	ds_read_b128 v[176:179], v136 offset:384
	ds_read_b128 v[180:183], v136 offset:4480
	s_waitcnt lgkmcnt(2)
	v_sub_f32_e32 v14, v14, v192
	v_mul_f32_e32 v14, v14, v193
	v_fma_f32 v14, v184, v14, v188
	v_sub_f32_e32 v15, v15, v192
	v_mul_f32_e32 v15, v15, v193
	v_fma_f32 v15, v185, v15, v189
	v_sub_f32_e32 v16, v16, v192
	v_mul_f32_e32 v16, v16, v193
	v_fma_f32 v16, v186, v16, v190
	v_sub_f32_e32 v17, v17, v192
	v_mul_f32_e32 v17, v17, v193
	v_fma_f32 v17, v187, v17, v191
	v_cvt_pk_bf16_f32 v146, v14, v15
	v_cvt_pk_bf16_f32 v147, v16, v17
	s_nop 1
	v_permlane16_swap_b32 v144, v146
	v_permlane16_swap_b32 v145, v147
	global_store_dwordx4 v137, v[144:147], s[94:95] sc1
	s_add_u32 s94, s94, 0x2000
	s_addc_u32 s95, s95, 0
	ds_read_b128 v[184:187], v136 offset:448
	ds_read_b128 v[188:191], v136 offset:4544
	s_waitcnt lgkmcnt(2)
	v_sub_f32_e32 v10, v10, v192
	v_mul_f32_e32 v10, v10, v193
	v_fma_f32 v10, v176, v10, v180
	v_sub_f32_e32 v11, v11, v192
	v_mul_f32_e32 v11, v11, v193
	v_fma_f32 v11, v177, v11, v181
	v_sub_f32_e32 v12, v12, v192
	v_mul_f32_e32 v12, v12, v193
	v_fma_f32 v12, v178, v12, v182
	v_sub_f32_e32 v13, v13, v192
	v_mul_f32_e32 v13, v13, v193
	v_fma_f32 v13, v179, v13, v183
	v_cvt_pk_bf16_f32 v152, v10, v11
	v_cvt_pk_bf16_f32 v153, v12, v13
	s_waitcnt lgkmcnt(0)
	v_sub_f32_e32 v6, v6, v192
	v_mul_f32_e32 v6, v6, v193
	v_fma_f32 v6, v184, v6, v188
	v_sub_f32_e32 v7, v7, v192
	v_mul_f32_e32 v7, v7, v193
	v_fma_f32 v7, v185, v7, v189
	v_sub_f32_e32 v8, v8, v192
	v_mul_f32_e32 v8, v8, v193
	v_fma_f32 v8, v186, v8, v190
	v_sub_f32_e32 v9, v9, v192
	v_mul_f32_e32 v9, v9, v193
	v_fma_f32 v9, v187, v9, v191
	v_cvt_pk_bf16_f32 v154, v6, v7
	v_cvt_pk_bf16_f32 v155, v8, v9
	s_nop 1
	v_permlane16_swap_b32 v152, v154
	v_permlane16_swap_b32 v153, v155
	global_store_dwordx4 v137, v[152:155], s[94:95] sc1
	s_waitcnt vmcnt(8) lgkmcnt(0)
	s_barrier
; DI void unit_O(const Params& p, char* lds, int l, int tile, int glu_tiles, int tile_b) {
;     ...
;         float s2[2], ss2[2];
; #pragma unroll
;         for (int mh = 0; mh < 2; ++mh) {
;             const int mt = half * 2 + mh, rl = mh * 16 + l15;
;             float s = 0.f, ss = 0.f;
; #pragma unroll
;             for (int nt = 0; nt < 8; ++nt) {
;                 f32x4 xr;
;                 if (l == 0) {
;                     const int chunk = wid * 32 + nt * 4 + quad;
;                     xr = *(const f32x4*)(XR + rl * 4096 + ((chunk ^ l15) << 4));
;                 } else {
;                     const u32x2 hb = *(const u32x2*)(XR + ((wid * 4 + (nt >> 1)) * 32 + rl) * 64 + (nt & 1) * 32 + quad * 8);
;                     xr = (f32x4){bf2f(hb[0] & 0xffffu), bf2f(hb[0] >> 16), bf2f(hb[1] & 0xffffu), bf2f(hb[1] >> 16)};
;                 }
; #pragma unroll
;                 for (int i = 0; i < 4; ++i) { const float v = acc[mt][nt][i] + DN_ALPHA * xr[i]; acc[mt][nt][i] = v; s += v; ss += v * v; }
;             }
;             s2[mh] = s; ss2[mh] = ss;
;         }
; #pragma unroll
;         for (int mh = 0; mh < 2; ++mh) { s2[mh] += __shfl_xor(s2[mh], 16); ss2[mh] += __shfl_xor(ss2[mh], 16); }
; #pragma unroll
;         for (int mh = 0; mh < 2; ++mh) { s2[mh] += __shfl_xor(s2[mh], 32); ss2[mh] += __shfl_xor(ss2[mh], 32); }
;         if (quad == 0) {
; #pragma unroll
;             for (int mh = 0; mh < 2; ++mh) *(f32x2*)&red[((mh * 16 + l15) * 8 + wid) * 2] = (f32x2){s2[mh], ss2[mh]};
;         }
;         __syncthreads();
;         if (half == 0) issue_x(1);
; #pragma unroll
;         for (int mh = 0; mh < 2; ++mh) {
;             const int mt = half * 2 + mh, rl = mh * 16 + l15, row = mt * 16 + l15;
;             float s = 0.f, ss = 0.f;
; #pragma unroll
;             for (int w = 0; w < 4; ++w) { const f32x4 v = *(const f32x4*)&red[rl * 16 + 4 * w]; s += v[0] + v[2]; ss += v[1] + v[3]; }
;             const float mu = s * (1.f / 1024.f);
;             const float var = ss * (1.f / 1024.f) - mu * mu;
;             const float rs = rsqrtf(var + LN_EPS);
;             float* orow = xo + (r0 + row) * 1024 + wid * 128 + quad * 4;
;             bf16_t* brow = xbo + xb_off((int)r0 + row, wid * 128) + quad * 4;
;             const float* gp = GB + wid * 128 + quad * 4;
; #pragma unroll
;             for (int nt = 0; nt < 8; ++nt) {
	ds_read_b128 v[144:147], v204
	ds_read_b128 v[148:151], v205
	ds_read_b128 v[152:155], v206
	ds_read_b128 v[156:159], v207
	ds_read_b128 v[160:163], v204 offset:256
	ds_read_b128 v[164:167], v205 offset:256
	ds_read_b128 v[168:171], v206 offset:256
	ds_read_b128 v[172:175], v207 offset:256
	s_waitcnt lgkmcnt(7)
	v_fmac_f32_e32 v62, s58, v144
	v_fmac_f32_e32 v63, s58, v145
	v_fmac_f32_e32 v64, s58, v146
	v_fmac_f32_e32 v65, s58, v147
	v_mov_b32_e32 v196, v62
	v_mul_f32_e32 v197, v62, v62
	v_mov_b32_e32 v130, v63
	v_mul_f32_e32 v142, v63, v63
	v_add_f32_e32 v196, v196, v64
	v_fmac_f32_e32 v197, v64, v64
	v_add_f32_e32 v130, v130, v65
	v_fmac_f32_e32 v142, v65, v65
	s_waitcnt lgkmcnt(6)
	v_fmac_f32_e32 v58, s58, v148
	v_fmac_f32_e32 v59, s58, v149
	v_fmac_f32_e32 v60, s58, v150
	v_fmac_f32_e32 v61, s58, v151
	v_add_f32_e32 v196, v196, v58
	v_fmac_f32_e32 v197, v58, v58
	v_add_f32_e32 v130, v130, v59
	v_fmac_f32_e32 v142, v59, v59
	v_add_f32_e32 v196, v196, v60
	v_fmac_f32_e32 v197, v60, v60
	v_add_f32_e32 v130, v130, v61
	v_fmac_f32_e32 v142, v61, v61
	s_waitcnt lgkmcnt(5)
	v_fmac_f32_e32 v54, s58, v152
	v_fmac_f32_e32 v55, s58, v153
	v_fmac_f32_e32 v56, s58, v154
	v_fmac_f32_e32 v57, s58, v155
	v_add_f32_e32 v196, v196, v54
	v_fmac_f32_e32 v197, v54, v54
	v_add_f32_e32 v130, v130, v55
	v_fmac_f32_e32 v142, v55, v55
	v_add_f32_e32 v196, v196, v56
	v_fmac_f32_e32 v197, v56, v56
	v_add_f32_e32 v130, v130, v57
	v_fmac_f32_e32 v142, v57, v57
	s_waitcnt lgkmcnt(4)
	v_fmac_f32_e32 v50, s58, v156
	v_fmac_f32_e32 v51, s58, v157
	v_fmac_f32_e32 v52, s58, v158
	v_fmac_f32_e32 v53, s58, v159
	v_add_f32_e32 v196, v196, v50
	v_fmac_f32_e32 v197, v50, v50
	v_add_f32_e32 v130, v130, v51
	v_fmac_f32_e32 v142, v51, v51
	v_add_f32_e32 v196, v196, v52
	v_fmac_f32_e32 v197, v52, v52
	v_add_f32_e32 v130, v130, v53
	v_fmac_f32_e32 v142, v53, v53
	s_waitcnt lgkmcnt(3)
	v_fmac_f32_e32 v46, s58, v160
	v_fmac_f32_e32 v47, s58, v161
	v_fmac_f32_e32 v48, s58, v162
	v_fmac_f32_e32 v49, s58, v163
	v_add_f32_e32 v196, v196, v46
	v_fmac_f32_e32 v197, v46, v46
	v_add_f32_e32 v130, v130, v47
	v_fmac_f32_e32 v142, v47, v47
	v_add_f32_e32 v196, v196, v48
	v_fmac_f32_e32 v197, v48, v48
	v_add_f32_e32 v130, v130, v49
	v_fmac_f32_e32 v142, v49, v49
	s_waitcnt lgkmcnt(2)
	v_fmac_f32_e32 v42, s58, v164
	v_fmac_f32_e32 v43, s58, v165
	v_fmac_f32_e32 v44, s58, v166
	v_fmac_f32_e32 v45, s58, v167
	v_add_f32_e32 v196, v196, v42
	v_fmac_f32_e32 v197, v42, v42
	v_add_f32_e32 v130, v130, v43
	v_fmac_f32_e32 v142, v43, v43
	v_add_f32_e32 v196, v196, v44
	v_fmac_f32_e32 v197, v44, v44
	v_add_f32_e32 v130, v130, v45
	v_fmac_f32_e32 v142, v45, v45
	s_waitcnt lgkmcnt(1)
	v_fmac_f32_e32 v38, s58, v168
	v_fmac_f32_e32 v39, s58, v169
	v_fmac_f32_e32 v40, s58, v170
	v_fmac_f32_e32 v41, s58, v171
	v_add_f32_e32 v196, v196, v38
	v_fmac_f32_e32 v197, v38, v38
	v_add_f32_e32 v130, v130, v39
	v_fmac_f32_e32 v142, v39, v39
	v_add_f32_e32 v196, v196, v40
	v_fmac_f32_e32 v197, v40, v40
	v_add_f32_e32 v130, v130, v41
	v_fmac_f32_e32 v142, v41, v41
	s_waitcnt lgkmcnt(0)
	v_fmac_f32_e32 v2, s58, v172
	v_fmac_f32_e32 v3, s58, v173
	v_fmac_f32_e32 v4, s58, v174
	v_fmac_f32_e32 v5, s58, v175
	v_add_f32_e32 v196, v196, v2
	v_fmac_f32_e32 v197, v2, v2
	v_add_f32_e32 v130, v130, v3
	v_fmac_f32_e32 v142, v3, v3
	v_add_f32_e32 v196, v196, v4
	v_fmac_f32_e32 v197, v4, v4
	v_add_f32_e32 v130, v130, v5
	v_fmac_f32_e32 v142, v5, v5
	v_add_f32_e32 v196, v196, v130
	v_add_f32_e32 v197, v197, v142
	v_mov_b32_e32 v198, v196
	v_mov_b32_e32 v199, v197
	s_nop 1
	v_permlane16_swap_b32 v198, v196
	v_permlane16_swap_b32 v199, v197
	v_add_f32_e32 v196, v196, v198
	v_add_f32_e32 v197, v197, v199
	v_mov_b32_e32 v198, v196
	v_mov_b32_e32 v199, v197
	s_nop 1
	v_permlane32_swap_b32 v198, v196
	v_permlane32_swap_b32 v199, v197
	v_add_f32_e32 v196, v196, v198
	v_add_f32_e32 v197, v197, v199
	s_mov_b64 exec, 0xffff
	ds_write_b64 v134, v[196:197]
	s_mov_b64 exec, -1
	s_waitcnt lgkmcnt(0)
	s_barrier
	ds_read_b128 v[160:163], v135 offset:0
	ds_read_b128 v[164:167], v135 offset:16
	ds_read_b128 v[168:171], v135 offset:32
	ds_read_b128 v[172:175], v135 offset:48
	s_waitcnt lgkmcnt(0)
	v_add_f32_e32 v160, v160, v162
	v_add_f32_e32 v161, v161, v163
	v_add_f32_e32 v164, v164, v166
	v_add_f32_e32 v165, v165, v167
	v_add_f32_e32 v168, v168, v170
	v_add_f32_e32 v169, v169, v171
	v_add_f32_e32 v172, v172, v174
	v_add_f32_e32 v173, v173, v175
	v_add_f32_e32 v160, v160, v164
	v_add_f32_e32 v161, v161, v165
	v_add_f32_e32 v168, v168, v172
	v_add_f32_e32 v169, v169, v173
	v_add_f32_e32 v160, v160, v168
	v_add_f32_e32 v161, v161, v169
	v_mul_f32_e32 v192, 0x3a800000, v160
	v_mul_f32_e32 v193, 0x3a800000, v161
	v_fma_f32 v193, -v192, v192, v193
	v_add_f32_e32 v193, 0x3727c5ac, v193
	v_rsq_f32_e32 v193, v193
	s_nop 0
	s_add_u32 s94, s78, 0xc00
	s_addc_u32 s95, s79, 0
	ds_read_b128 v[176:179], v136
	ds_read_b128 v[180:183], v136 offset:4096
	ds_read_b128 v[184:187], v136 offset:64
	ds_read_b128 v[188:191], v136 offset:4160
	s_waitcnt lgkmcnt(2)
	v_sub_f32_e32 v62, v62, v192
	v_mul_f32_e32 v62, v62, v193
	v_fma_f32 v62, v176, v62, v180
	v_sub_f32_e32 v63, v63, v192
	v_mul_f32_e32 v63, v63, v193
	v_fma_f32 v63, v177, v63, v181
	v_sub_f32_e32 v64, v64, v192
	v_mul_f32_e32 v64, v64, v193
	v_fma_f32 v64, v178, v64, v182
	v_sub_f32_e32 v65, v65, v192
	v_mul_f32_e32 v65, v65, v193
	v_fma_f32 v65, v179, v65, v183
	v_cvt_pk_bf16_f32 v144, v62, v63
	v_cvt_pk_bf16_f32 v145, v64, v65
	ds_read_b128 v[176:179], v136 offset:128
	ds_read_b128 v[180:183], v136 offset:4224
	s_waitcnt lgkmcnt(2)
; DI unsigned pk2(float lo, float hi) { const f32x2 v = {lo, hi}; const bf16x2_t b = __builtin_convertvector(v, bf16x2_t); return __builtin_bit_cast(unsigned, b); }
; DI size_t xb_off(int tok, int col) { return ((size_t)(((tok >> 7) * 32 + (col >> 5)) * 128 + (tok & 127))) * 32 + (col & 31); }
; DI void unit_O(const Params& p, char* lds, int l, int tile, int glu_tiles, int tile_b) {
;     ...
;             float* orow = xo + (r0 + row) * 1024 + wid * 128 + quad * 4;
;             bf16_t* brow = xbo + xb_off((int)r0 + row, wid * 128) + quad * 4;
;             const float* gp = GB + wid * 128 + quad * 4;
; #pragma unroll
;             for (int nt = 0; nt < 8; ++nt) {
;                 const f32x4 g = *(const f32x4*)(gp + nt * 16), bb = *(const f32x4*)(gp + 1024 + nt * 16);
;                 f32x4 o;
; #pragma unroll
;                 for (int i = 0; i < 4; ++i) o[i] = (acc[mt][nt][i] - mu) * rs * g[i] + bb[i];
;                 if (l == 0) *(u32x2*)(brow + (nt >> 1) * 4096 + (nt & 1) * 16) = (u32x2){pk2(o[0], o[1]), pk2(o[2], o[3])};
;                 else *(f32x4*)(orow + nt * 16) = o;
;             }
;         }
	v_sub_f32_e32 v58, v58, v192
	v_mul_f32_e32 v58, v58, v193
	v_fma_f32 v58, v184, v58, v188
	v_sub_f32_e32 v59, v59, v192
	v_mul_f32_e32 v59, v59, v193
	v_fma_f32 v59, v185, v59, v189
	v_sub_f32_e32 v60, v60, v192
	v_mul_f32_e32 v60, v60, v193
	v_fma_f32 v60, v186, v60, v190
	v_sub_f32_e32 v61, v61, v192
	v_mul_f32_e32 v61, v61, v193
	v_fma_f32 v61, v187, v61, v191
	v_cvt_pk_bf16_f32 v146, v58, v59
	v_cvt_pk_bf16_f32 v147, v60, v61
	s_nop 1
	v_permlane16_swap_b32 v144, v146
	v_permlane16_swap_b32 v145, v147
	global_store_dwordx4 v137, v[144:147], s[94:95] sc1
	s_add_u32 s94, s94, 0x2000
	s_addc_u32 s95, s95, 0
	ds_read_b128 v[184:187], v136 offset:192
	ds_read_b128 v[188:191], v136 offset:4288
	s_waitcnt lgkmcnt(2)
	v_sub_f32_e32 v54, v54, v192
	v_mul_f32_e32 v54, v54, v193
	v_fma_f32 v54, v176, v54, v180
	v_sub_f32_e32 v55, v55, v192
	v_mul_f32_e32 v55, v55, v193
	v_fma_f32 v55, v177, v55, v181
	v_sub_f32_e32 v56, v56, v192
	v_mul_f32_e32 v56, v56, v193
	v_fma_f32 v56, v178, v56, v182
	v_sub_f32_e32 v57, v57, v192
	v_mul_f32_e32 v57, v57, v193
	v_fma_f32 v57, v179, v57, v183
	v_cvt_pk_bf16_f32 v152, v54, v55
	v_cvt_pk_bf16_f32 v153, v56, v57
	ds_read_b128 v[176:179], v136 offset:256
	ds_read_b128 v[180:183], v136 offset:4352
	s_waitcnt lgkmcnt(2)
	v_sub_f32_e32 v50, v50, v192
	v_mul_f32_e32 v50, v50, v193
	v_fma_f32 v50, v184, v50, v188
	v_sub_f32_e32 v51, v51, v192
	v_mul_f32_e32 v51, v51, v193
	v_fma_f32 v51, v185, v51, v189
	v_sub_f32_e32 v52, v52, v192
	v_mul_f32_e32 v52, v52, v193
	v_fma_f32 v52, v186, v52, v190
	v_sub_f32_e32 v53, v53, v192
	v_mul_f32_e32 v53, v53, v193
	v_fma_f32 v53, v187, v53, v191
	v_cvt_pk_bf16_f32 v154, v50, v51
	v_cvt_pk_bf16_f32 v155, v52, v53
	s_nop 1
	v_permlane16_swap_b32 v152, v154
	v_permlane16_swap_b32 v153, v155
	global_store_dwordx4 v137, v[152:155], s[94:95] sc1
	s_add_u32 s94, s94, 0x2000
	s_addc_u32 s95, s95, 0
	ds_read_b128 v[184:187], v136 offset:320
	ds_read_b128 v[188:191], v136 offset:4416
	s_waitcnt lgkmcnt(2)
	v_sub_f32_e32 v46, v46, v192
	v_mul_f32_e32 v46, v46, v193
	v_fma_f32 v46, v176, v46, v180
	v_sub_f32_e32 v47, v47, v192
	v_mul_f32_e32 v47, v47, v193
	v_fma_f32 v47, v177, v47, v181
	v_sub_f32_e32 v48, v48, v192
	v_mul_f32_e32 v48, v48, v193
	v_fma_f32 v48, v178, v48, v182
	v_sub_f32_e32 v49, v49, v192
	v_mul_f32_e32 v49, v49, v193
	v_fma_f32 v49, v179, v49, v183
	v_cvt_pk_bf16_f32 v144, v46, v47
	v_cvt_pk_bf16_f32 v145, v48, v49
	ds_read_b128 v[176:179], v136 offset:384
	ds_read_b128 v[180:183], v136 offset:4480
	s_waitcnt lgkmcnt(2)
	v_sub_f32_e32 v42, v42, v192
	v_mul_f32_e32 v42, v42, v193
	v_fma_f32 v42, v184, v42, v188
	v_sub_f32_e32 v43, v43, v192
	v_mul_f32_e32 v43, v43, v193
	v_fma_f32 v43, v185, v43, v189
	v_sub_f32_e32 v44, v44, v192
	v_mul_f32_e32 v44, v44, v193
	v_fma_f32 v44, v186, v44, v190
	v_sub_f32_e32 v45, v45, v192
	v_mul_f32_e32 v45, v45, v193
	v_fma_f32 v45, v187, v45, v191
	v_cvt_pk_bf16_f32 v146, v42, v43
	v_cvt_pk_bf16_f32 v147, v44, v45
	s_nop 1
	v_permlane16_swap_b32 v144, v146
	v_permlane16_swap_b32 v145, v147
	global_store_dwordx4 v137, v[144:147], s[94:95] sc1
	s_add_u32 s94, s94, 0x2000
	s_addc_u32 s95, s95, 0
	ds_read_b128 v[184:187], v136 offset:448
	ds_read_b128 v[188:191], v136 offset:4544
	s_waitcnt lgkmcnt(2)
	v_sub_f32_e32 v38, v38, v192
	v_mul_f32_e32 v38, v38, v193
	v_fma_f32 v38, v176, v38, v180
	v_sub_f32_e32 v39, v39, v192
	v_mul_f32_e32 v39, v39, v193
	v_fma_f32 v39, v177, v39, v181
	v_sub_f32_e32 v40, v40, v192
	v_mul_f32_e32 v40, v40, v193
	v_fma_f32 v40, v178, v40, v182
	v_sub_f32_e32 v41, v41, v192
	v_mul_f32_e32 v41, v41, v193
	v_fma_f32 v41, v179, v41, v183
	v_cvt_pk_bf16_f32 v152, v38, v39
	v_cvt_pk_bf16_f32 v153, v40, v41
	s_waitcnt lgkmcnt(0)
	v_sub_f32_e32 v2, v2, v192
	v_mul_f32_e32 v2, v2, v193
	v_fma_f32 v2, v184, v2, v188
	v_sub_f32_e32 v3, v3, v192
	v_mul_f32_e32 v3, v3, v193
	v_fma_f32 v3, v185, v3, v189
	v_sub_f32_e32 v4, v4, v192
	v_mul_f32_e32 v4, v4, v193
	v_fma_f32 v4, v186, v4, v190
	v_sub_f32_e32 v5, v5, v192
	v_mul_f32_e32 v5, v5, v193
	v_fma_f32 v5, v187, v5, v191
	v_cvt_pk_bf16_f32 v154, v2, v3
	v_cvt_pk_bf16_f32 v155, v4, v5
	s_nop 1
	v_permlane16_swap_b32 v152, v154
	v_permlane16_swap_b32 v153, v155
	global_store_dwordx4 v137, v[152:155], s[94:95] sc1
	s_branch .Le2_done
; DI void unit_O(const Params& p, char* lds, int l, int tile, int glu_tiles, int tile_b) {
;     ...
;     auto issue_x = [&](int half) {
;         if (l == 0) {
; #pragma unroll 1
;             for (int i = 0; i < 16; ++i) {
;                 const int pc = (wid * 16 + i + xrot) & 127, row = pc >> 2, phys = (pc & 3) * 64 + lane, logical = phys ^ (row & 15);
;                 __builtin_amdgcn_global_load_lds((const unsigned*)(xres + (r0 + half * 32 + row) * 1024 + logical * 4), (unsigned*)(XR + pc * 1024 + lane * 16), 16, 0, 0);
;             }
;         } else {
; #pragma unroll 1
;             for (int i = 0; i < 8; ++i) {
;                 const int pc = (wid * 8 + i + (xrot >> 1)) & 63, kt = pc >> 1, sub = pc & 1;
;                 __builtin_amdgcn_global_load_lds((const unsigned*)(xbres + ((size_t)kt * 128 + half * 32) * 32 + sub * 512 + lane * 8), (unsigned*)(XR + pc * 1024 + lane * 16), 16, 0, 0);
;             }
;         }
;     };
;     issue_x(0);
;     {
;         const float* gsrc = (tid < 256) ? (p.ln_g + l * 1024 + tid * 4) : (p.ln_b + l * 1024 + (tid - 256) * 4);
;         *(f32x4*)(GB + tid * 4) = *(const f32x4*)gsrc;
;     }
;     float* xo = (l == 0) ? WS_PTR(float, OFF_X1) : p.out;
;     bf16_t* xbo = WS_PTR(bf16_t, OFF_XB1);
; #pragma unroll
;     for (int half = 0; half < 2; ++half) {
;         if (half == 0) wait_vm<0>();
;         else wait_vm<8>();
;         __syncthreads();
;         float s2[2], ss2[2];
; #pragma unroll
;         for (int mh = 0; mh < 2; ++mh) {
;             const int mt = half * 2 + mh, rl = mh * 16 + l15;
;             float s = 0.f, ss = 0.f;
; #pragma unroll
;             for (int nt = 0; nt < 8; ++nt) {
;                 f32x4 xr;
;                 if (l == 0) {
;                     const int chunk = wid * 32 + nt * 4 + quad;
;                     xr = *(const f32x4*)(XR + rl * 4096 + ((chunk ^ l15) << 4));
;                 } else {
;                     const u32x2 hb = *(const u32x2*)(XR + ((wid * 4 + (nt >> 1)) * 32 + rl) * 64 + (nt & 1) * 32 + quad * 8);
;                     xr = (f32x4){bf2f(hb[0] & 0xffffu), bf2f(hb[0] >> 16), bf2f(hb[1] & 0xffffu), bf2f(hb[1] >> 16)};
;                 }
; #pragma unroll
;                 for (int i = 0; i < 4; ++i) { const float v = acc[mt][nt][i] + DN_ALPHA * xr[i]; acc[mt][nt][i] = v; s += v; ss += v * v; }
;             }
;             s2[mh] = s; ss2[mh] = ss;
.Le2_l1:
	v_lshlrev_b32_e32 v133, 12, v140
	v_lshl_add_u32 v133, v138, 6, v133
	v_lshl_add_u32 v133, v139, 3, v133
	v_lshlrev_b32_e32 v137, 12, v138
	v_lshl_add_u32 v137, v140, 9, v137
	v_lshl_add_u32 v137, v139, 4, v137
	s_lshl_b32 s40, s48, 18
	s_add_u32 s78, s16, s40
	s_addc_u32 s79, s17, 0
	s_add_u32 s92, s96, 0x400
	s_addc_u32 s93, s97, 0
	s_add_u32 s40, s91, 0x8000
	s_mov_b32 m0, s40
	s_nop 0
	global_load_lds_dwordx4 v208, s[92:93]
	s_add_u32 s92, s92, 0x2000
	s_addc_u32 s93, s93, 0
	s_add_u32 m0, m0, 0x400
	s_nop 0
	global_load_lds_dwordx4 v208, s[92:93]
	s_add_u32 s92, s92, 0x2000
	s_addc_u32 s93, s93, 0
	s_add_u32 m0, m0, 0x400
	s_nop 0
	global_load_lds_dwordx4 v208, s[92:93]
	s_add_u32 s92, s92, 0x2000
	s_addc_u32 s93, s93, 0
	s_add_u32 m0, m0, 0x400
	s_nop 0
	global_load_lds_dwordx4 v208, s[92:93]
	s_waitcnt vmcnt(4)
	ds_write_b128 v143, v[176:179]
	s_waitcnt vmcnt(4) lgkmcnt(0)
	s_barrier
	ds_read_b64 v[180:181], v133 offset:0
	ds_read_b64 v[182:183], v133 offset:32
	ds_read_b64 v[184:185], v133 offset:1024
	ds_read_b64 v[186:187], v133 offset:1056
	ds_read_b64 v[188:189], v133 offset:2048
	ds_read_b64 v[190:191], v133 offset:2080
	ds_read_b64 v[192:193], v133 offset:3072
	ds_read_b64 v[194:195], v133 offset:3104
	s_waitcnt lgkmcnt(7)
	v_lshlrev_b32_e32 v144, 16, v180
	v_and_b32_e32 v145, 0xffff0000, v180
	v_lshlrev_b32_e32 v146, 16, v181
	v_and_b32_e32 v147, 0xffff0000, v181
	v_fmac_f32_e32 v98, s58, v144
	v_fmac_f32_e32 v99, s58, v145
	v_fmac_f32_e32 v100, s58, v146
	v_fmac_f32_e32 v101, s58, v147
	v_mov_b32_e32 v196, v98
	v_mul_f32_e32 v197, v98, v98
	v_mov_b32_e32 v130, v99
	v_mul_f32_e32 v142, v99, v99
	v_add_f32_e32 v196, v196, v100
	v_fmac_f32_e32 v197, v100, v100
	v_add_f32_e32 v130, v130, v101
	v_fmac_f32_e32 v142, v101, v101
	s_waitcnt lgkmcnt(6)
	v_lshlrev_b32_e32 v148, 16, v182
	v_and_b32_e32 v149, 0xffff0000, v182
	v_lshlrev_b32_e32 v150, 16, v183
	v_and_b32_e32 v151, 0xffff0000, v183
	v_fmac_f32_e32 v94, s58, v148
	v_fmac_f32_e32 v95, s58, v149
	v_fmac_f32_e32 v96, s58, v150
	v_fmac_f32_e32 v97, s58, v151
	v_add_f32_e32 v196, v196, v94
	v_fmac_f32_e32 v197, v94, v94
	v_add_f32_e32 v130, v130, v95
	v_fmac_f32_e32 v142, v95, v95
	v_add_f32_e32 v196, v196, v96
	v_fmac_f32_e32 v197, v96, v96
	v_add_f32_e32 v130, v130, v97
	v_fmac_f32_e32 v142, v97, v97
	s_waitcnt lgkmcnt(5)
	v_lshlrev_b32_e32 v152, 16, v184
	v_and_b32_e32 v153, 0xffff0000, v184
	v_lshlrev_b32_e32 v154, 16, v185
	v_and_b32_e32 v155, 0xffff0000, v185
	v_fmac_f32_e32 v90, s58, v152
	v_fmac_f32_e32 v91, s58, v153
	v_fmac_f32_e32 v92, s58, v154
	v_fmac_f32_e32 v93, s58, v155
	v_add_f32_e32 v196, v196, v90
	v_fmac_f32_e32 v197, v90, v90
	v_add_f32_e32 v130, v130, v91
	v_fmac_f32_e32 v142, v91, v91
	v_add_f32_e32 v196, v196, v92
	v_fmac_f32_e32 v197, v92, v92
	v_add_f32_e32 v130, v130, v93
	v_fmac_f32_e32 v142, v93, v93
	s_waitcnt lgkmcnt(4)
	v_lshlrev_b32_e32 v156, 16, v186
	v_and_b32_e32 v157, 0xffff0000, v186
	v_lshlrev_b32_e32 v158, 16, v187
	v_and_b32_e32 v159, 0xffff0000, v187
	v_fmac_f32_e32 v86, s58, v156
	v_fmac_f32_e32 v87, s58, v157
	v_fmac_f32_e32 v88, s58, v158
	v_fmac_f32_e32 v89, s58, v159
	v_add_f32_e32 v196, v196, v86
	v_fmac_f32_e32 v197, v86, v86
	v_add_f32_e32 v130, v130, v87
	v_fmac_f32_e32 v142, v87, v87
	v_add_f32_e32 v196, v196, v88
	v_fmac_f32_e32 v197, v88, v88
	v_add_f32_e32 v130, v130, v89
	v_fmac_f32_e32 v142, v89, v89
	s_waitcnt lgkmcnt(3)
	v_lshlrev_b32_e32 v160, 16, v188
	v_and_b32_e32 v161, 0xffff0000, v188
	v_lshlrev_b32_e32 v162, 16, v189
	v_and_b32_e32 v163, 0xffff0000, v189
	v_fmac_f32_e32 v82, s58, v160
	v_fmac_f32_e32 v83, s58, v161
	v_fmac_f32_e32 v84, s58, v162
	v_fmac_f32_e32 v85, s58, v163
	v_add_f32_e32 v196, v196, v82
	v_fmac_f32_e32 v197, v82, v82
	v_add_f32_e32 v130, v130, v83
	v_fmac_f32_e32 v142, v83, v83
	v_add_f32_e32 v196, v196, v84
	v_fmac_f32_e32 v197, v84, v84
	v_add_f32_e32 v130, v130, v85
	v_fmac_f32_e32 v142, v85, v85
	s_waitcnt lgkmcnt(2)
	v_lshlrev_b32_e32 v164, 16, v190
	v_and_b32_e32 v165, 0xffff0000, v190
	v_lshlrev_b32_e32 v166, 16, v191
	v_and_b32_e32 v167, 0xffff0000, v191
	v_fmac_f32_e32 v78, s58, v164
	v_fmac_f32_e32 v79, s58, v165
	v_fmac_f32_e32 v80, s58, v166
	v_fmac_f32_e32 v81, s58, v167
	v_add_f32_e32 v196, v196, v78
	v_fmac_f32_e32 v197, v78, v78
	v_add_f32_e32 v130, v130, v79
	v_fmac_f32_e32 v142, v79, v79
	v_add_f32_e32 v196, v196, v80
	v_fmac_f32_e32 v197, v80, v80
	v_add_f32_e32 v130, v130, v81
	v_fmac_f32_e32 v142, v81, v81
	s_waitcnt lgkmcnt(1)
	v_lshlrev_b32_e32 v168, 16, v192
	v_and_b32_e32 v169, 0xffff0000, v192
	v_lshlrev_b32_e32 v170, 16, v193
	v_and_b32_e32 v171, 0xffff0000, v193
	v_fmac_f32_e32 v74, s58, v168
	v_fmac_f32_e32 v75, s58, v169
	v_fmac_f32_e32 v76, s58, v170
	v_fmac_f32_e32 v77, s58, v171
	v_add_f32_e32 v196, v196, v74
	v_fmac_f32_e32 v197, v74, v74
	v_add_f32_e32 v130, v130, v75
	v_fmac_f32_e32 v142, v75, v75
	v_add_f32_e32 v196, v196, v76
	v_fmac_f32_e32 v197, v76, v76
	v_add_f32_e32 v130, v130, v77
	v_fmac_f32_e32 v142, v77, v77
	s_waitcnt lgkmcnt(0)
	v_lshlrev_b32_e32 v172, 16, v194
	v_and_b32_e32 v173, 0xffff0000, v194
	v_lshlrev_b32_e32 v174, 16, v195
	v_and_b32_e32 v175, 0xffff0000, v195
	v_fmac_f32_e32 v70, s58, v172
	v_fmac_f32_e32 v71, s58, v173
	v_fmac_f32_e32 v72, s58, v174
	v_fmac_f32_e32 v73, s58, v175
	v_add_f32_e32 v196, v196, v70
	v_fmac_f32_e32 v197, v70, v70
	v_add_f32_e32 v130, v130, v71
	v_fmac_f32_e32 v142, v71, v71
	v_add_f32_e32 v196, v196, v72
	v_fmac_f32_e32 v197, v72, v72
	v_add_f32_e32 v130, v130, v73
	v_fmac_f32_e32 v142, v73, v73
	v_add_f32_e32 v196, v196, v130
	v_add_f32_e32 v197, v197, v142
	v_mov_b32_e32 v198, v196
	v_mov_b32_e32 v199, v197
	s_nop 1
	v_permlane16_swap_b32 v198, v196
	v_permlane16_swap_b32 v199, v197
	v_add_f32_e32 v196, v196, v198
	v_add_f32_e32 v197, v197, v199
	v_mov_b32_e32 v198, v196
	v_mov_b32_e32 v199, v197
	s_nop 1
	v_permlane32_swap_b32 v198, v196
	v_permlane32_swap_b32 v199, v197
	v_add_f32_e32 v196, v196, v198
	v_add_f32_e32 v197, v197, v199
	s_mov_b64 exec, 0xffff
	ds_write_b64 v134, v[196:197]
	s_mov_b64 exec, -1
	s_waitcnt lgkmcnt(0)
	s_barrier
; DI unsigned pk2(float lo, float hi) { const f32x2 v = {lo, hi}; const bf16x2_t b = __builtin_convertvector(v, bf16x2_t); return __builtin_bit_cast(unsigned, b); }
; DI size_t xb_off(int tok, int col) { return ((size_t)(((tok >> 7) * 32 + (col >> 5)) * 128 + (tok & 127))) * 32 + (col & 31); }
; DI void unit_O(const Params& p, char* lds, int l, int tile, int glu_tiles, int tile_b) {
;     ...
;         if (half == 0) issue_x(1);
; #pragma unroll
;         for (int mh = 0; mh < 2; ++mh) {
;             const int mt = half * 2 + mh, rl = mh * 16 + l15, row = mt * 16 + l15;
;             float s = 0.f, ss = 0.f;
; #pragma unroll
;             for (int w = 0; w < 4; ++w) { const f32x4 v = *(const f32x4*)&red[rl * 16 + 4 * w]; s += v[0] + v[2]; ss += v[1] + v[3]; }
;             const float mu = s * (1.f / 1024.f);
;             const float var = ss * (1.f / 1024.f) - mu * mu;
;             const float rs = rsqrtf(var + LN_EPS);
;             float* orow = xo + (r0 + row) * 1024 + wid * 128 + quad * 4;
;             bf16_t* brow = xbo + xb_off((int)r0 + row, wid * 128) + quad * 4;
;             const float* gp = GB + wid * 128 + quad * 4;
; #pragma unroll
;             for (int nt = 0; nt < 8; ++nt) {
;                 const f32x4 g = *(const f32x4*)(gp + nt * 16), bb = *(const f32x4*)(gp + 1024 + nt * 16);
;                 f32x4 o;
; #pragma unroll
;                 for (int i = 0; i < 4; ++i) o[i] = (acc[mt][nt][i] - mu) * rs * g[i] + bb[i];
;                 if (l == 0) *(u32x2*)(brow + (nt >> 1) * 4096 + (nt & 1) * 16) = (u32x2){pk2(o[0], o[1]), pk2(o[2], o[3])};
;                 else *(f32x4*)(orow + nt * 16) = o;
;             }
;         }
	s_add_u32 s92, s96, 0x800
	s_addc_u32 s93, s97, 0
	s_add_u32 s40, s91, 0x0
	s_mov_b32 m0, s40
	s_nop 0
	global_load_lds_dwordx4 v208, s[92:93]
	s_add_u32 s92, s92, 0x2000
	s_addc_u32 s93, s93, 0
	s_add_u32 m0, m0, 0x400
	s_nop 0
	global_load_lds_dwordx4 v208, s[92:93]
	s_add_u32 s92, s92, 0x2000
	s_addc_u32 s93, s93, 0
	s_add_u32 m0, m0, 0x400
	s_nop 0
	global_load_lds_dwordx4 v208, s[92:93]
	s_add_u32 s92, s92, 0x2000
	s_addc_u32 s93, s93, 0
	s_add_u32 m0, m0, 0x400
	s_nop 0
	global_load_lds_dwordx4 v208, s[92:93]
	ds_read_b128 v[160:163], v135 offset:0
	ds_read_b128 v[164:167], v135 offset:16
	ds_read_b128 v[168:171], v135 offset:32
	ds_read_b128 v[172:175], v135 offset:48
	s_waitcnt lgkmcnt(0)
	v_add_f32_e32 v160, v160, v162
	v_add_f32_e32 v161, v161, v163
	v_add_f32_e32 v164, v164, v166
	v_add_f32_e32 v165, v165, v167
	v_add_f32_e32 v168, v168, v170
	v_add_f32_e32 v169, v169, v171
	v_add_f32_e32 v172, v172, v174
	v_add_f32_e32 v173, v173, v175
	v_add_f32_e32 v160, v160, v164
	v_add_f32_e32 v161, v161, v165
	v_add_f32_e32 v168, v168, v172
	v_add_f32_e32 v169, v169, v173
	v_add_f32_e32 v160, v160, v168
	v_add_f32_e32 v161, v161, v169
	v_mul_f32_e32 v192, 0x3a800000, v160
	v_mul_f32_e32 v193, 0x3a800000, v161
	v_fma_f32 v193, -v192, v192, v193
	v_add_f32_e32 v193, 0x3727c5ac, v193
	v_rsq_f32_e32 v193, v193
	s_nop 0
	s_add_u32 s94, s78, 0x0
	s_addc_u32 s95, s79, 0
	ds_read_b128 v[176:179], v136
	ds_read_b128 v[180:183], v136 offset:4096
	ds_read_b128 v[184:187], v136 offset:64
	ds_read_b128 v[188:191], v136 offset:4160
	s_waitcnt lgkmcnt(2)
	v_sub_f32_e32 v98, v98, v192
	v_mul_f32_e32 v98, v98, v193
	v_fma_f32 v98, v176, v98, v180
	v_sub_f32_e32 v99, v99, v192
	v_mul_f32_e32 v99, v99, v193
	v_fma_f32 v99, v177, v99, v181
	v_sub_f32_e32 v100, v100, v192
	v_mul_f32_e32 v100, v100, v193
	v_fma_f32 v100, v178, v100, v182
	v_sub_f32_e32 v101, v101, v192
	v_mul_f32_e32 v101, v101, v193
	v_fma_f32 v101, v179, v101, v183
	global_store_dwordx4 v137, v[98:101], s[94:95]
	ds_read_b128 v[176:179], v136 offset:128
	ds_read_b128 v[180:183], v136 offset:4224
	s_waitcnt lgkmcnt(2)
	v_sub_f32_e32 v94, v94, v192
	v_mul_f32_e32 v94, v94, v193
	v_fma_f32 v94, v184, v94, v188
	v_sub_f32_e32 v95, v95, v192
	v_mul_f32_e32 v95, v95, v193
	v_fma_f32 v95, v185, v95, v189
	v_sub_f32_e32 v96, v96, v192
	v_mul_f32_e32 v96, v96, v193
	v_fma_f32 v96, v186, v96, v190
	v_sub_f32_e32 v97, v97, v192
	v_mul_f32_e32 v97, v97, v193
	v_fma_f32 v97, v187, v97, v191
	global_store_dwordx4 v137, v[94:97], s[94:95] offset:64
	ds_read_b128 v[184:187], v136 offset:192
	ds_read_b128 v[188:191], v136 offset:4288
	s_waitcnt lgkmcnt(2)
	v_sub_f32_e32 v90, v90, v192
	v_mul_f32_e32 v90, v90, v193
	v_fma_f32 v90, v176, v90, v180
	v_sub_f32_e32 v91, v91, v192
	v_mul_f32_e32 v91, v91, v193
	v_fma_f32 v91, v177, v91, v181
	v_sub_f32_e32 v92, v92, v192
	v_mul_f32_e32 v92, v92, v193
	v_fma_f32 v92, v178, v92, v182
	v_sub_f32_e32 v93, v93, v192
	v_mul_f32_e32 v93, v93, v193
	v_fma_f32 v93, v179, v93, v183
	global_store_dwordx4 v137, v[90:93], s[94:95] offset:128
	ds_read_b128 v[176:179], v136 offset:256
	ds_read_b128 v[180:183], v136 offset:4352
	s_waitcnt lgkmcnt(2)
	v_sub_f32_e32 v86, v86, v192
	v_mul_f32_e32 v86, v86, v193
	v_fma_f32 v86, v184, v86, v188
	v_sub_f32_e32 v87, v87, v192
	v_mul_f32_e32 v87, v87, v193
	v_fma_f32 v87, v185, v87, v189
	v_sub_f32_e32 v88, v88, v192
	v_mul_f32_e32 v88, v88, v193
	v_fma_f32 v88, v186, v88, v190
	v_sub_f32_e32 v89, v89, v192
	v_mul_f32_e32 v89, v89, v193
	v_fma_f32 v89, v187, v89, v191
	global_store_dwordx4 v137, v[86:89], s[94:95] offset:192
	ds_read_b128 v[184:187], v136 offset:320
	ds_read_b128 v[188:191], v136 offset:4416
	s_waitcnt lgkmcnt(2)
	v_sub_f32_e32 v82, v82, v192
	v_mul_f32_e32 v82, v82, v193
	v_fma_f32 v82, v176, v82, v180
	v_sub_f32_e32 v83, v83, v192
	v_mul_f32_e32 v83, v83, v193
	v_fma_f32 v83, v177, v83, v181
	v_sub_f32_e32 v84, v84, v192
	v_mul_f32_e32 v84, v84, v193
	v_fma_f32 v84, v178, v84, v182
	v_sub_f32_e32 v85, v85, v192
	v_mul_f32_e32 v85, v85, v193
	v_fma_f32 v85, v179, v85, v183
	global_store_dwordx4 v137, v[82:85], s[94:95] offset:256
	ds_read_b128 v[176:179], v136 offset:384
	ds_read_b128 v[180:183], v136 offset:4480
	s_waitcnt lgkmcnt(2)
	v_sub_f32_e32 v78, v78, v192
	v_mul_f32_e32 v78, v78, v193
	v_fma_f32 v78, v184, v78, v188
	v_sub_f32_e32 v79, v79, v192
	v_mul_f32_e32 v79, v79, v193
	v_fma_f32 v79, v185, v79, v189
	v_sub_f32_e32 v80, v80, v192
	v_mul_f32_e32 v80, v80, v193
	v_fma_f32 v80, v186, v80, v190
	v_sub_f32_e32 v81, v81, v192
	v_mul_f32_e32 v81, v81, v193
	v_fma_f32 v81, v187, v81, v191
	global_store_dwordx4 v137, v[78:81], s[94:95] offset:320
	ds_read_b128 v[184:187], v136 offset:448
	ds_read_b128 v[188:191], v136 offset:4544
	s_waitcnt lgkmcnt(2)
	v_sub_f32_e32 v74, v74, v192
	v_mul_f32_e32 v74, v74, v193
	v_fma_f32 v74, v176, v74, v180
	v_sub_f32_e32 v75, v75, v192
	v_mul_f32_e32 v75, v75, v193
	v_fma_f32 v75, v177, v75, v181
	v_sub_f32_e32 v76, v76, v192
	v_mul_f32_e32 v76, v76, v193
	v_fma_f32 v76, v178, v76, v182
	v_sub_f32_e32 v77, v77, v192
	v_mul_f32_e32 v77, v77, v193
	v_fma_f32 v77, v179, v77, v183
	global_store_dwordx4 v137, v[74:77], s[94:95] offset:384
	s_waitcnt lgkmcnt(0)
	v_sub_f32_e32 v70, v70, v192
	v_mul_f32_e32 v70, v70, v193
	v_fma_f32 v70, v184, v70, v188
	v_sub_f32_e32 v71, v71, v192
	v_mul_f32_e32 v71, v71, v193
	v_fma_f32 v71, v185, v71, v189
	v_sub_f32_e32 v72, v72, v192
	v_mul_f32_e32 v72, v72, v193
	v_fma_f32 v72, v186, v72, v190
	v_sub_f32_e32 v73, v73, v192
	v_mul_f32_e32 v73, v73, v193
	v_fma_f32 v73, v187, v73, v191
	global_store_dwordx4 v137, v[70:73], s[94:95] offset:448
	s_waitcnt vmcnt(12) lgkmcnt(0)
	s_barrier
; DI float bf2f(unsigned b) { return __uint_as_float(b << 16); }
; DI void unit_O(const Params& p, char* lds, int l, int tile, int glu_tiles, int tile_b) {
;     ...
;         float s2[2], ss2[2];
; #pragma unroll
;         for (int mh = 0; mh < 2; ++mh) {
;             const int mt = half * 2 + mh, rl = mh * 16 + l15;
;             float s = 0.f, ss = 0.f;
; #pragma unroll
;             for (int nt = 0; nt < 8; ++nt) {
;                 f32x4 xr;
;                 if (l == 0) {
;                     const int chunk = wid * 32 + nt * 4 + quad;
;                     xr = *(const f32x4*)(XR + rl * 4096 + ((chunk ^ l15) << 4));
;                 } else {
;                     const u32x2 hb = *(const u32x2*)(XR + ((wid * 4 + (nt >> 1)) * 32 + rl) * 64 + (nt & 1) * 32 + quad * 8);
;                     xr = (f32x4){bf2f(hb[0] & 0xffffu), bf2f(hb[0] >> 16), bf2f(hb[1] & 0xffffu), bf2f(hb[1] >> 16)};
;                 }
; #pragma unroll
;                 for (int i = 0; i < 4; ++i) { const float v = acc[mt][nt][i] + DN_ALPHA * xr[i]; acc[mt][nt][i] = v; s += v; ss += v * v; }
;             }
;             s2[mh] = s; ss2[mh] = ss;
;         }
; #pragma unroll
;         for (int mh = 0; mh < 2; ++mh) { s2[mh] += __shfl_xor(s2[mh], 16); ss2[mh] += __shfl_xor(ss2[mh], 16); }
; #pragma unroll
;         for (int mh = 0; mh < 2; ++mh) { s2[mh] += __shfl_xor(s2[mh], 32); ss2[mh] += __shfl_xor(ss2[mh], 32); }
;         if (quad == 0) {
; #pragma unroll
;             for (int mh = 0; mh < 2; ++mh) *(f32x2*)&red[((mh * 16 + l15) * 8 + wid) * 2] = (f32x2){s2[mh], ss2[mh]};
;         }
;         __syncthreads();
	ds_read_b64 v[180:181], v133 offset:32768
	ds_read_b64 v[182:183], v133 offset:32800
	ds_read_b64 v[184:185], v133 offset:33792
	ds_read_b64 v[186:187], v133 offset:33824
	ds_read_b64 v[188:189], v133 offset:34816
	ds_read_b64 v[190:191], v133 offset:34848
	ds_read_b64 v[192:193], v133 offset:35840
	ds_read_b64 v[194:195], v133 offset:35872
	s_waitcnt lgkmcnt(7)
	v_lshlrev_b32_e32 v144, 16, v180
	v_and_b32_e32 v145, 0xffff0000, v180
	v_lshlrev_b32_e32 v146, 16, v181
	v_and_b32_e32 v147, 0xffff0000, v181
	v_fmac_f32_e32 v126, s58, v144
	v_fmac_f32_e32 v127, s58, v145
	v_fmac_f32_e32 v128, s58, v146
	v_fmac_f32_e32 v129, s58, v147
	v_mov_b32_e32 v196, v126
	v_mul_f32_e32 v197, v126, v126
	v_mov_b32_e32 v130, v127
	v_mul_f32_e32 v142, v127, v127
	v_add_f32_e32 v196, v196, v128
	v_fmac_f32_e32 v197, v128, v128
	v_add_f32_e32 v130, v130, v129
	v_fmac_f32_e32 v142, v129, v129
	s_waitcnt lgkmcnt(6)
	v_lshlrev_b32_e32 v148, 16, v182
	v_and_b32_e32 v149, 0xffff0000, v182
	v_lshlrev_b32_e32 v150, 16, v183
	v_and_b32_e32 v151, 0xffff0000, v183
	v_fmac_f32_e32 v122, s58, v148
	v_fmac_f32_e32 v123, s58, v149
	v_fmac_f32_e32 v124, s58, v150
	v_fmac_f32_e32 v125, s58, v151
	v_add_f32_e32 v196, v196, v122
	v_fmac_f32_e32 v197, v122, v122
	v_add_f32_e32 v130, v130, v123
	v_fmac_f32_e32 v142, v123, v123
	v_add_f32_e32 v196, v196, v124
	v_fmac_f32_e32 v197, v124, v124
	v_add_f32_e32 v130, v130, v125
	v_fmac_f32_e32 v142, v125, v125
	s_waitcnt lgkmcnt(5)
	v_lshlrev_b32_e32 v152, 16, v184
	v_and_b32_e32 v153, 0xffff0000, v184
	v_lshlrev_b32_e32 v154, 16, v185
	v_and_b32_e32 v155, 0xffff0000, v185
	v_fmac_f32_e32 v118, s58, v152
	v_fmac_f32_e32 v119, s58, v153
	v_fmac_f32_e32 v120, s58, v154
	v_fmac_f32_e32 v121, s58, v155
	v_add_f32_e32 v196, v196, v118
	v_fmac_f32_e32 v197, v118, v118
	v_add_f32_e32 v130, v130, v119
	v_fmac_f32_e32 v142, v119, v119
	v_add_f32_e32 v196, v196, v120
	v_fmac_f32_e32 v197, v120, v120
	v_add_f32_e32 v130, v130, v121
	v_fmac_f32_e32 v142, v121, v121
	s_waitcnt lgkmcnt(4)
	v_lshlrev_b32_e32 v156, 16, v186
	v_and_b32_e32 v157, 0xffff0000, v186
	v_lshlrev_b32_e32 v158, 16, v187
	v_and_b32_e32 v159, 0xffff0000, v187
	v_fmac_f32_e32 v114, s58, v156
	v_fmac_f32_e32 v115, s58, v157
	v_fmac_f32_e32 v116, s58, v158
	v_fmac_f32_e32 v117, s58, v159
	v_add_f32_e32 v196, v196, v114
	v_fmac_f32_e32 v197, v114, v114
	v_add_f32_e32 v130, v130, v115
	v_fmac_f32_e32 v142, v115, v115
	v_add_f32_e32 v196, v196, v116
	v_fmac_f32_e32 v197, v116, v116
	v_add_f32_e32 v130, v130, v117
	v_fmac_f32_e32 v142, v117, v117
	s_waitcnt lgkmcnt(3)
	v_lshlrev_b32_e32 v160, 16, v188
	v_and_b32_e32 v161, 0xffff0000, v188
	v_lshlrev_b32_e32 v162, 16, v189
	v_and_b32_e32 v163, 0xffff0000, v189
	v_fmac_f32_e32 v110, s58, v160
	v_fmac_f32_e32 v111, s58, v161
	v_fmac_f32_e32 v112, s58, v162
	v_fmac_f32_e32 v113, s58, v163
	v_add_f32_e32 v196, v196, v110
	v_fmac_f32_e32 v197, v110, v110
	v_add_f32_e32 v130, v130, v111
	v_fmac_f32_e32 v142, v111, v111
	v_add_f32_e32 v196, v196, v112
	v_fmac_f32_e32 v197, v112, v112
	v_add_f32_e32 v130, v130, v113
	v_fmac_f32_e32 v142, v113, v113
	s_waitcnt lgkmcnt(2)
	v_lshlrev_b32_e32 v164, 16, v190
	v_and_b32_e32 v165, 0xffff0000, v190
	v_lshlrev_b32_e32 v166, 16, v191
	v_and_b32_e32 v167, 0xffff0000, v191
	v_fmac_f32_e32 v106, s58, v164
	v_fmac_f32_e32 v107, s58, v165
	v_fmac_f32_e32 v108, s58, v166
	v_fmac_f32_e32 v109, s58, v167
	v_add_f32_e32 v196, v196, v106
	v_fmac_f32_e32 v197, v106, v106
	v_add_f32_e32 v130, v130, v107
	v_fmac_f32_e32 v142, v107, v107
	v_add_f32_e32 v196, v196, v108
	v_fmac_f32_e32 v197, v108, v108
	v_add_f32_e32 v130, v130, v109
	v_fmac_f32_e32 v142, v109, v109
	s_waitcnt lgkmcnt(1)
	v_lshlrev_b32_e32 v168, 16, v192
	v_and_b32_e32 v169, 0xffff0000, v192
	v_lshlrev_b32_e32 v170, 16, v193
	v_and_b32_e32 v171, 0xffff0000, v193
	v_fmac_f32_e32 v102, s58, v168
	v_fmac_f32_e32 v103, s58, v169
	v_fmac_f32_e32 v104, s58, v170
	v_fmac_f32_e32 v105, s58, v171
	v_add_f32_e32 v196, v196, v102
	v_fmac_f32_e32 v197, v102, v102
	v_add_f32_e32 v130, v130, v103
	v_fmac_f32_e32 v142, v103, v103
	v_add_f32_e32 v196, v196, v104
	v_fmac_f32_e32 v197, v104, v104
	v_add_f32_e32 v130, v130, v105
	v_fmac_f32_e32 v142, v105, v105
	s_waitcnt lgkmcnt(0)
	v_lshlrev_b32_e32 v172, 16, v194
	v_and_b32_e32 v173, 0xffff0000, v194
	v_lshlrev_b32_e32 v174, 16, v195
	v_and_b32_e32 v175, 0xffff0000, v195
	v_fmac_f32_e32 v66, s58, v172
	v_fmac_f32_e32 v67, s58, v173
	v_fmac_f32_e32 v68, s58, v174
	v_fmac_f32_e32 v69, s58, v175
	v_add_f32_e32 v196, v196, v66
	v_fmac_f32_e32 v197, v66, v66
	v_add_f32_e32 v130, v130, v67
	v_fmac_f32_e32 v142, v67, v67
	v_add_f32_e32 v196, v196, v68
	v_fmac_f32_e32 v197, v68, v68
	v_add_f32_e32 v130, v130, v69
	v_fmac_f32_e32 v142, v69, v69
	v_add_f32_e32 v196, v196, v130
	v_add_f32_e32 v197, v197, v142
	v_mov_b32_e32 v198, v196
	v_mov_b32_e32 v199, v197
	s_nop 1
	v_permlane16_swap_b32 v198, v196
	v_permlane16_swap_b32 v199, v197
	v_add_f32_e32 v196, v196, v198
	v_add_f32_e32 v197, v197, v199
	v_mov_b32_e32 v198, v196
	v_mov_b32_e32 v199, v197
	s_nop 1
	v_permlane32_swap_b32 v198, v196
	v_permlane32_swap_b32 v199, v197
	v_add_f32_e32 v196, v196, v198
	v_add_f32_e32 v197, v197, v199
	s_mov_b64 exec, 0xffff
	ds_write_b64 v134, v[196:197]
	s_mov_b64 exec, -1
	s_waitcnt lgkmcnt(0)
	s_barrier
; DI unsigned pk2(float lo, float hi) { const f32x2 v = {lo, hi}; const bf16x2_t b = __builtin_convertvector(v, bf16x2_t); return __builtin_bit_cast(unsigned, b); }
; DI size_t xb_off(int tok, int col) { return ((size_t)(((tok >> 7) * 32 + (col >> 5)) * 128 + (tok & 127))) * 32 + (col & 31); }
; DI void unit_O(const Params& p, char* lds, int l, int tile, int glu_tiles, int tile_b) {
;     ...
;         if (half == 0) issue_x(1);
; #pragma unroll
;         for (int mh = 0; mh < 2; ++mh) {
;             const int mt = half * 2 + mh, rl = mh * 16 + l15, row = mt * 16 + l15;
;             float s = 0.f, ss = 0.f;
; #pragma unroll
;             for (int w = 0; w < 4; ++w) { const f32x4 v = *(const f32x4*)&red[rl * 16 + 4 * w]; s += v[0] + v[2]; ss += v[1] + v[3]; }
;             const float mu = s * (1.f / 1024.f);
;             const float var = ss * (1.f / 1024.f) - mu * mu;
;             const float rs = rsqrtf(var + LN_EPS);
;             float* orow = xo + (r0 + row) * 1024 + wid * 128 + quad * 4;
;             bf16_t* brow = xbo + xb_off((int)r0 + row, wid * 128) + quad * 4;
;             const float* gp = GB + wid * 128 + quad * 4;
; #pragma unroll
;             for (int nt = 0; nt < 8; ++nt) {
;                 const f32x4 g = *(const f32x4*)(gp + nt * 16), bb = *(const f32x4*)(gp + 1024 + nt * 16);
;                 f32x4 o;
; #pragma unroll
;                 for (int i = 0; i < 4; ++i) o[i] = (acc[mt][nt][i] - mu) * rs * g[i] + bb[i];
;                 if (l == 0) *(u32x2*)(brow + (nt >> 1) * 4096 + (nt & 1) * 16) = (u32x2){pk2(o[0], o[1]), pk2(o[2], o[3])};
;                 else *(f32x4*)(orow + nt * 16) = o;
;             }
;         }
	s_add_u32 s92, s96, 0xc00
	s_addc_u32 s93, s97, 0
	s_add_u32 s40, s91, 0x8000
	s_mov_b32 m0, s40
	s_nop 0
	global_load_lds_dwordx4 v208, s[92:93]
	s_add_u32 s92, s92, 0x2000
	s_addc_u32 s93, s93, 0
	s_add_u32 m0, m0, 0x400
	s_nop 0
	global_load_lds_dwordx4 v208, s[92:93]
	s_add_u32 s92, s92, 0x2000
	s_addc_u32 s93, s93, 0
	s_add_u32 m0, m0, 0x400
	s_nop 0
	global_load_lds_dwordx4 v208, s[92:93]
	s_add_u32 s92, s92, 0x2000
	s_addc_u32 s93, s93, 0
	s_add_u32 m0, m0, 0x400
	s_nop 0
	global_load_lds_dwordx4 v208, s[92:93]
	ds_read_b128 v[160:163], v135 offset:0
	ds_read_b128 v[164:167], v135 offset:16
	ds_read_b128 v[168:171], v135 offset:32
	ds_read_b128 v[172:175], v135 offset:48
	s_waitcnt lgkmcnt(0)
	v_add_f32_e32 v160, v160, v162
	v_add_f32_e32 v161, v161, v163
	v_add_f32_e32 v164, v164, v166
	v_add_f32_e32 v165, v165, v167
	v_add_f32_e32 v168, v168, v170
	v_add_f32_e32 v169, v169, v171
	v_add_f32_e32 v172, v172, v174
	v_add_f32_e32 v173, v173, v175
	v_add_f32_e32 v160, v160, v164
	v_add_f32_e32 v161, v161, v165
	v_add_f32_e32 v168, v168, v172
	v_add_f32_e32 v169, v169, v173
	v_add_f32_e32 v160, v160, v168
	v_add_f32_e32 v161, v161, v169
	v_mul_f32_e32 v192, 0x3a800000, v160
	v_mul_f32_e32 v193, 0x3a800000, v161
	v_fma_f32 v193, -v192, v192, v193
	v_add_f32_e32 v193, 0x3727c5ac, v193
	v_rsq_f32_e32 v193, v193
	s_nop 0
	s_add_u32 s94, s78, 0x10000
	s_addc_u32 s95, s79, 0
	ds_read_b128 v[176:179], v136
	ds_read_b128 v[180:183], v136 offset:4096
	ds_read_b128 v[184:187], v136 offset:64
	ds_read_b128 v[188:191], v136 offset:4160
	s_waitcnt lgkmcnt(2)
	v_sub_f32_e32 v126, v126, v192
	v_mul_f32_e32 v126, v126, v193
	v_fma_f32 v126, v176, v126, v180
	v_sub_f32_e32 v127, v127, v192
	v_mul_f32_e32 v127, v127, v193
	v_fma_f32 v127, v177, v127, v181
	v_sub_f32_e32 v128, v128, v192
	v_mul_f32_e32 v128, v128, v193
	v_fma_f32 v128, v178, v128, v182
	v_sub_f32_e32 v129, v129, v192
	v_mul_f32_e32 v129, v129, v193
	v_fma_f32 v129, v179, v129, v183
	global_store_dwordx4 v137, v[126:129], s[94:95]
	ds_read_b128 v[176:179], v136 offset:128
	ds_read_b128 v[180:183], v136 offset:4224
	s_waitcnt lgkmcnt(2)
	v_sub_f32_e32 v122, v122, v192
	v_mul_f32_e32 v122, v122, v193
	v_fma_f32 v122, v184, v122, v188
	v_sub_f32_e32 v123, v123, v192
	v_mul_f32_e32 v123, v123, v193
	v_fma_f32 v123, v185, v123, v189
	v_sub_f32_e32 v124, v124, v192
	v_mul_f32_e32 v124, v124, v193
	v_fma_f32 v124, v186, v124, v190
	v_sub_f32_e32 v125, v125, v192
	v_mul_f32_e32 v125, v125, v193
	v_fma_f32 v125, v187, v125, v191
	global_store_dwordx4 v137, v[122:125], s[94:95] offset:64
	ds_read_b128 v[184:187], v136 offset:192
	ds_read_b128 v[188:191], v136 offset:4288
	s_waitcnt lgkmcnt(2)
	v_sub_f32_e32 v118, v118, v192
	v_mul_f32_e32 v118, v118, v193
	v_fma_f32 v118, v176, v118, v180
	v_sub_f32_e32 v119, v119, v192
	v_mul_f32_e32 v119, v119, v193
	v_fma_f32 v119, v177, v119, v181
	v_sub_f32_e32 v120, v120, v192
	v_mul_f32_e32 v120, v120, v193
	v_fma_f32 v120, v178, v120, v182
	v_sub_f32_e32 v121, v121, v192
	v_mul_f32_e32 v121, v121, v193
	v_fma_f32 v121, v179, v121, v183
	global_store_dwordx4 v137, v[118:121], s[94:95] offset:128
	ds_read_b128 v[176:179], v136 offset:256
	ds_read_b128 v[180:183], v136 offset:4352
	s_waitcnt lgkmcnt(2)
	v_sub_f32_e32 v114, v114, v192
	v_mul_f32_e32 v114, v114, v193
	v_fma_f32 v114, v184, v114, v188
	v_sub_f32_e32 v115, v115, v192
	v_mul_f32_e32 v115, v115, v193
	v_fma_f32 v115, v185, v115, v189
	v_sub_f32_e32 v116, v116, v192
	v_mul_f32_e32 v116, v116, v193
	v_fma_f32 v116, v186, v116, v190
	v_sub_f32_e32 v117, v117, v192
	v_mul_f32_e32 v117, v117, v193
	v_fma_f32 v117, v187, v117, v191
	global_store_dwordx4 v137, v[114:117], s[94:95] offset:192
	ds_read_b128 v[184:187], v136 offset:320
	ds_read_b128 v[188:191], v136 offset:4416
	s_waitcnt lgkmcnt(2)
	v_sub_f32_e32 v110, v110, v192
	v_mul_f32_e32 v110, v110, v193
	v_fma_f32 v110, v176, v110, v180
	v_sub_f32_e32 v111, v111, v192
	v_mul_f32_e32 v111, v111, v193
	v_fma_f32 v111, v177, v111, v181
	v_sub_f32_e32 v112, v112, v192
	v_mul_f32_e32 v112, v112, v193
	v_fma_f32 v112, v178, v112, v182
	v_sub_f32_e32 v113, v113, v192
	v_mul_f32_e32 v113, v113, v193
	v_fma_f32 v113, v179, v113, v183
	global_store_dwordx4 v137, v[110:113], s[94:95] offset:256
	ds_read_b128 v[176:179], v136 offset:384
	ds_read_b128 v[180:183], v136 offset:4480
	s_waitcnt lgkmcnt(2)
	v_sub_f32_e32 v106, v106, v192
	v_mul_f32_e32 v106, v106, v193
	v_fma_f32 v106, v184, v106, v188
	v_sub_f32_e32 v107, v107, v192
	v_mul_f32_e32 v107, v107, v193
	v_fma_f32 v107, v185, v107, v189
	v_sub_f32_e32 v108, v108, v192
	v_mul_f32_e32 v108, v108, v193
	v_fma_f32 v108, v186, v108, v190
	v_sub_f32_e32 v109, v109, v192
	v_mul_f32_e32 v109, v109, v193
	v_fma_f32 v109, v187, v109, v191
	global_store_dwordx4 v137, v[106:109], s[94:95] offset:320
	ds_read_b128 v[184:187], v136 offset:448
	ds_read_b128 v[188:191], v136 offset:4544
	s_waitcnt lgkmcnt(2)
	v_sub_f32_e32 v102, v102, v192
	v_mul_f32_e32 v102, v102, v193
	v_fma_f32 v102, v176, v102, v180
	v_sub_f32_e32 v103, v103, v192
	v_mul_f32_e32 v103, v103, v193
	v_fma_f32 v103, v177, v103, v181
	v_sub_f32_e32 v104, v104, v192
	v_mul_f32_e32 v104, v104, v193
	v_fma_f32 v104, v178, v104, v182
	v_sub_f32_e32 v105, v105, v192
	v_mul_f32_e32 v105, v105, v193
	v_fma_f32 v105, v179, v105, v183
	global_store_dwordx4 v137, v[102:105], s[94:95] offset:384
	s_waitcnt lgkmcnt(0)
	v_sub_f32_e32 v66, v66, v192
	v_mul_f32_e32 v66, v66, v193
	v_fma_f32 v66, v184, v66, v188
	v_sub_f32_e32 v67, v67, v192
	v_mul_f32_e32 v67, v67, v193
	v_fma_f32 v67, v185, v67, v189
	v_sub_f32_e32 v68, v68, v192
	v_mul_f32_e32 v68, v68, v193
	v_fma_f32 v68, v186, v68, v190
	v_sub_f32_e32 v69, v69, v192
	v_mul_f32_e32 v69, v69, v193
	v_fma_f32 v69, v187, v69, v191
	global_store_dwordx4 v137, v[66:69], s[94:95] offset:448
	s_waitcnt vmcnt(20) lgkmcnt(0)
	s_barrier
; DI float bf2f(unsigned b) { return __uint_as_float(b << 16); }
; DI void unit_O(const Params& p, char* lds, int l, int tile, int glu_tiles, int tile_b) {
;     ...
;         float s2[2], ss2[2];
; #pragma unroll
;         for (int mh = 0; mh < 2; ++mh) {
;             const int mt = half * 2 + mh, rl = mh * 16 + l15;
;             float s = 0.f, ss = 0.f;
; #pragma unroll
;             for (int nt = 0; nt < 8; ++nt) {
;                 f32x4 xr;
;                 if (l == 0) {
;                     const int chunk = wid * 32 + nt * 4 + quad;
;                     xr = *(const f32x4*)(XR + rl * 4096 + ((chunk ^ l15) << 4));
;                 } else {
;                     const u32x2 hb = *(const u32x2*)(XR + ((wid * 4 + (nt >> 1)) * 32 + rl) * 64 + (nt & 1) * 32 + quad * 8);
;                     xr = (f32x4){bf2f(hb[0] & 0xffffu), bf2f(hb[0] >> 16), bf2f(hb[1] & 0xffffu), bf2f(hb[1] >> 16)};
;                 }
; #pragma unroll
;                 for (int i = 0; i < 4; ++i) { const float v = acc[mt][nt][i] + DN_ALPHA * xr[i]; acc[mt][nt][i] = v; s += v; ss += v * v; }
;             }
;             s2[mh] = s; ss2[mh] = ss;
;         }
; #pragma unroll
;         for (int mh = 0; mh < 2; ++mh) { s2[mh] += __shfl_xor(s2[mh], 16); ss2[mh] += __shfl_xor(ss2[mh], 16); }
; #pragma unroll
;         for (int mh = 0; mh < 2; ++mh) { s2[mh] += __shfl_xor(s2[mh], 32); ss2[mh] += __shfl_xor(ss2[mh], 32); }
;         if (quad == 0) {
; #pragma unroll
;             for (int mh = 0; mh < 2; ++mh) *(f32x2*)&red[((mh * 16 + l15) * 8 + wid) * 2] = (f32x2){s2[mh], ss2[mh]};
;         }
;         __syncthreads();
	ds_read_b64 v[180:181], v133 offset:0
	ds_read_b64 v[182:183], v133 offset:32
	ds_read_b64 v[184:185], v133 offset:1024
	ds_read_b64 v[186:187], v133 offset:1056
	ds_read_b64 v[188:189], v133 offset:2048
	ds_read_b64 v[190:191], v133 offset:2080
	ds_read_b64 v[192:193], v133 offset:3072
	ds_read_b64 v[194:195], v133 offset:3104
	s_waitcnt lgkmcnt(7)
	v_lshlrev_b32_e32 v144, 16, v180
	v_and_b32_e32 v145, 0xffff0000, v180
	v_lshlrev_b32_e32 v146, 16, v181
	v_and_b32_e32 v147, 0xffff0000, v181
	v_fmac_f32_e32 v34, s58, v144
	v_fmac_f32_e32 v35, s58, v145
	v_fmac_f32_e32 v36, s58, v146
	v_fmac_f32_e32 v37, s58, v147
	v_mov_b32_e32 v196, v34
	v_mul_f32_e32 v197, v34, v34
	v_mov_b32_e32 v130, v35
	v_mul_f32_e32 v142, v35, v35
	v_add_f32_e32 v196, v196, v36
	v_fmac_f32_e32 v197, v36, v36
	v_add_f32_e32 v130, v130, v37
	v_fmac_f32_e32 v142, v37, v37
	s_waitcnt lgkmcnt(6)
	v_lshlrev_b32_e32 v148, 16, v182
	v_and_b32_e32 v149, 0xffff0000, v182
	v_lshlrev_b32_e32 v150, 16, v183
	v_and_b32_e32 v151, 0xffff0000, v183
	v_fmac_f32_e32 v30, s58, v148
	v_fmac_f32_e32 v31, s58, v149
	v_fmac_f32_e32 v32, s58, v150
	v_fmac_f32_e32 v33, s58, v151
	v_add_f32_e32 v196, v196, v30
	v_fmac_f32_e32 v197, v30, v30
	v_add_f32_e32 v130, v130, v31
	v_fmac_f32_e32 v142, v31, v31
	v_add_f32_e32 v196, v196, v32
	v_fmac_f32_e32 v197, v32, v32
	v_add_f32_e32 v130, v130, v33
	v_fmac_f32_e32 v142, v33, v33
	s_waitcnt lgkmcnt(5)
	v_lshlrev_b32_e32 v152, 16, v184
	v_and_b32_e32 v153, 0xffff0000, v184
	v_lshlrev_b32_e32 v154, 16, v185
	v_and_b32_e32 v155, 0xffff0000, v185
	v_fmac_f32_e32 v26, s58, v152
	v_fmac_f32_e32 v27, s58, v153
	v_fmac_f32_e32 v28, s58, v154
	v_fmac_f32_e32 v29, s58, v155
	v_add_f32_e32 v196, v196, v26
	v_fmac_f32_e32 v197, v26, v26
	v_add_f32_e32 v130, v130, v27
	v_fmac_f32_e32 v142, v27, v27
	v_add_f32_e32 v196, v196, v28
	v_fmac_f32_e32 v197, v28, v28
	v_add_f32_e32 v130, v130, v29
	v_fmac_f32_e32 v142, v29, v29
	s_waitcnt lgkmcnt(4)
	v_lshlrev_b32_e32 v156, 16, v186
	v_and_b32_e32 v157, 0xffff0000, v186
	v_lshlrev_b32_e32 v158, 16, v187
	v_and_b32_e32 v159, 0xffff0000, v187
	v_fmac_f32_e32 v22, s58, v156
	v_fmac_f32_e32 v23, s58, v157
	v_fmac_f32_e32 v24, s58, v158
	v_fmac_f32_e32 v25, s58, v159
	v_add_f32_e32 v196, v196, v22
	v_fmac_f32_e32 v197, v22, v22
	v_add_f32_e32 v130, v130, v23
	v_fmac_f32_e32 v142, v23, v23
	v_add_f32_e32 v196, v196, v24
	v_fmac_f32_e32 v197, v24, v24
	v_add_f32_e32 v130, v130, v25
	v_fmac_f32_e32 v142, v25, v25
	s_waitcnt lgkmcnt(3)
	v_lshlrev_b32_e32 v160, 16, v188
	v_and_b32_e32 v161, 0xffff0000, v188
	v_lshlrev_b32_e32 v162, 16, v189
	v_and_b32_e32 v163, 0xffff0000, v189
	v_fmac_f32_e32 v18, s58, v160
	v_fmac_f32_e32 v19, s58, v161
	v_fmac_f32_e32 v20, s58, v162
	v_fmac_f32_e32 v21, s58, v163
	v_add_f32_e32 v196, v196, v18
	v_fmac_f32_e32 v197, v18, v18
	v_add_f32_e32 v130, v130, v19
	v_fmac_f32_e32 v142, v19, v19
	v_add_f32_e32 v196, v196, v20
	v_fmac_f32_e32 v197, v20, v20
	v_add_f32_e32 v130, v130, v21
	v_fmac_f32_e32 v142, v21, v21
	s_waitcnt lgkmcnt(2)
	v_lshlrev_b32_e32 v164, 16, v190
	v_and_b32_e32 v165, 0xffff0000, v190
	v_lshlrev_b32_e32 v166, 16, v191
	v_and_b32_e32 v167, 0xffff0000, v191
	v_fmac_f32_e32 v14, s58, v164
	v_fmac_f32_e32 v15, s58, v165
	v_fmac_f32_e32 v16, s58, v166
	v_fmac_f32_e32 v17, s58, v167
	v_add_f32_e32 v196, v196, v14
	v_fmac_f32_e32 v197, v14, v14
	v_add_f32_e32 v130, v130, v15
	v_fmac_f32_e32 v142, v15, v15
	v_add_f32_e32 v196, v196, v16
	v_fmac_f32_e32 v197, v16, v16
	v_add_f32_e32 v130, v130, v17
	v_fmac_f32_e32 v142, v17, v17
	s_waitcnt lgkmcnt(1)
	v_lshlrev_b32_e32 v168, 16, v192
	v_and_b32_e32 v169, 0xffff0000, v192
	v_lshlrev_b32_e32 v170, 16, v193
	v_and_b32_e32 v171, 0xffff0000, v193
	v_fmac_f32_e32 v10, s58, v168
	v_fmac_f32_e32 v11, s58, v169
	v_fmac_f32_e32 v12, s58, v170
	v_fmac_f32_e32 v13, s58, v171
	v_add_f32_e32 v196, v196, v10
	v_fmac_f32_e32 v197, v10, v10
	v_add_f32_e32 v130, v130, v11
	v_fmac_f32_e32 v142, v11, v11
	v_add_f32_e32 v196, v196, v12
	v_fmac_f32_e32 v197, v12, v12
	v_add_f32_e32 v130, v130, v13
	v_fmac_f32_e32 v142, v13, v13
	s_waitcnt lgkmcnt(0)
	v_lshlrev_b32_e32 v172, 16, v194
	v_and_b32_e32 v173, 0xffff0000, v194
	v_lshlrev_b32_e32 v174, 16, v195
	v_and_b32_e32 v175, 0xffff0000, v195
	v_fmac_f32_e32 v6, s58, v172
	v_fmac_f32_e32 v7, s58, v173
	v_fmac_f32_e32 v8, s58, v174
	v_fmac_f32_e32 v9, s58, v175
	v_add_f32_e32 v196, v196, v6
	v_fmac_f32_e32 v197, v6, v6
	v_add_f32_e32 v130, v130, v7
	v_fmac_f32_e32 v142, v7, v7
	v_add_f32_e32 v196, v196, v8
	v_fmac_f32_e32 v197, v8, v8
	v_add_f32_e32 v130, v130, v9
	v_fmac_f32_e32 v142, v9, v9
	v_add_f32_e32 v196, v196, v130
	v_add_f32_e32 v197, v197, v142
	v_mov_b32_e32 v198, v196
	v_mov_b32_e32 v199, v197
	s_nop 1
	v_permlane16_swap_b32 v198, v196
	v_permlane16_swap_b32 v199, v197
	v_add_f32_e32 v196, v196, v198
	v_add_f32_e32 v197, v197, v199
	v_mov_b32_e32 v198, v196
	v_mov_b32_e32 v199, v197
	s_nop 1
	v_permlane32_swap_b32 v198, v196
	v_permlane32_swap_b32 v199, v197
	v_add_f32_e32 v196, v196, v198
	v_add_f32_e32 v197, v197, v199
	s_mov_b64 exec, 0xffff
	ds_write_b64 v134, v[196:197]
	s_mov_b64 exec, -1
	s_waitcnt lgkmcnt(0)
	s_barrier
; DI unsigned pk2(float lo, float hi) { const f32x2 v = {lo, hi}; const bf16x2_t b = __builtin_convertvector(v, bf16x2_t); return __builtin_bit_cast(unsigned, b); }
; DI size_t xb_off(int tok, int col) { return ((size_t)(((tok >> 7) * 32 + (col >> 5)) * 128 + (tok & 127))) * 32 + (col & 31); }
; DI void unit_O(const Params& p, char* lds, int l, int tile, int glu_tiles, int tile_b) {
;     ...
; #pragma unroll
;         for (int mh = 0; mh < 2; ++mh) {
;             const int mt = half * 2 + mh, rl = mh * 16 + l15, row = mt * 16 + l15;
;             float s = 0.f, ss = 0.f;
; #pragma unroll
;             for (int w = 0; w < 4; ++w) { const f32x4 v = *(const f32x4*)&red[rl * 16 + 4 * w]; s += v[0] + v[2]; ss += v[1] + v[3]; }
;             const float mu = s * (1.f / 1024.f);
;             const float var = ss * (1.f / 1024.f) - mu * mu;
;             const float rs = rsqrtf(var + LN_EPS);
;             float* orow = xo + (r0 + row) * 1024 + wid * 128 + quad * 4;
;             bf16_t* brow = xbo + xb_off((int)r0 + row, wid * 128) + quad * 4;
;             const float* gp = GB + wid * 128 + quad * 4;
; #pragma unroll
;             for (int nt = 0; nt < 8; ++nt) {
;                 const f32x4 g = *(const f32x4*)(gp + nt * 16), bb = *(const f32x4*)(gp + 1024 + nt * 16);
;                 f32x4 o;
; #pragma unroll
;                 for (int i = 0; i < 4; ++i) o[i] = (acc[mt][nt][i] - mu) * rs * g[i] + bb[i];
;                 if (l == 0) *(u32x2*)(brow + (nt >> 1) * 4096 + (nt & 1) * 16) = (u32x2){pk2(o[0], o[1]), pk2(o[2], o[3])};
;                 else *(f32x4*)(orow + nt * 16) = o;
;             }
;         }
	ds_read_b128 v[160:163], v135 offset:0
	ds_read_b128 v[164:167], v135 offset:16
	ds_read_b128 v[168:171], v135 offset:32
	ds_read_b128 v[172:175], v135 offset:48
	s_waitcnt lgkmcnt(0)
	v_add_f32_e32 v160, v160, v162
	v_add_f32_e32 v161, v161, v163
	v_add_f32_e32 v164, v164, v166
	v_add_f32_e32 v165, v165, v167
	v_add_f32_e32 v168, v168, v170
	v_add_f32_e32 v169, v169, v171
	v_add_f32_e32 v172, v172, v174
	v_add_f32_e32 v173, v173, v175
	v_add_f32_e32 v160, v160, v164
	v_add_f32_e32 v161, v161, v165
	v_add_f32_e32 v168, v168, v172
	v_add_f32_e32 v169, v169, v173
	v_add_f32_e32 v160, v160, v168
	v_add_f32_e32 v161, v161, v169
	v_mul_f32_e32 v192, 0x3a800000, v160
	v_mul_f32_e32 v193, 0x3a800000, v161
	v_fma_f32 v193, -v192, v192, v193
	v_add_f32_e32 v193, 0x3727c5ac, v193
	v_rsq_f32_e32 v193, v193
	s_nop 0
	s_add_u32 s94, s78, 0x20000
	s_addc_u32 s95, s79, 0
	ds_read_b128 v[176:179], v136
	ds_read_b128 v[180:183], v136 offset:4096
	ds_read_b128 v[184:187], v136 offset:64
	ds_read_b128 v[188:191], v136 offset:4160
	s_waitcnt lgkmcnt(2)
	v_sub_f32_e32 v34, v34, v192
	v_mul_f32_e32 v34, v34, v193
	v_fma_f32 v34, v176, v34, v180
	v_sub_f32_e32 v35, v35, v192
	v_mul_f32_e32 v35, v35, v193
	v_fma_f32 v35, v177, v35, v181
	v_sub_f32_e32 v36, v36, v192
	v_mul_f32_e32 v36, v36, v193
	v_fma_f32 v36, v178, v36, v182
	v_sub_f32_e32 v37, v37, v192
	v_mul_f32_e32 v37, v37, v193
	v_fma_f32 v37, v179, v37, v183
	global_store_dwordx4 v137, v[34:37], s[94:95]
	ds_read_b128 v[176:179], v136 offset:128
	ds_read_b128 v[180:183], v136 offset:4224
	s_waitcnt lgkmcnt(2)
	v_sub_f32_e32 v30, v30, v192
	v_mul_f32_e32 v30, v30, v193
	v_fma_f32 v30, v184, v30, v188
	v_sub_f32_e32 v31, v31, v192
	v_mul_f32_e32 v31, v31, v193
	v_fma_f32 v31, v185, v31, v189
	v_sub_f32_e32 v32, v32, v192
	v_mul_f32_e32 v32, v32, v193
	v_fma_f32 v32, v186, v32, v190
	v_sub_f32_e32 v33, v33, v192
	v_mul_f32_e32 v33, v33, v193
	v_fma_f32 v33, v187, v33, v191
	global_store_dwordx4 v137, v[30:33], s[94:95] offset:64
	ds_read_b128 v[184:187], v136 offset:192
	ds_read_b128 v[188:191], v136 offset:4288
	s_waitcnt lgkmcnt(2)
	v_sub_f32_e32 v26, v26, v192
	v_mul_f32_e32 v26, v26, v193
	v_fma_f32 v26, v176, v26, v180
	v_sub_f32_e32 v27, v27, v192
	v_mul_f32_e32 v27, v27, v193
	v_fma_f32 v27, v177, v27, v181
	v_sub_f32_e32 v28, v28, v192
	v_mul_f32_e32 v28, v28, v193
	v_fma_f32 v28, v178, v28, v182
	v_sub_f32_e32 v29, v29, v192
	v_mul_f32_e32 v29, v29, v193
	v_fma_f32 v29, v179, v29, v183
	global_store_dwordx4 v137, v[26:29], s[94:95] offset:128
	ds_read_b128 v[176:179], v136 offset:256
	ds_read_b128 v[180:183], v136 offset:4352
	s_waitcnt lgkmcnt(2)
	v_sub_f32_e32 v22, v22, v192
	v_mul_f32_e32 v22, v22, v193
	v_fma_f32 v22, v184, v22, v188
	v_sub_f32_e32 v23, v23, v192
	v_mul_f32_e32 v23, v23, v193
	v_fma_f32 v23, v185, v23, v189
	v_sub_f32_e32 v24, v24, v192
	v_mul_f32_e32 v24, v24, v193
	v_fma_f32 v24, v186, v24, v190
	v_sub_f32_e32 v25, v25, v192
	v_mul_f32_e32 v25, v25, v193
	v_fma_f32 v25, v187, v25, v191
	global_store_dwordx4 v137, v[22:25], s[94:95] offset:192
	ds_read_b128 v[184:187], v136 offset:320
	ds_read_b128 v[188:191], v136 offset:4416
	s_waitcnt lgkmcnt(2)
	v_sub_f32_e32 v18, v18, v192
	v_mul_f32_e32 v18, v18, v193
	v_fma_f32 v18, v176, v18, v180
	v_sub_f32_e32 v19, v19, v192
	v_mul_f32_e32 v19, v19, v193
	v_fma_f32 v19, v177, v19, v181
	v_sub_f32_e32 v20, v20, v192
	v_mul_f32_e32 v20, v20, v193
	v_fma_f32 v20, v178, v20, v182
	v_sub_f32_e32 v21, v21, v192
	v_mul_f32_e32 v21, v21, v193
	v_fma_f32 v21, v179, v21, v183
	global_store_dwordx4 v137, v[18:21], s[94:95] offset:256
	ds_read_b128 v[176:179], v136 offset:384
	ds_read_b128 v[180:183], v136 offset:4480
	s_waitcnt lgkmcnt(2)
	v_sub_f32_e32 v14, v14, v192
	v_mul_f32_e32 v14, v14, v193
	v_fma_f32 v14, v184, v14, v188
	v_sub_f32_e32 v15, v15, v192
	v_mul_f32_e32 v15, v15, v193
	v_fma_f32 v15, v185, v15, v189
	v_sub_f32_e32 v16, v16, v192
	v_mul_f32_e32 v16, v16, v193
	v_fma_f32 v16, v186, v16, v190
	v_sub_f32_e32 v17, v17, v192
	v_mul_f32_e32 v17, v17, v193
	v_fma_f32 v17, v187, v17, v191
	global_store_dwordx4 v137, v[14:17], s[94:95] offset:320
	ds_read_b128 v[184:187], v136 offset:448
	ds_read_b128 v[188:191], v136 offset:4544
	s_waitcnt lgkmcnt(2)
	v_sub_f32_e32 v10, v10, v192
	v_mul_f32_e32 v10, v10, v193
	v_fma_f32 v10, v176, v10, v180
	v_sub_f32_e32 v11, v11, v192
	v_mul_f32_e32 v11, v11, v193
	v_fma_f32 v11, v177, v11, v181
	v_sub_f32_e32 v12, v12, v192
	v_mul_f32_e32 v12, v12, v193
	v_fma_f32 v12, v178, v12, v182
	v_sub_f32_e32 v13, v13, v192
	v_mul_f32_e32 v13, v13, v193
	v_fma_f32 v13, v179, v13, v183
	global_store_dwordx4 v137, v[10:13], s[94:95] offset:384
	s_waitcnt lgkmcnt(0)
	v_sub_f32_e32 v6, v6, v192
	v_mul_f32_e32 v6, v6, v193
	v_fma_f32 v6, v184, v6, v188
	v_sub_f32_e32 v7, v7, v192
	v_mul_f32_e32 v7, v7, v193
	v_fma_f32 v7, v185, v7, v189
	v_sub_f32_e32 v8, v8, v192
	v_mul_f32_e32 v8, v8, v193
	v_fma_f32 v8, v186, v8, v190
	v_sub_f32_e32 v9, v9, v192
	v_mul_f32_e32 v9, v9, v193
	v_fma_f32 v9, v187, v9, v191
	global_store_dwordx4 v137, v[6:9], s[94:95] offset:448
	s_waitcnt vmcnt(16) lgkmcnt(0)
	s_barrier
; DI float bf2f(unsigned b) { return __uint_as_float(b << 16); }
; DI void unit_O(const Params& p, char* lds, int l, int tile, int glu_tiles, int tile_b) {
;     ...
;         float s2[2], ss2[2];
; #pragma unroll
;         for (int mh = 0; mh < 2; ++mh) {
;             const int mt = half * 2 + mh, rl = mh * 16 + l15;
;             float s = 0.f, ss = 0.f;
; #pragma unroll
;             for (int nt = 0; nt < 8; ++nt) {
;                 f32x4 xr;
;                 if (l == 0) {
;                     const int chunk = wid * 32 + nt * 4 + quad;
;                     xr = *(const f32x4*)(XR + rl * 4096 + ((chunk ^ l15) << 4));
;                 } else {
;                     const u32x2 hb = *(const u32x2*)(XR + ((wid * 4 + (nt >> 1)) * 32 + rl) * 64 + (nt & 1) * 32 + quad * 8);
;                     xr = (f32x4){bf2f(hb[0] & 0xffffu), bf2f(hb[0] >> 16), bf2f(hb[1] & 0xffffu), bf2f(hb[1] >> 16)};
;                 }
; #pragma unroll
;                 for (int i = 0; i < 4; ++i) { const float v = acc[mt][nt][i] + DN_ALPHA * xr[i]; acc[mt][nt][i] = v; s += v; ss += v * v; }
;             }
;             s2[mh] = s; ss2[mh] = ss;
;         }
; #pragma unroll
;         for (int mh = 0; mh < 2; ++mh) { s2[mh] += __shfl_xor(s2[mh], 16); ss2[mh] += __shfl_xor(ss2[mh], 16); }
; #pragma unroll
;         for (int mh = 0; mh < 2; ++mh) { s2[mh] += __shfl_xor(s2[mh], 32); ss2[mh] += __shfl_xor(ss2[mh], 32); }
;         if (quad == 0) {
; #pragma unroll
;             for (int mh = 0; mh < 2; ++mh) *(f32x2*)&red[((mh * 16 + l15) * 8 + wid) * 2] = (f32x2){s2[mh], ss2[mh]};
;         }
;         __syncthreads();
	ds_read_b64 v[180:181], v133 offset:32768
	ds_read_b64 v[182:183], v133 offset:32800
	ds_read_b64 v[184:185], v133 offset:33792
	ds_read_b64 v[186:187], v133 offset:33824
	ds_read_b64 v[188:189], v133 offset:34816
	ds_read_b64 v[190:191], v133 offset:34848
	ds_read_b64 v[192:193], v133 offset:35840
	ds_read_b64 v[194:195], v133 offset:35872
	s_waitcnt lgkmcnt(7)
	v_lshlrev_b32_e32 v144, 16, v180
	v_and_b32_e32 v145, 0xffff0000, v180
	v_lshlrev_b32_e32 v146, 16, v181
	v_and_b32_e32 v147, 0xffff0000, v181
	v_fmac_f32_e32 v62, s58, v144
	v_fmac_f32_e32 v63, s58, v145
	v_fmac_f32_e32 v64, s58, v146
	v_fmac_f32_e32 v65, s58, v147
	v_mov_b32_e32 v196, v62
	v_mul_f32_e32 v197, v62, v62
	v_mov_b32_e32 v130, v63
	v_mul_f32_e32 v142, v63, v63
	v_add_f32_e32 v196, v196, v64
	v_fmac_f32_e32 v197, v64, v64
	v_add_f32_e32 v130, v130, v65
	v_fmac_f32_e32 v142, v65, v65
	s_waitcnt lgkmcnt(6)
	v_lshlrev_b32_e32 v148, 16, v182
	v_and_b32_e32 v149, 0xffff0000, v182
	v_lshlrev_b32_e32 v150, 16, v183
	v_and_b32_e32 v151, 0xffff0000, v183
	v_fmac_f32_e32 v58, s58, v148
	v_fmac_f32_e32 v59, s58, v149
	v_fmac_f32_e32 v60, s58, v150
	v_fmac_f32_e32 v61, s58, v151
	v_add_f32_e32 v196, v196, v58
	v_fmac_f32_e32 v197, v58, v58
	v_add_f32_e32 v130, v130, v59
	v_fmac_f32_e32 v142, v59, v59
	v_add_f32_e32 v196, v196, v60
	v_fmac_f32_e32 v197, v60, v60
	v_add_f32_e32 v130, v130, v61
	v_fmac_f32_e32 v142, v61, v61
	s_waitcnt lgkmcnt(5)
	v_lshlrev_b32_e32 v152, 16, v184
	v_and_b32_e32 v153, 0xffff0000, v184
	v_lshlrev_b32_e32 v154, 16, v185
	v_and_b32_e32 v155, 0xffff0000, v185
	v_fmac_f32_e32 v54, s58, v152
	v_fmac_f32_e32 v55, s58, v153
	v_fmac_f32_e32 v56, s58, v154
	v_fmac_f32_e32 v57, s58, v155
	v_add_f32_e32 v196, v196, v54
	v_fmac_f32_e32 v197, v54, v54
	v_add_f32_e32 v130, v130, v55
	v_fmac_f32_e32 v142, v55, v55
	v_add_f32_e32 v196, v196, v56
	v_fmac_f32_e32 v197, v56, v56
	v_add_f32_e32 v130, v130, v57
	v_fmac_f32_e32 v142, v57, v57
	s_waitcnt lgkmcnt(4)
	v_lshlrev_b32_e32 v156, 16, v186
	v_and_b32_e32 v157, 0xffff0000, v186
	v_lshlrev_b32_e32 v158, 16, v187
	v_and_b32_e32 v159, 0xffff0000, v187
	v_fmac_f32_e32 v50, s58, v156
	v_fmac_f32_e32 v51, s58, v157
	v_fmac_f32_e32 v52, s58, v158
	v_fmac_f32_e32 v53, s58, v159
	v_add_f32_e32 v196, v196, v50
	v_fmac_f32_e32 v197, v50, v50
	v_add_f32_e32 v130, v130, v51
	v_fmac_f32_e32 v142, v51, v51
	v_add_f32_e32 v196, v196, v52
	v_fmac_f32_e32 v197, v52, v52
	v_add_f32_e32 v130, v130, v53
	v_fmac_f32_e32 v142, v53, v53
	s_waitcnt lgkmcnt(3)
	v_lshlrev_b32_e32 v160, 16, v188
	v_and_b32_e32 v161, 0xffff0000, v188
	v_lshlrev_b32_e32 v162, 16, v189
	v_and_b32_e32 v163, 0xffff0000, v189
	v_fmac_f32_e32 v46, s58, v160
	v_fmac_f32_e32 v47, s58, v161
	v_fmac_f32_e32 v48, s58, v162
	v_fmac_f32_e32 v49, s58, v163
	v_add_f32_e32 v196, v196, v46
	v_fmac_f32_e32 v197, v46, v46
	v_add_f32_e32 v130, v130, v47
	v_fmac_f32_e32 v142, v47, v47
	v_add_f32_e32 v196, v196, v48
	v_fmac_f32_e32 v197, v48, v48
	v_add_f32_e32 v130, v130, v49
	v_fmac_f32_e32 v142, v49, v49
	s_waitcnt lgkmcnt(2)
	v_lshlrev_b32_e32 v164, 16, v190
	v_and_b32_e32 v165, 0xffff0000, v190
	v_lshlrev_b32_e32 v166, 16, v191
	v_and_b32_e32 v167, 0xffff0000, v191
	v_fmac_f32_e32 v42, s58, v164
	v_fmac_f32_e32 v43, s58, v165
	v_fmac_f32_e32 v44, s58, v166
	v_fmac_f32_e32 v45, s58, v167
	v_add_f32_e32 v196, v196, v42
	v_fmac_f32_e32 v197, v42, v42
	v_add_f32_e32 v130, v130, v43
	v_fmac_f32_e32 v142, v43, v43
	v_add_f32_e32 v196, v196, v44
	v_fmac_f32_e32 v197, v44, v44
	v_add_f32_e32 v130, v130, v45
	v_fmac_f32_e32 v142, v45, v45
	s_waitcnt lgkmcnt(1)
	v_lshlrev_b32_e32 v168, 16, v192
	v_and_b32_e32 v169, 0xffff0000, v192
	v_lshlrev_b32_e32 v170, 16, v193
	v_and_b32_e32 v171, 0xffff0000, v193
	v_fmac_f32_e32 v38, s58, v168
	v_fmac_f32_e32 v39, s58, v169
	v_fmac_f32_e32 v40, s58, v170
	v_fmac_f32_e32 v41, s58, v171
	v_add_f32_e32 v196, v196, v38
	v_fmac_f32_e32 v197, v38, v38
	v_add_f32_e32 v130, v130, v39
	v_fmac_f32_e32 v142, v39, v39
	v_add_f32_e32 v196, v196, v40
	v_fmac_f32_e32 v197, v40, v40
	v_add_f32_e32 v130, v130, v41
	v_fmac_f32_e32 v142, v41, v41
	s_waitcnt lgkmcnt(0)
	v_lshlrev_b32_e32 v172, 16, v194
	v_and_b32_e32 v173, 0xffff0000, v194
	v_lshlrev_b32_e32 v174, 16, v195
	v_and_b32_e32 v175, 0xffff0000, v195
	v_fmac_f32_e32 v2, s58, v172
	v_fmac_f32_e32 v3, s58, v173
	v_fmac_f32_e32 v4, s58, v174
	v_fmac_f32_e32 v5, s58, v175
	v_add_f32_e32 v196, v196, v2
	v_fmac_f32_e32 v197, v2, v2
	v_add_f32_e32 v130, v130, v3
	v_fmac_f32_e32 v142, v3, v3
	v_add_f32_e32 v196, v196, v4
	v_fmac_f32_e32 v197, v4, v4
	v_add_f32_e32 v130, v130, v5
	v_fmac_f32_e32 v142, v5, v5
	v_add_f32_e32 v196, v196, v130
	v_add_f32_e32 v197, v197, v142
	v_mov_b32_e32 v198, v196
	v_mov_b32_e32 v199, v197
	s_nop 1
	v_permlane16_swap_b32 v198, v196
	v_permlane16_swap_b32 v199, v197
	v_add_f32_e32 v196, v196, v198
	v_add_f32_e32 v197, v197, v199
	v_mov_b32_e32 v198, v196
	v_mov_b32_e32 v199, v197
	s_nop 1
	v_permlane32_swap_b32 v198, v196
	v_permlane32_swap_b32 v199, v197
	v_add_f32_e32 v196, v196, v198
	v_add_f32_e32 v197, v197, v199
	s_mov_b64 exec, 0xffff
	ds_write_b64 v134, v[196:197]
	s_mov_b64 exec, -1
	s_waitcnt lgkmcnt(0)
	s_barrier
; DI unsigned pk2(float lo, float hi) { const f32x2 v = {lo, hi}; const bf16x2_t b = __builtin_convertvector(v, bf16x2_t); return __builtin_bit_cast(unsigned, b); }
; DI size_t xb_off(int tok, int col) { return ((size_t)(((tok >> 7) * 32 + (col >> 5)) * 128 + (tok & 127))) * 32 + (col & 31); }
; DI void unit_O(const Params& p, char* lds, int l, int tile, int glu_tiles, int tile_b) {
;     ...
; #pragma unroll
;         for (int mh = 0; mh < 2; ++mh) {
;             const int mt = half * 2 + mh, rl = mh * 16 + l15, row = mt * 16 + l15;
;             float s = 0.f, ss = 0.f;
; #pragma unroll
;             for (int w = 0; w < 4; ++w) { const f32x4 v = *(const f32x4*)&red[rl * 16 + 4 * w]; s += v[0] + v[2]; ss += v[1] + v[3]; }
;             const float mu = s * (1.f / 1024.f);
;             const float var = ss * (1.f / 1024.f) - mu * mu;
;             const float rs = rsqrtf(var + LN_EPS);
;             float* orow = xo + (r0 + row) * 1024 + wid * 128 + quad * 4;
;             bf16_t* brow = xbo + xb_off((int)r0 + row, wid * 128) + quad * 4;
;             const float* gp = GB + wid * 128 + quad * 4;
; #pragma unroll
;             for (int nt = 0; nt < 8; ++nt) {
;                 const f32x4 g = *(const f32x4*)(gp + nt * 16), bb = *(const f32x4*)(gp + 1024 + nt * 16);
;                 f32x4 o;
; #pragma unroll
;                 for (int i = 0; i < 4; ++i) o[i] = (acc[mt][nt][i] - mu) * rs * g[i] + bb[i];
;                 if (l == 0) *(u32x2*)(brow + (nt >> 1) * 4096 + (nt & 1) * 16) = (u32x2){pk2(o[0], o[1]), pk2(o[2], o[3])};
;                 else *(f32x4*)(orow + nt * 16) = o;
;             }
;         }
	ds_read_b128 v[160:163], v135 offset:0
	ds_read_b128 v[164:167], v135 offset:16
	ds_read_b128 v[168:171], v135 offset:32
	ds_read_b128 v[172:175], v135 offset:48
	s_waitcnt lgkmcnt(0)
	v_add_f32_e32 v160, v160, v162
	v_add_f32_e32 v161, v161, v163
	v_add_f32_e32 v164, v164, v166
	v_add_f32_e32 v165, v165, v167
	v_add_f32_e32 v168, v168, v170
	v_add_f32_e32 v169, v169, v171
	v_add_f32_e32 v172, v172, v174
	v_add_f32_e32 v173, v173, v175
	v_add_f32_e32 v160, v160, v164
	v_add_f32_e32 v161, v161, v165
	v_add_f32_e32 v168, v168, v172
	v_add_f32_e32 v169, v169, v173
	v_add_f32_e32 v160, v160, v168
	v_add_f32_e32 v161, v161, v169
	v_mul_f32_e32 v192, 0x3a800000, v160
	v_mul_f32_e32 v193, 0x3a800000, v161
	v_fma_f32 v193, -v192, v192, v193
	v_add_f32_e32 v193, 0x3727c5ac, v193
	v_rsq_f32_e32 v193, v193
	s_nop 0
	s_add_u32 s94, s78, 0x30000
	s_addc_u32 s95, s79, 0
	ds_read_b128 v[176:179], v136
	ds_read_b128 v[180:183], v136 offset:4096
	ds_read_b128 v[184:187], v136 offset:64
	ds_read_b128 v[188:191], v136 offset:4160
	s_waitcnt lgkmcnt(2)
	v_sub_f32_e32 v62, v62, v192
	v_mul_f32_e32 v62, v62, v193
	v_fma_f32 v62, v176, v62, v180
	v_sub_f32_e32 v63, v63, v192
	v_mul_f32_e32 v63, v63, v193
	v_fma_f32 v63, v177, v63, v181
	v_sub_f32_e32 v64, v64, v192
	v_mul_f32_e32 v64, v64, v193
	v_fma_f32 v64, v178, v64, v182
	v_sub_f32_e32 v65, v65, v192
	v_mul_f32_e32 v65, v65, v193
	v_fma_f32 v65, v179, v65, v183
	global_store_dwordx4 v137, v[62:65], s[94:95]
	ds_read_b128 v[176:179], v136 offset:128
	ds_read_b128 v[180:183], v136 offset:4224
	s_waitcnt lgkmcnt(2)
	v_sub_f32_e32 v58, v58, v192
	v_mul_f32_e32 v58, v58, v193
	v_fma_f32 v58, v184, v58, v188
	v_sub_f32_e32 v59, v59, v192
	v_mul_f32_e32 v59, v59, v193
	v_fma_f32 v59, v185, v59, v189
	v_sub_f32_e32 v60, v60, v192
	v_mul_f32_e32 v60, v60, v193
	v_fma_f32 v60, v186, v60, v190
	v_sub_f32_e32 v61, v61, v192
	v_mul_f32_e32 v61, v61, v193
	v_fma_f32 v61, v187, v61, v191
	global_store_dwordx4 v137, v[58:61], s[94:95] offset:64
	ds_read_b128 v[184:187], v136 offset:192
	ds_read_b128 v[188:191], v136 offset:4288
	s_waitcnt lgkmcnt(2)
	v_sub_f32_e32 v54, v54, v192
	v_mul_f32_e32 v54, v54, v193
	v_fma_f32 v54, v176, v54, v180
	v_sub_f32_e32 v55, v55, v192
	v_mul_f32_e32 v55, v55, v193
	v_fma_f32 v55, v177, v55, v181
	v_sub_f32_e32 v56, v56, v192
	v_mul_f32_e32 v56, v56, v193
	v_fma_f32 v56, v178, v56, v182
	v_sub_f32_e32 v57, v57, v192
	v_mul_f32_e32 v57, v57, v193
	v_fma_f32 v57, v179, v57, v183
	global_store_dwordx4 v137, v[54:57], s[94:95] offset:128
	ds_read_b128 v[176:179], v136 offset:256
	ds_read_b128 v[180:183], v136 offset:4352
	s_waitcnt lgkmcnt(2)
	v_sub_f32_e32 v50, v50, v192
	v_mul_f32_e32 v50, v50, v193
	v_fma_f32 v50, v184, v50, v188
	v_sub_f32_e32 v51, v51, v192
	v_mul_f32_e32 v51, v51, v193
	v_fma_f32 v51, v185, v51, v189
	v_sub_f32_e32 v52, v52, v192
	v_mul_f32_e32 v52, v52, v193
	v_fma_f32 v52, v186, v52, v190
	v_sub_f32_e32 v53, v53, v192
	v_mul_f32_e32 v53, v53, v193
	v_fma_f32 v53, v187, v53, v191
	global_store_dwordx4 v137, v[50:53], s[94:95] offset:192
	ds_read_b128 v[184:187], v136 offset:320
	ds_read_b128 v[188:191], v136 offset:4416
	s_waitcnt lgkmcnt(2)
	v_sub_f32_e32 v46, v46, v192
	v_mul_f32_e32 v46, v46, v193
	v_fma_f32 v46, v176, v46, v180
	v_sub_f32_e32 v47, v47, v192
	v_mul_f32_e32 v47, v47, v193
	v_fma_f32 v47, v177, v47, v181
	v_sub_f32_e32 v48, v48, v192
	v_mul_f32_e32 v48, v48, v193
	v_fma_f32 v48, v178, v48, v182
	v_sub_f32_e32 v49, v49, v192
	v_mul_f32_e32 v49, v49, v193
	v_fma_f32 v49, v179, v49, v183
	global_store_dwordx4 v137, v[46:49], s[94:95] offset:256
	ds_read_b128 v[176:179], v136 offset:384
	ds_read_b128 v[180:183], v136 offset:4480
	s_waitcnt lgkmcnt(2)
	v_sub_f32_e32 v42, v42, v192
	v_mul_f32_e32 v42, v42, v193
	v_fma_f32 v42, v184, v42, v188
	v_sub_f32_e32 v43, v43, v192
	v_mul_f32_e32 v43, v43, v193
	v_fma_f32 v43, v185, v43, v189
	v_sub_f32_e32 v44, v44, v192
	v_mul_f32_e32 v44, v44, v193
	v_fma_f32 v44, v186, v44, v190
	v_sub_f32_e32 v45, v45, v192
	v_mul_f32_e32 v45, v45, v193
	v_fma_f32 v45, v187, v45, v191
	global_store_dwordx4 v137, v[42:45], s[94:95] offset:320
	ds_read_b128 v[184:187], v136 offset:448
	ds_read_b128 v[188:191], v136 offset:4544
	s_waitcnt lgkmcnt(2)
	v_sub_f32_e32 v38, v38, v192
	v_mul_f32_e32 v38, v38, v193
	v_fma_f32 v38, v176, v38, v180
	v_sub_f32_e32 v39, v39, v192
	v_mul_f32_e32 v39, v39, v193
	v_fma_f32 v39, v177, v39, v181
	v_sub_f32_e32 v40, v40, v192
	v_mul_f32_e32 v40, v40, v193
	v_fma_f32 v40, v178, v40, v182
	v_sub_f32_e32 v41, v41, v192
	v_mul_f32_e32 v41, v41, v193
	v_fma_f32 v41, v179, v41, v183
	global_store_dwordx4 v137, v[38:41], s[94:95] offset:384
	s_waitcnt lgkmcnt(0)
	v_sub_f32_e32 v2, v2, v192
	v_mul_f32_e32 v2, v2, v193
	v_fma_f32 v2, v184, v2, v188
	v_sub_f32_e32 v3, v3, v192
	v_mul_f32_e32 v3, v3, v193
	v_fma_f32 v3, v185, v3, v189
	v_sub_f32_e32 v4, v4, v192
	v_mul_f32_e32 v4, v4, v193
	v_fma_f32 v4, v186, v4, v190
	v_sub_f32_e32 v5, v5, v192
	v_mul_f32_e32 v5, v5, v193
	v_fma_f32 v5, v187, v5, v191
	global_store_dwordx4 v137, v[2:5], s[94:95] offset:448
